# v88 + ksalu: K-loop bodies drop the adjacent s_setprio 0/1 pair between MFMA groups and the duplicate lgkmcnt(0) wait (12 SALU per body)
# speedup vs baseline: 1.0084x; 1.0013x over previous
.LBB0_367:
	s_ashr_i32 s55, s54, 31
	s_lshl_b64 s[2:3], s[54:55], 19
	s_add_u32 s58, s4, s2
	s_addc_u32 s59, s5, s3
	s_and_b64 s[2:3], s[56:57], exec
	s_cselect_b32 s2, s59, s7
	s_cselect_b32 s3, s58, s6
	s_ashr_i32 s53, s52, 31
	s_lshl_b64 s[10:11], s[52:53], 19
	s_add_u32 s60, s15, s10
	s_addc_u32 s61, s78, s11
	s_and_b64 s[10:11], s[56:57], exec
	s_cselect_b32 s12, s61, s9
	s_cselect_b32 s13, s60, s8
	s_add_u32 s6, s6, 0x40080
	s_addc_u32 s7, s7, 0
	s_add_u32 s24, s8, 0x100
	s_addc_u32 s25, s9, 0
	s_mov_b32 s26, -2
	v_add_u32_e32 v254, 0x18000, v173
	v_add_u32_e32 v255, 0x1c000, v173
	ds_read_b128 v[114:117], v197
	ds_read_b128 v[134:137], v197 offset:1024
	ds_read_b128 v[138:141], v197 offset:2048
	ds_read_b128 v[142:145], v197 offset:3072
	ds_read_b128 v[146:149], v198
	ds_read_b128 v[150:153], v198 offset:1024
	ds_read_b128 v[154:157], v198 offset:2048
	ds_read_b128 v[158:161], v198 offset:3072
	s_add_u32 s0, s6, 0xfffc0080
	s_addc_u32 s8, s7, -1
	s_cmp_eq_u32 s26, 12
	s_cselect_b32 s11, s2, s8
	s_cselect_b32 s10, s3, s0
	s_cselect_b32 s9, s12, s25
	s_cselect_b32 s8, s13, s24
	s_add_i32 m0, s31, 0xc000
	ds_read_b128 v[184:187], v199
	ds_read_b128 v[188:191], v199 offset:1024
	ds_read_b128 v[206:209], v199 offset:2048
	ds_read_b128 v[210:213], v199 offset:3072
	ds_read_b128 v[214:217], v199 offset:4096
	ds_read_b128 v[218:221], v199 offset:5120
	ds_read_b128 v[222:225], v199 offset:6144
	ds_read_b128 v[226:229], v199 offset:7168
	global_load_lds_dwordx4 v180, s[6:7]
	s_add_i32 m0, s31, 0xe000
	s_nop 0
	global_load_lds_dwordx4 v182, s[6:7]
	s_waitcnt vmcnt(8)
	s_waitcnt lgkmcnt(0)
	s_barrier
	s_setprio 1
	v_mfma_f32_16x16x32_bf16 v[130:133], v[114:117], v[184:187], 0
	v_mfma_f32_16x16x32_bf16 v[126:129], v[138:141], v[184:187], 0
	v_mfma_f32_16x16x32_bf16 v[110:113], v[114:117], v[206:209], 0
	v_mfma_f32_16x16x32_bf16 v[106:109], v[138:141], v[206:209], 0
	v_mfma_f32_16x16x32_bf16 v[94:97], v[114:117], v[214:217], 0
	v_mfma_f32_16x16x32_bf16 v[90:93], v[138:141], v[214:217], 0
	v_mfma_f32_16x16x32_bf16 v[78:81], v[114:117], v[222:225], 0
	v_mfma_f32_16x16x32_bf16 v[74:77], v[138:141], v[222:225], 0
	v_mfma_f32_16x16x32_bf16 v[130:133], v[134:137], v[188:191], v[130:133]
	v_mfma_f32_16x16x32_bf16 v[126:129], v[142:145], v[188:191], v[126:129]
	v_mfma_f32_16x16x32_bf16 v[110:113], v[134:137], v[210:213], v[110:113]
	v_mfma_f32_16x16x32_bf16 v[106:109], v[142:145], v[210:213], v[106:109]
	v_mfma_f32_16x16x32_bf16 v[94:97], v[134:137], v[218:221], v[94:97]
	v_mfma_f32_16x16x32_bf16 v[90:93], v[142:145], v[218:221], v[90:93]
	v_mfma_f32_16x16x32_bf16 v[78:81], v[134:137], v[226:229], v[78:81]
	v_mfma_f32_16x16x32_bf16 v[74:77], v[142:145], v[226:229], v[74:77]
	v_mfma_f32_16x16x32_bf16 v[122:125], v[146:149], v[184:187], 0
	v_mfma_f32_16x16x32_bf16 v[118:121], v[154:157], v[184:187], 0
	v_mfma_f32_16x16x32_bf16 v[102:105], v[146:149], v[206:209], 0
	v_mfma_f32_16x16x32_bf16 v[98:101], v[154:157], v[206:209], 0
	v_mfma_f32_16x16x32_bf16 v[86:89], v[146:149], v[214:217], 0
	v_mfma_f32_16x16x32_bf16 v[82:85], v[154:157], v[214:217], 0
	v_mfma_f32_16x16x32_bf16 v[70:73], v[146:149], v[222:225], 0
	v_mfma_f32_16x16x32_bf16 v[66:69], v[154:157], v[222:225], 0
	v_mfma_f32_16x16x32_bf16 v[122:125], v[150:153], v[188:191], v[122:125]
	v_mfma_f32_16x16x32_bf16 v[118:121], v[158:161], v[188:191], v[118:121]
	v_mfma_f32_16x16x32_bf16 v[102:105], v[150:153], v[210:213], v[102:105]
	v_mfma_f32_16x16x32_bf16 v[98:101], v[158:161], v[210:213], v[98:101]
	v_mfma_f32_16x16x32_bf16 v[86:89], v[150:153], v[218:221], v[86:89]
	v_mfma_f32_16x16x32_bf16 v[82:85], v[158:161], v[218:221], v[82:85]
	v_mfma_f32_16x16x32_bf16 v[70:73], v[150:153], v[226:229], v[70:73]
	v_mfma_f32_16x16x32_bf16 v[66:69], v[158:161], v[226:229], v[66:69]
	s_setprio 0
	s_barrier
	s_add_i32 s0, s89, s79
	s_mov_b32 m0, s0
	ds_read_b128 v[184:187], v199 offset:16384
	ds_read_b128 v[188:191], v199 offset:17408
	ds_read_b128 v[206:209], v199 offset:18432
	ds_read_b128 v[210:213], v199 offset:19456
	ds_read_b128 v[214:217], v199 offset:20480
	ds_read_b128 v[218:221], v199 offset:21504
	ds_read_b128 v[222:225], v199 offset:22528
	ds_read_b128 v[226:229], v199 offset:23552
	global_load_lds_dwordx4 v164, s[8:9]
	s_add_i32 m0, s0, 0x2000
	s_add_u32 s62, s8, 0x40000
	s_addc_u32 s63, s9, 0
	s_add_i32 s0, s90, s79
	global_load_lds_dwordx4 v168, s[8:9]
	s_mov_b32 m0, s0
	s_nop 0
	global_load_lds_dwordx4 v164, s[62:63]
	s_add_i32 m0, s0, 0x2000
	s_nop 0
	global_load_lds_dwordx4 v168, s[62:63]
	s_mov_b32 m0, s31
	s_nop 0
	global_load_lds_dwordx4 v162, s[10:11]
	s_mov_b32 m0, s80
	s_nop 0
	global_load_lds_dwordx4 v166, s[10:11]
	s_waitcnt vmcnt(8)
	s_waitcnt lgkmcnt(0)
	s_barrier
	s_setprio 1
	v_mfma_f32_16x16x32_bf16 v[62:65], v[114:117], v[184:187], 0
	v_mfma_f32_16x16x32_bf16 v[58:61], v[138:141], v[184:187], 0
	v_mfma_f32_16x16x32_bf16 v[46:49], v[114:117], v[206:209], 0
	v_mfma_f32_16x16x32_bf16 v[42:45], v[138:141], v[206:209], 0
	v_mfma_f32_16x16x32_bf16 v[30:33], v[114:117], v[214:217], 0
	v_mfma_f32_16x16x32_bf16 v[26:29], v[138:141], v[214:217], 0
	v_mfma_f32_16x16x32_bf16 v[14:17], v[114:117], v[222:225], 0
	v_mfma_f32_16x16x32_bf16 v[10:13], v[138:141], v[222:225], 0
	v_mfma_f32_16x16x32_bf16 v[62:65], v[134:137], v[188:191], v[62:65]
	v_mfma_f32_16x16x32_bf16 v[58:61], v[142:145], v[188:191], v[58:61]
	v_mfma_f32_16x16x32_bf16 v[46:49], v[134:137], v[210:213], v[46:49]
	v_mfma_f32_16x16x32_bf16 v[42:45], v[142:145], v[210:213], v[42:45]
	v_mfma_f32_16x16x32_bf16 v[30:33], v[134:137], v[218:221], v[30:33]
	v_mfma_f32_16x16x32_bf16 v[26:29], v[142:145], v[218:221], v[26:29]
	v_mfma_f32_16x16x32_bf16 v[14:17], v[134:137], v[226:229], v[14:17]
	v_mfma_f32_16x16x32_bf16 v[10:13], v[142:145], v[226:229], v[10:13]
	v_mfma_f32_16x16x32_bf16 v[54:57], v[146:149], v[184:187], 0
	v_mfma_f32_16x16x32_bf16 v[50:53], v[154:157], v[184:187], 0
	v_mfma_f32_16x16x32_bf16 v[38:41], v[146:149], v[206:209], 0
	v_mfma_f32_16x16x32_bf16 v[34:37], v[154:157], v[206:209], 0
	v_mfma_f32_16x16x32_bf16 v[22:25], v[146:149], v[214:217], 0
	v_mfma_f32_16x16x32_bf16 v[18:21], v[154:157], v[214:217], 0
	v_mfma_f32_16x16x32_bf16 v[6:9], v[146:149], v[222:225], 0
	v_mfma_f32_16x16x32_bf16 v[2:5], v[154:157], v[222:225], 0
	v_mfma_f32_16x16x32_bf16 v[54:57], v[150:153], v[188:191], v[54:57]
	v_mfma_f32_16x16x32_bf16 v[50:53], v[158:161], v[188:191], v[50:53]
	v_mfma_f32_16x16x32_bf16 v[38:41], v[150:153], v[210:213], v[38:41]
	v_mfma_f32_16x16x32_bf16 v[34:37], v[158:161], v[210:213], v[34:37]
	v_mfma_f32_16x16x32_bf16 v[22:25], v[150:153], v[218:221], v[22:25]
	v_mfma_f32_16x16x32_bf16 v[18:21], v[158:161], v[218:221], v[18:21]
	v_mfma_f32_16x16x32_bf16 v[6:9], v[150:153], v[226:229], v[6:9]
	v_mfma_f32_16x16x32_bf16 v[2:5], v[158:161], v[226:229], v[2:5]
	s_setprio 0
	s_barrier
	s_add_i32 s0, 0, 0x18000
	s_add_i32 s27, 0, 0x1c000
	ds_read_b128 v[114:117], v254
	ds_read_b128 v[134:137], v254 offset:1024
	ds_read_b128 v[138:141], v254 offset:2048
	ds_read_b128 v[142:145], v254 offset:3072
	ds_read_b128 v[146:149], v255
	ds_read_b128 v[150:153], v255 offset:1024
	ds_read_b128 v[154:157], v255 offset:2048
	ds_read_b128 v[158:161], v255 offset:3072
	s_add_u32 s10, s10, 0x40000
	s_addc_u32 s11, s11, 0
	s_mov_b32 m0, s81
	ds_read_b128 v[184:187], v199 offset:32768
	ds_read_b128 v[188:191], v199 offset:33792
	ds_read_b128 v[206:209], v199 offset:34816
	ds_read_b128 v[210:213], v199 offset:35840
	ds_read_b128 v[214:217], v199 offset:36864
	ds_read_b128 v[218:221], v199 offset:37888
	ds_read_b128 v[222:225], v199 offset:38912
	ds_read_b128 v[226:229], v199 offset:39936
	global_load_lds_dwordx4 v162, s[10:11]
	s_mov_b32 m0, s82
	s_nop 0
	global_load_lds_dwordx4 v166, s[10:11]
	s_waitcnt vmcnt(8)
	s_waitcnt lgkmcnt(0)
	s_barrier
	s_setprio 1
	v_mfma_f32_16x16x32_bf16 v[130:133], v[114:117], v[184:187], v[130:133]
	v_mfma_f32_16x16x32_bf16 v[126:129], v[138:141], v[184:187], v[126:129]
	v_mfma_f32_16x16x32_bf16 v[110:113], v[114:117], v[206:209], v[110:113]
	v_mfma_f32_16x16x32_bf16 v[106:109], v[138:141], v[206:209], v[106:109]
	v_mfma_f32_16x16x32_bf16 v[94:97], v[114:117], v[214:217], v[94:97]
	v_mfma_f32_16x16x32_bf16 v[90:93], v[138:141], v[214:217], v[90:93]
	v_mfma_f32_16x16x32_bf16 v[78:81], v[114:117], v[222:225], v[78:81]
	v_mfma_f32_16x16x32_bf16 v[74:77], v[138:141], v[222:225], v[74:77]
	v_mfma_f32_16x16x32_bf16 v[130:133], v[134:137], v[188:191], v[130:133]
	v_mfma_f32_16x16x32_bf16 v[126:129], v[142:145], v[188:191], v[126:129]
	v_mfma_f32_16x16x32_bf16 v[110:113], v[134:137], v[210:213], v[110:113]
	v_mfma_f32_16x16x32_bf16 v[106:109], v[142:145], v[210:213], v[106:109]
	v_mfma_f32_16x16x32_bf16 v[94:97], v[134:137], v[218:221], v[94:97]
	v_mfma_f32_16x16x32_bf16 v[90:93], v[142:145], v[218:221], v[90:93]
	v_mfma_f32_16x16x32_bf16 v[78:81], v[134:137], v[226:229], v[78:81]
	v_mfma_f32_16x16x32_bf16 v[74:77], v[142:145], v[226:229], v[74:77]
	v_mfma_f32_16x16x32_bf16 v[122:125], v[146:149], v[184:187], v[122:125]
	v_mfma_f32_16x16x32_bf16 v[118:121], v[154:157], v[184:187], v[118:121]
	v_mfma_f32_16x16x32_bf16 v[102:105], v[146:149], v[206:209], v[102:105]
	v_mfma_f32_16x16x32_bf16 v[98:101], v[154:157], v[206:209], v[98:101]
	v_mfma_f32_16x16x32_bf16 v[86:89], v[146:149], v[214:217], v[86:89]
	v_mfma_f32_16x16x32_bf16 v[82:85], v[154:157], v[214:217], v[82:85]
	v_mfma_f32_16x16x32_bf16 v[70:73], v[146:149], v[222:225], v[70:73]
	v_mfma_f32_16x16x32_bf16 v[66:69], v[154:157], v[222:225], v[66:69]
	v_mfma_f32_16x16x32_bf16 v[122:125], v[150:153], v[188:191], v[122:125]
	v_mfma_f32_16x16x32_bf16 v[118:121], v[158:161], v[188:191], v[118:121]
	v_mfma_f32_16x16x32_bf16 v[102:105], v[150:153], v[210:213], v[102:105]
	v_mfma_f32_16x16x32_bf16 v[98:101], v[158:161], v[210:213], v[98:101]
	v_mfma_f32_16x16x32_bf16 v[86:89], v[150:153], v[218:221], v[86:89]
	v_mfma_f32_16x16x32_bf16 v[82:85], v[158:161], v[218:221], v[82:85]
	v_mfma_f32_16x16x32_bf16 v[70:73], v[150:153], v[226:229], v[70:73]
	v_mfma_f32_16x16x32_bf16 v[66:69], v[158:161], v[226:229], v[66:69]
	s_setprio 0
	s_barrier
	s_add_i32 s0, s0, s79
	s_mov_b32 m0, s0
	ds_read_b128 v[184:187], v199 offset:49152
	ds_read_b128 v[188:191], v199 offset:50176
	ds_read_b128 v[206:209], v199 offset:51200
	ds_read_b128 v[210:213], v199 offset:52224
	ds_read_b128 v[214:217], v199 offset:53248
	ds_read_b128 v[218:221], v199 offset:54272
	ds_read_b128 v[222:225], v199 offset:55296
	ds_read_b128 v[226:229], v199 offset:56320
	s_add_u32 s98, s8, 0x80
	s_addc_u32 s99, s9, 0
	global_load_lds_dwordx4 v164, s[98:99]
	s_add_i32 m0, s0, 0x2000
	s_add_u32 s8, s8, 0x40080
	s_addc_u32 s9, s9, 0
	s_add_i32 s0, s27, s79
	global_load_lds_dwordx4 v168, s[98:99]
	s_mov_b32 m0, s0
	s_nop 0
	global_load_lds_dwordx4 v164, s[8:9]
	s_add_i32 m0, s0, 0x2000
	s_nop 0
	global_load_lds_dwordx4 v168, s[8:9]
	s_add_u32 s98, s10, 0xfffc0080
	s_addc_u32 s99, s11, -1
	s_mov_b32 m0, s84
	s_nop 0
	global_load_lds_dwordx4 v162, s[98:99]
	s_mov_b32 m0, s85
	s_nop 0
	global_load_lds_dwordx4 v166, s[98:99]
	s_waitcnt vmcnt(8)
	s_waitcnt lgkmcnt(0)
	s_barrier
	s_setprio 1
	v_mfma_f32_16x16x32_bf16 v[62:65], v[114:117], v[184:187], v[62:65]
	v_mfma_f32_16x16x32_bf16 v[58:61], v[138:141], v[184:187], v[58:61]
	v_mfma_f32_16x16x32_bf16 v[46:49], v[114:117], v[206:209], v[46:49]
	v_mfma_f32_16x16x32_bf16 v[42:45], v[138:141], v[206:209], v[42:45]
	v_mfma_f32_16x16x32_bf16 v[30:33], v[114:117], v[214:217], v[30:33]
	v_mfma_f32_16x16x32_bf16 v[26:29], v[138:141], v[214:217], v[26:29]
	v_mfma_f32_16x16x32_bf16 v[14:17], v[114:117], v[222:225], v[14:17]
	v_mfma_f32_16x16x32_bf16 v[10:13], v[138:141], v[222:225], v[10:13]
	v_mfma_f32_16x16x32_bf16 v[62:65], v[134:137], v[188:191], v[62:65]
	v_mfma_f32_16x16x32_bf16 v[58:61], v[142:145], v[188:191], v[58:61]
	v_mfma_f32_16x16x32_bf16 v[46:49], v[134:137], v[210:213], v[46:49]
	v_mfma_f32_16x16x32_bf16 v[42:45], v[142:145], v[210:213], v[42:45]
	v_mfma_f32_16x16x32_bf16 v[30:33], v[134:137], v[218:221], v[30:33]
	v_mfma_f32_16x16x32_bf16 v[26:29], v[142:145], v[218:221], v[26:29]
	v_mfma_f32_16x16x32_bf16 v[14:17], v[134:137], v[226:229], v[14:17]
	v_mfma_f32_16x16x32_bf16 v[10:13], v[142:145], v[226:229], v[10:13]
	v_mfma_f32_16x16x32_bf16 v[54:57], v[146:149], v[184:187], v[54:57]
	v_mfma_f32_16x16x32_bf16 v[50:53], v[154:157], v[184:187], v[50:53]
	v_mfma_f32_16x16x32_bf16 v[38:41], v[146:149], v[206:209], v[38:41]
	v_mfma_f32_16x16x32_bf16 v[34:37], v[154:157], v[206:209], v[34:37]
	v_mfma_f32_16x16x32_bf16 v[22:25], v[146:149], v[214:217], v[22:25]
	v_mfma_f32_16x16x32_bf16 v[18:21], v[154:157], v[214:217], v[18:21]
	v_mfma_f32_16x16x32_bf16 v[6:9], v[146:149], v[222:225], v[6:9]
	v_mfma_f32_16x16x32_bf16 v[2:5], v[154:157], v[222:225], v[2:5]
	v_mfma_f32_16x16x32_bf16 v[54:57], v[150:153], v[188:191], v[54:57]
	v_mfma_f32_16x16x32_bf16 v[50:53], v[158:161], v[188:191], v[50:53]
	v_mfma_f32_16x16x32_bf16 v[38:41], v[150:153], v[210:213], v[38:41]
	v_mfma_f32_16x16x32_bf16 v[34:37], v[158:161], v[210:213], v[34:37]
	v_mfma_f32_16x16x32_bf16 v[22:25], v[150:153], v[218:221], v[22:25]
	v_mfma_f32_16x16x32_bf16 v[18:21], v[158:161], v[218:221], v[18:21]
	v_mfma_f32_16x16x32_bf16 v[6:9], v[150:153], v[226:229], v[6:9]
	v_mfma_f32_16x16x32_bf16 v[2:5], v[158:161], v[226:229], v[2:5]
	s_setprio 0
	s_barrier
	s_add_i32 s26, s26, 2
	s_add_u32 s6, s6, 0x100
	s_addc_u32 s7, s7, 0
	s_add_u32 s24, s24, 0x100
	s_addc_u32 s25, s25, 0
	s_cmp_gt_u32 s26, 13
	s_cbranch_scc1 .Lpeel_x1
.LBB0_368:
	ds_read_b128 v[114:117], v197
	ds_read_b128 v[134:137], v197 offset:1024
	ds_read_b128 v[138:141], v197 offset:2048
	ds_read_b128 v[142:145], v197 offset:3072
	ds_read_b128 v[146:149], v198
	ds_read_b128 v[150:153], v198 offset:1024
	ds_read_b128 v[154:157], v198 offset:2048
	ds_read_b128 v[158:161], v198 offset:3072
	s_add_u32 s0, s6, 0xfffc0080
	s_addc_u32 s8, s7, -1
	s_cmp_eq_u32 s26, 12
	s_cselect_b32 s11, s2, s8
	s_cselect_b32 s10, s3, s0
	s_cselect_b32 s9, s12, s25
	s_cselect_b32 s8, s13, s24
	s_add_i32 m0, s31, 0xc000
	ds_read_b128 v[184:187], v199
	ds_read_b128 v[188:191], v199 offset:1024
	ds_read_b128 v[206:209], v199 offset:2048
	ds_read_b128 v[210:213], v199 offset:3072
	ds_read_b128 v[214:217], v199 offset:4096
	ds_read_b128 v[218:221], v199 offset:5120
	ds_read_b128 v[222:225], v199 offset:6144
	ds_read_b128 v[226:229], v199 offset:7168
	global_load_lds_dwordx4 v180, s[6:7]
	s_add_i32 m0, s31, 0xe000
	s_nop 0
	global_load_lds_dwordx4 v182, s[6:7]
	s_waitcnt vmcnt(8)
	s_waitcnt lgkmcnt(0)
	s_barrier
	s_setprio 1
	v_mfma_f32_16x16x32_bf16 v[130:133], v[114:117], v[184:187], v[130:133]
	v_mfma_f32_16x16x32_bf16 v[126:129], v[138:141], v[184:187], v[126:129]
	v_mfma_f32_16x16x32_bf16 v[110:113], v[114:117], v[206:209], v[110:113]
	v_mfma_f32_16x16x32_bf16 v[106:109], v[138:141], v[206:209], v[106:109]
	v_mfma_f32_16x16x32_bf16 v[94:97], v[114:117], v[214:217], v[94:97]
	v_mfma_f32_16x16x32_bf16 v[90:93], v[138:141], v[214:217], v[90:93]
	v_mfma_f32_16x16x32_bf16 v[78:81], v[114:117], v[222:225], v[78:81]
	v_mfma_f32_16x16x32_bf16 v[74:77], v[138:141], v[222:225], v[74:77]
	v_mfma_f32_16x16x32_bf16 v[130:133], v[134:137], v[188:191], v[130:133]
	v_mfma_f32_16x16x32_bf16 v[126:129], v[142:145], v[188:191], v[126:129]
	v_mfma_f32_16x16x32_bf16 v[110:113], v[134:137], v[210:213], v[110:113]
	v_mfma_f32_16x16x32_bf16 v[106:109], v[142:145], v[210:213], v[106:109]
	v_mfma_f32_16x16x32_bf16 v[94:97], v[134:137], v[218:221], v[94:97]
	v_mfma_f32_16x16x32_bf16 v[90:93], v[142:145], v[218:221], v[90:93]
	v_mfma_f32_16x16x32_bf16 v[78:81], v[134:137], v[226:229], v[78:81]
	v_mfma_f32_16x16x32_bf16 v[74:77], v[142:145], v[226:229], v[74:77]
	v_mfma_f32_16x16x32_bf16 v[122:125], v[146:149], v[184:187], v[122:125]
	v_mfma_f32_16x16x32_bf16 v[118:121], v[154:157], v[184:187], v[118:121]
	v_mfma_f32_16x16x32_bf16 v[102:105], v[146:149], v[206:209], v[102:105]
	v_mfma_f32_16x16x32_bf16 v[98:101], v[154:157], v[206:209], v[98:101]
	v_mfma_f32_16x16x32_bf16 v[86:89], v[146:149], v[214:217], v[86:89]
	v_mfma_f32_16x16x32_bf16 v[82:85], v[154:157], v[214:217], v[82:85]
	v_mfma_f32_16x16x32_bf16 v[70:73], v[146:149], v[222:225], v[70:73]
	v_mfma_f32_16x16x32_bf16 v[66:69], v[154:157], v[222:225], v[66:69]
	v_mfma_f32_16x16x32_bf16 v[122:125], v[150:153], v[188:191], v[122:125]
	v_mfma_f32_16x16x32_bf16 v[118:121], v[158:161], v[188:191], v[118:121]
	v_mfma_f32_16x16x32_bf16 v[102:105], v[150:153], v[210:213], v[102:105]
	v_mfma_f32_16x16x32_bf16 v[98:101], v[158:161], v[210:213], v[98:101]
	v_mfma_f32_16x16x32_bf16 v[86:89], v[150:153], v[218:221], v[86:89]
	v_mfma_f32_16x16x32_bf16 v[82:85], v[158:161], v[218:221], v[82:85]
	v_mfma_f32_16x16x32_bf16 v[70:73], v[150:153], v[226:229], v[70:73]
	v_mfma_f32_16x16x32_bf16 v[66:69], v[158:161], v[226:229], v[66:69]
	s_setprio 0
	s_barrier
	s_add_i32 s0, s89, s79
	s_mov_b32 m0, s0
	ds_read_b128 v[184:187], v199 offset:16384
	ds_read_b128 v[188:191], v199 offset:17408
	ds_read_b128 v[206:209], v199 offset:18432
	ds_read_b128 v[210:213], v199 offset:19456
	ds_read_b128 v[214:217], v199 offset:20480
	ds_read_b128 v[218:221], v199 offset:21504
	ds_read_b128 v[222:225], v199 offset:22528
	ds_read_b128 v[226:229], v199 offset:23552
	global_load_lds_dwordx4 v164, s[8:9]
	s_add_i32 m0, s0, 0x2000
	s_add_u32 s62, s8, 0x40000
	s_addc_u32 s63, s9, 0
	s_add_i32 s0, s90, s79
	global_load_lds_dwordx4 v168, s[8:9]
	s_mov_b32 m0, s0
	s_nop 0
	global_load_lds_dwordx4 v164, s[62:63]
	s_add_i32 m0, s0, 0x2000
	s_nop 0
	global_load_lds_dwordx4 v168, s[62:63]
	s_mov_b32 m0, s31
	s_nop 0
	global_load_lds_dwordx4 v162, s[10:11]
	s_mov_b32 m0, s80
	s_nop 0
	global_load_lds_dwordx4 v166, s[10:11]
	s_waitcnt vmcnt(8)
	s_waitcnt lgkmcnt(0)
	s_barrier
	s_setprio 1
	v_mfma_f32_16x16x32_bf16 v[62:65], v[114:117], v[184:187], v[62:65]
	v_mfma_f32_16x16x32_bf16 v[58:61], v[138:141], v[184:187], v[58:61]
	v_mfma_f32_16x16x32_bf16 v[46:49], v[114:117], v[206:209], v[46:49]
	v_mfma_f32_16x16x32_bf16 v[42:45], v[138:141], v[206:209], v[42:45]
	v_mfma_f32_16x16x32_bf16 v[30:33], v[114:117], v[214:217], v[30:33]
	v_mfma_f32_16x16x32_bf16 v[26:29], v[138:141], v[214:217], v[26:29]
	v_mfma_f32_16x16x32_bf16 v[14:17], v[114:117], v[222:225], v[14:17]
	v_mfma_f32_16x16x32_bf16 v[10:13], v[138:141], v[222:225], v[10:13]
	v_mfma_f32_16x16x32_bf16 v[62:65], v[134:137], v[188:191], v[62:65]
	v_mfma_f32_16x16x32_bf16 v[58:61], v[142:145], v[188:191], v[58:61]
	v_mfma_f32_16x16x32_bf16 v[46:49], v[134:137], v[210:213], v[46:49]
	v_mfma_f32_16x16x32_bf16 v[42:45], v[142:145], v[210:213], v[42:45]
	v_mfma_f32_16x16x32_bf16 v[30:33], v[134:137], v[218:221], v[30:33]
	v_mfma_f32_16x16x32_bf16 v[26:29], v[142:145], v[218:221], v[26:29]
	v_mfma_f32_16x16x32_bf16 v[14:17], v[134:137], v[226:229], v[14:17]
	v_mfma_f32_16x16x32_bf16 v[10:13], v[142:145], v[226:229], v[10:13]
	v_mfma_f32_16x16x32_bf16 v[54:57], v[146:149], v[184:187], v[54:57]
	v_mfma_f32_16x16x32_bf16 v[50:53], v[154:157], v[184:187], v[50:53]
	v_mfma_f32_16x16x32_bf16 v[38:41], v[146:149], v[206:209], v[38:41]
	v_mfma_f32_16x16x32_bf16 v[34:37], v[154:157], v[206:209], v[34:37]
	v_mfma_f32_16x16x32_bf16 v[22:25], v[146:149], v[214:217], v[22:25]
	v_mfma_f32_16x16x32_bf16 v[18:21], v[154:157], v[214:217], v[18:21]
	v_mfma_f32_16x16x32_bf16 v[6:9], v[146:149], v[222:225], v[6:9]
	v_mfma_f32_16x16x32_bf16 v[2:5], v[154:157], v[222:225], v[2:5]
	v_mfma_f32_16x16x32_bf16 v[54:57], v[150:153], v[188:191], v[54:57]
	v_mfma_f32_16x16x32_bf16 v[50:53], v[158:161], v[188:191], v[50:53]
	v_mfma_f32_16x16x32_bf16 v[38:41], v[150:153], v[210:213], v[38:41]
	v_mfma_f32_16x16x32_bf16 v[34:37], v[158:161], v[210:213], v[34:37]
	v_mfma_f32_16x16x32_bf16 v[22:25], v[150:153], v[218:221], v[22:25]
	v_mfma_f32_16x16x32_bf16 v[18:21], v[158:161], v[218:221], v[18:21]
	v_mfma_f32_16x16x32_bf16 v[6:9], v[150:153], v[226:229], v[6:9]
	v_mfma_f32_16x16x32_bf16 v[2:5], v[158:161], v[226:229], v[2:5]
	s_setprio 0
	s_barrier
	s_add_i32 s0, 0, 0x18000
	s_add_i32 s27, 0, 0x1c000
	ds_read_b128 v[114:117], v254
	ds_read_b128 v[134:137], v254 offset:1024
	ds_read_b128 v[138:141], v254 offset:2048
	ds_read_b128 v[142:145], v254 offset:3072
	ds_read_b128 v[146:149], v255
	ds_read_b128 v[150:153], v255 offset:1024
	ds_read_b128 v[154:157], v255 offset:2048
	ds_read_b128 v[158:161], v255 offset:3072
	s_add_u32 s10, s10, 0x40000
	s_addc_u32 s11, s11, 0
	s_mov_b32 m0, s81
	ds_read_b128 v[184:187], v199 offset:32768
	ds_read_b128 v[188:191], v199 offset:33792
	ds_read_b128 v[206:209], v199 offset:34816
	ds_read_b128 v[210:213], v199 offset:35840
	ds_read_b128 v[214:217], v199 offset:36864
	ds_read_b128 v[218:221], v199 offset:37888
	ds_read_b128 v[222:225], v199 offset:38912
	ds_read_b128 v[226:229], v199 offset:39936
	global_load_lds_dwordx4 v162, s[10:11]
	s_mov_b32 m0, s82
	s_nop 0
	global_load_lds_dwordx4 v166, s[10:11]
	s_waitcnt vmcnt(8)
	s_waitcnt lgkmcnt(0)
	s_barrier
	s_setprio 1
	v_mfma_f32_16x16x32_bf16 v[130:133], v[114:117], v[184:187], v[130:133]
	v_mfma_f32_16x16x32_bf16 v[126:129], v[138:141], v[184:187], v[126:129]
	v_mfma_f32_16x16x32_bf16 v[110:113], v[114:117], v[206:209], v[110:113]
	v_mfma_f32_16x16x32_bf16 v[106:109], v[138:141], v[206:209], v[106:109]
	v_mfma_f32_16x16x32_bf16 v[94:97], v[114:117], v[214:217], v[94:97]
	v_mfma_f32_16x16x32_bf16 v[90:93], v[138:141], v[214:217], v[90:93]
	v_mfma_f32_16x16x32_bf16 v[78:81], v[114:117], v[222:225], v[78:81]
	v_mfma_f32_16x16x32_bf16 v[74:77], v[138:141], v[222:225], v[74:77]
	v_mfma_f32_16x16x32_bf16 v[130:133], v[134:137], v[188:191], v[130:133]
	v_mfma_f32_16x16x32_bf16 v[126:129], v[142:145], v[188:191], v[126:129]
	v_mfma_f32_16x16x32_bf16 v[110:113], v[134:137], v[210:213], v[110:113]
	v_mfma_f32_16x16x32_bf16 v[106:109], v[142:145], v[210:213], v[106:109]
	v_mfma_f32_16x16x32_bf16 v[94:97], v[134:137], v[218:221], v[94:97]
	v_mfma_f32_16x16x32_bf16 v[90:93], v[142:145], v[218:221], v[90:93]
	v_mfma_f32_16x16x32_bf16 v[78:81], v[134:137], v[226:229], v[78:81]
	v_mfma_f32_16x16x32_bf16 v[74:77], v[142:145], v[226:229], v[74:77]
	v_mfma_f32_16x16x32_bf16 v[122:125], v[146:149], v[184:187], v[122:125]
	v_mfma_f32_16x16x32_bf16 v[118:121], v[154:157], v[184:187], v[118:121]
	v_mfma_f32_16x16x32_bf16 v[102:105], v[146:149], v[206:209], v[102:105]
	v_mfma_f32_16x16x32_bf16 v[98:101], v[154:157], v[206:209], v[98:101]
	v_mfma_f32_16x16x32_bf16 v[86:89], v[146:149], v[214:217], v[86:89]
	v_mfma_f32_16x16x32_bf16 v[82:85], v[154:157], v[214:217], v[82:85]
	v_mfma_f32_16x16x32_bf16 v[70:73], v[146:149], v[222:225], v[70:73]
	v_mfma_f32_16x16x32_bf16 v[66:69], v[154:157], v[222:225], v[66:69]
	v_mfma_f32_16x16x32_bf16 v[122:125], v[150:153], v[188:191], v[122:125]
	v_mfma_f32_16x16x32_bf16 v[118:121], v[158:161], v[188:191], v[118:121]
	v_mfma_f32_16x16x32_bf16 v[102:105], v[150:153], v[210:213], v[102:105]
	v_mfma_f32_16x16x32_bf16 v[98:101], v[158:161], v[210:213], v[98:101]
	v_mfma_f32_16x16x32_bf16 v[86:89], v[150:153], v[218:221], v[86:89]
	v_mfma_f32_16x16x32_bf16 v[82:85], v[158:161], v[218:221], v[82:85]
	v_mfma_f32_16x16x32_bf16 v[70:73], v[150:153], v[226:229], v[70:73]
	v_mfma_f32_16x16x32_bf16 v[66:69], v[158:161], v[226:229], v[66:69]
	s_setprio 0
	s_barrier
	s_add_i32 s0, s0, s79
	s_mov_b32 m0, s0
	ds_read_b128 v[184:187], v199 offset:49152
	ds_read_b128 v[188:191], v199 offset:50176
	ds_read_b128 v[206:209], v199 offset:51200
	ds_read_b128 v[210:213], v199 offset:52224
	ds_read_b128 v[214:217], v199 offset:53248
	ds_read_b128 v[218:221], v199 offset:54272
	ds_read_b128 v[222:225], v199 offset:55296
	ds_read_b128 v[226:229], v199 offset:56320
	s_add_u32 s98, s8, 0x80
	s_addc_u32 s99, s9, 0
	global_load_lds_dwordx4 v164, s[98:99]
	s_add_i32 m0, s0, 0x2000
	s_add_u32 s8, s8, 0x40080
	s_addc_u32 s9, s9, 0
	s_add_i32 s0, s27, s79
	global_load_lds_dwordx4 v168, s[98:99]
	s_mov_b32 m0, s0
	s_nop 0
	global_load_lds_dwordx4 v164, s[8:9]
	s_add_i32 m0, s0, 0x2000
	s_nop 0
	global_load_lds_dwordx4 v168, s[8:9]
	s_add_u32 s98, s10, 0xfffc0080
	s_addc_u32 s99, s11, -1
	s_mov_b32 m0, s84
	s_nop 0
	global_load_lds_dwordx4 v162, s[98:99]
	s_mov_b32 m0, s85
	s_nop 0
	global_load_lds_dwordx4 v166, s[98:99]
	s_waitcnt vmcnt(8)
	s_waitcnt lgkmcnt(0)
	s_barrier
	s_setprio 1
	v_mfma_f32_16x16x32_bf16 v[62:65], v[114:117], v[184:187], v[62:65]
	v_mfma_f32_16x16x32_bf16 v[58:61], v[138:141], v[184:187], v[58:61]
	v_mfma_f32_16x16x32_bf16 v[46:49], v[114:117], v[206:209], v[46:49]
	v_mfma_f32_16x16x32_bf16 v[42:45], v[138:141], v[206:209], v[42:45]
	v_mfma_f32_16x16x32_bf16 v[30:33], v[114:117], v[214:217], v[30:33]
	v_mfma_f32_16x16x32_bf16 v[26:29], v[138:141], v[214:217], v[26:29]
	v_mfma_f32_16x16x32_bf16 v[14:17], v[114:117], v[222:225], v[14:17]
	v_mfma_f32_16x16x32_bf16 v[10:13], v[138:141], v[222:225], v[10:13]
	v_mfma_f32_16x16x32_bf16 v[62:65], v[134:137], v[188:191], v[62:65]
	v_mfma_f32_16x16x32_bf16 v[58:61], v[142:145], v[188:191], v[58:61]
	v_mfma_f32_16x16x32_bf16 v[46:49], v[134:137], v[210:213], v[46:49]
	v_mfma_f32_16x16x32_bf16 v[42:45], v[142:145], v[210:213], v[42:45]
	v_mfma_f32_16x16x32_bf16 v[30:33], v[134:137], v[218:221], v[30:33]
	v_mfma_f32_16x16x32_bf16 v[26:29], v[142:145], v[218:221], v[26:29]
	v_mfma_f32_16x16x32_bf16 v[14:17], v[134:137], v[226:229], v[14:17]
	v_mfma_f32_16x16x32_bf16 v[10:13], v[142:145], v[226:229], v[10:13]
	v_mfma_f32_16x16x32_bf16 v[54:57], v[146:149], v[184:187], v[54:57]
	v_mfma_f32_16x16x32_bf16 v[50:53], v[154:157], v[184:187], v[50:53]
	v_mfma_f32_16x16x32_bf16 v[38:41], v[146:149], v[206:209], v[38:41]
	v_mfma_f32_16x16x32_bf16 v[34:37], v[154:157], v[206:209], v[34:37]
	v_mfma_f32_16x16x32_bf16 v[22:25], v[146:149], v[214:217], v[22:25]
	v_mfma_f32_16x16x32_bf16 v[18:21], v[154:157], v[214:217], v[18:21]
	v_mfma_f32_16x16x32_bf16 v[6:9], v[146:149], v[222:225], v[6:9]
	v_mfma_f32_16x16x32_bf16 v[2:5], v[154:157], v[222:225], v[2:5]
	v_mfma_f32_16x16x32_bf16 v[54:57], v[150:153], v[188:191], v[54:57]
	v_mfma_f32_16x16x32_bf16 v[50:53], v[158:161], v[188:191], v[50:53]
	v_mfma_f32_16x16x32_bf16 v[38:41], v[150:153], v[210:213], v[38:41]
	v_mfma_f32_16x16x32_bf16 v[34:37], v[158:161], v[210:213], v[34:37]
	v_mfma_f32_16x16x32_bf16 v[22:25], v[150:153], v[218:221], v[22:25]
	v_mfma_f32_16x16x32_bf16 v[18:21], v[158:161], v[218:221], v[18:21]
	v_mfma_f32_16x16x32_bf16 v[6:9], v[150:153], v[226:229], v[6:9]
	v_mfma_f32_16x16x32_bf16 v[2:5], v[158:161], v[226:229], v[2:5]
	s_setprio 0
	s_barrier
	s_add_i32 s26, s26, 2
	s_add_u32 s6, s6, 0x100
	s_addc_u32 s7, s7, 0
	s_add_u32 s24, s24, 0x100
	s_addc_u32 s25, s25, 0
	s_cmp_gt_u32 s26, 13
	s_cbranch_scc0 .LBB0_368

.LBB0_824:
	ds_read_b128 v[156:159], v185
	ds_read_b128 v[160:163], v185 offset:1024
	ds_read_b128 v[164:167], v185 offset:2048
	ds_read_b128 v[168:171], v185 offset:3072
	ds_read_b128 v[172:175], v186
	ds_read_b128 v[188:191], v186 offset:1024
	ds_read_b128 v[192:195], v186 offset:2048
	ds_read_b128 v[196:199], v186 offset:3072
	s_add_i32 s41, s41, 2
	v_lshl_add_u64 v[176:177], s[38:39], 0, v[154:155]
	v_lshl_add_u64 v[176:177], v[176:177], 0, s[44:45]
	v_lshl_add_u64 v[182:183], v[176:177], 0, s[22:23]
	s_add_i32 m0, s5, 0xc000
	ds_read_b128 v[200:203], v187
	ds_read_b128 v[204:207], v187 offset:1024
	ds_read_b128 v[208:211], v187 offset:2048
	ds_read_b128 v[212:215], v187 offset:3072
	ds_read_b128 v[216:219], v187 offset:4096
	ds_read_b128 v[220:223], v187 offset:5120
	ds_read_b128 v[224:227], v187 offset:6144
	ds_read_b128 v[228:231], v187 offset:7168
	global_load_lds_dwordx4 v[182:183], off
	v_lshl_add_u64 v[182:183], s[38:39], 0, v[150:151]
	v_lshl_add_u64 v[182:183], v[182:183], 0, s[44:45]
	v_lshl_add_u64 v[232:233], v[182:183], 0, s[22:23]
	s_add_i32 m0, s5, 0xe000
	s_nop 0
	global_load_lds_dwordx4 v[232:233], off
	s_waitcnt vmcnt(8)
	s_waitcnt lgkmcnt(0)
	s_barrier
	s_setprio 1
	v_mfma_f32_16x16x32_bf16 v[70:73], v[156:159], v[200:203], v[70:73]
	v_mfma_f32_16x16x32_bf16 v[66:69], v[164:167], v[200:203], v[66:69]
	v_mfma_f32_16x16x32_bf16 v[86:89], v[156:159], v[208:211], v[86:89]
	v_mfma_f32_16x16x32_bf16 v[94:97], v[164:167], v[208:211], v[94:97]
	v_mfma_f32_16x16x32_bf16 v[110:113], v[156:159], v[216:219], v[110:113]
	v_mfma_f32_16x16x32_bf16 v[114:117], v[164:167], v[216:219], v[114:117]
	v_mfma_f32_16x16x32_bf16 v[126:129], v[156:159], v[224:227], v[126:129]
	v_mfma_f32_16x16x32_bf16 v[102:105], v[164:167], v[224:227], v[102:105]
	v_mfma_f32_16x16x32_bf16 v[70:73], v[160:163], v[204:207], v[70:73]
	v_mfma_f32_16x16x32_bf16 v[66:69], v[168:171], v[204:207], v[66:69]
	v_mfma_f32_16x16x32_bf16 v[86:89], v[160:163], v[212:215], v[86:89]
	v_mfma_f32_16x16x32_bf16 v[94:97], v[168:171], v[212:215], v[94:97]
	v_mfma_f32_16x16x32_bf16 v[110:113], v[160:163], v[220:223], v[110:113]
	v_mfma_f32_16x16x32_bf16 v[114:117], v[168:171], v[220:223], v[114:117]
	v_mfma_f32_16x16x32_bf16 v[126:129], v[160:163], v[228:231], v[126:129]
	v_mfma_f32_16x16x32_bf16 v[102:105], v[168:171], v[228:231], v[102:105]
	v_mfma_f32_16x16x32_bf16 v[74:77], v[172:175], v[200:203], v[74:77]
	v_mfma_f32_16x16x32_bf16 v[82:85], v[192:195], v[200:203], v[82:85]
	v_mfma_f32_16x16x32_bf16 v[98:101], v[172:175], v[208:211], v[98:101]
	v_mfma_f32_16x16x32_bf16 v[106:109], v[192:195], v[208:211], v[106:109]
	v_mfma_f32_16x16x32_bf16 v[118:121], v[172:175], v[216:219], v[118:121]
	v_mfma_f32_16x16x32_bf16 v[122:125], v[192:195], v[216:219], v[122:125]
	v_mfma_f32_16x16x32_bf16 v[90:93], v[172:175], v[224:227], v[90:93]
	v_mfma_f32_16x16x32_bf16 v[78:81], v[192:195], v[224:227], v[78:81]
	v_mfma_f32_16x16x32_bf16 v[74:77], v[188:191], v[204:207], v[74:77]
	v_mfma_f32_16x16x32_bf16 v[82:85], v[196:199], v[204:207], v[82:85]
	v_mfma_f32_16x16x32_bf16 v[98:101], v[188:191], v[212:215], v[98:101]
	v_mfma_f32_16x16x32_bf16 v[106:109], v[196:199], v[212:215], v[106:109]
	v_mfma_f32_16x16x32_bf16 v[118:121], v[188:191], v[220:223], v[118:121]
	v_mfma_f32_16x16x32_bf16 v[122:125], v[196:199], v[220:223], v[122:125]
	v_mfma_f32_16x16x32_bf16 v[90:93], v[188:191], v[228:231], v[90:93]
	v_mfma_f32_16x16x32_bf16 v[78:81], v[196:199], v[228:231], v[78:81]
	s_setprio 0
	s_barrier
	v_lshl_add_u64 v[232:233], s[36:37], 0, v[144:145]
	v_lshl_add_u64 v[232:233], v[232:233], 0, s[44:45]
	s_add_i32 s60, s57, s4
	v_lshl_add_u64 v[234:235], v[232:233], 0, s[26:27]
	s_mov_b32 m0, s60
	ds_read_b128 v[200:203], v187 offset:16384
	ds_read_b128 v[204:207], v187 offset:17408
	ds_read_b128 v[208:211], v187 offset:18432
	ds_read_b128 v[212:215], v187 offset:19456
	ds_read_b128 v[216:219], v187 offset:20480
	ds_read_b128 v[220:223], v187 offset:21504
	ds_read_b128 v[224:227], v187 offset:22528
	ds_read_b128 v[228:231], v187 offset:23552
	global_load_lds_dwordx4 v[234:235], off
	v_lshl_add_u64 v[234:235], s[36:37], 0, v[140:141]
	v_lshl_add_u64 v[234:235], v[234:235], 0, s[44:45]
	v_lshl_add_u64 v[236:237], v[234:235], 0, s[26:27]
	s_add_i32 m0, s60, 0x2000
	s_add_i32 s60, s58, s4
	global_load_lds_dwordx4 v[236:237], off
	v_lshl_add_u64 v[236:237], s[36:37], 0, v[146:147]
	v_lshl_add_u64 v[236:237], v[236:237], 0, s[44:45]
	v_lshl_add_u64 v[238:239], v[236:237], 0, s[26:27]
	s_mov_b32 m0, s60
	s_nop 0
	global_load_lds_dwordx4 v[238:239], off
	v_lshl_add_u64 v[238:239], s[36:37], 0, v[142:143]
	v_lshl_add_u64 v[238:239], v[238:239], 0, s[44:45]
	v_lshl_add_u64 v[240:241], v[238:239], 0, s[26:27]
	s_add_i32 m0, s60, 0x2000
	s_nop 0
	global_load_lds_dwordx4 v[240:241], off
	v_lshl_add_u64 v[240:241], s[38:39], 0, v[152:153]
	v_lshl_add_u64 v[240:241], v[240:241], 0, s[44:45]
	v_lshl_add_u64 v[242:243], v[240:241], 0, s[26:27]
	s_mov_b32 m0, s5
	s_nop 0
	global_load_lds_dwordx4 v[242:243], off
	v_lshl_add_u64 v[242:243], s[38:39], 0, v[148:149]
	v_lshl_add_u64 v[242:243], v[242:243], 0, s[44:45]
	v_lshl_add_u64 v[244:245], v[242:243], 0, s[26:27]
	s_mov_b32 m0, s46
	s_nop 0
	global_load_lds_dwordx4 v[244:245], off
	s_waitcnt vmcnt(8)
	s_waitcnt lgkmcnt(0)
	s_barrier
	s_setprio 1
	v_mfma_f32_16x16x32_bf16 v[62:65], v[156:159], v[200:203], v[62:65]
	v_mfma_f32_16x16x32_bf16 v[58:61], v[164:167], v[200:203], v[58:61]
	v_mfma_f32_16x16x32_bf16 v[46:49], v[156:159], v[208:211], v[46:49]
	v_mfma_f32_16x16x32_bf16 v[42:45], v[164:167], v[208:211], v[42:45]
	v_mfma_f32_16x16x32_bf16 v[30:33], v[156:159], v[216:219], v[30:33]
	v_mfma_f32_16x16x32_bf16 v[26:29], v[164:167], v[216:219], v[26:29]
	v_mfma_f32_16x16x32_bf16 v[14:17], v[156:159], v[224:227], v[14:17]
	v_mfma_f32_16x16x32_bf16 v[10:13], v[164:167], v[224:227], v[10:13]
	v_mfma_f32_16x16x32_bf16 v[62:65], v[160:163], v[204:207], v[62:65]
	v_mfma_f32_16x16x32_bf16 v[58:61], v[168:171], v[204:207], v[58:61]
	v_mfma_f32_16x16x32_bf16 v[46:49], v[160:163], v[212:215], v[46:49]
	v_mfma_f32_16x16x32_bf16 v[42:45], v[168:171], v[212:215], v[42:45]
	v_mfma_f32_16x16x32_bf16 v[30:33], v[160:163], v[220:223], v[30:33]
	v_mfma_f32_16x16x32_bf16 v[26:29], v[168:171], v[220:223], v[26:29]
	v_mfma_f32_16x16x32_bf16 v[14:17], v[160:163], v[228:231], v[14:17]
	v_mfma_f32_16x16x32_bf16 v[10:13], v[168:171], v[228:231], v[10:13]
	v_mfma_f32_16x16x32_bf16 v[54:57], v[172:175], v[200:203], v[54:57]
	v_mfma_f32_16x16x32_bf16 v[50:53], v[192:195], v[200:203], v[50:53]
	v_mfma_f32_16x16x32_bf16 v[38:41], v[172:175], v[208:211], v[38:41]
	v_mfma_f32_16x16x32_bf16 v[34:37], v[192:195], v[208:211], v[34:37]
	v_mfma_f32_16x16x32_bf16 v[22:25], v[172:175], v[216:219], v[22:25]
	v_mfma_f32_16x16x32_bf16 v[18:21], v[192:195], v[216:219], v[18:21]
	v_mfma_f32_16x16x32_bf16 v[6:9], v[172:175], v[224:227], v[6:9]
	v_mfma_f32_16x16x32_bf16 v[2:5], v[192:195], v[224:227], v[2:5]
	v_mfma_f32_16x16x32_bf16 v[54:57], v[188:191], v[204:207], v[54:57]
	v_mfma_f32_16x16x32_bf16 v[50:53], v[196:199], v[204:207], v[50:53]
	v_mfma_f32_16x16x32_bf16 v[38:41], v[188:191], v[212:215], v[38:41]
	v_mfma_f32_16x16x32_bf16 v[34:37], v[196:199], v[212:215], v[34:37]
	v_mfma_f32_16x16x32_bf16 v[22:25], v[188:191], v[220:223], v[22:25]
	v_mfma_f32_16x16x32_bf16 v[18:21], v[196:199], v[220:223], v[18:21]
	v_mfma_f32_16x16x32_bf16 v[6:9], v[188:191], v[228:231], v[6:9]
	v_mfma_f32_16x16x32_bf16 v[2:5], v[196:199], v[228:231], v[2:5]
	s_setprio 0
	s_barrier
	s_add_i32 s60, 0, 0x18000
	v_add_u32_e32 v138, s60, v181
	s_add_i32 s61, 0, 0x1c000
	ds_read_b128 v[156:159], v138
	ds_read_b128 v[160:163], v138 offset:1024
	ds_read_b128 v[164:167], v138 offset:2048
	ds_read_b128 v[168:171], v138 offset:3072
	v_add_u32_e32 v138, s61, v181
	ds_read_b128 v[172:175], v138
	ds_read_b128 v[188:191], v138 offset:1024
	ds_read_b128 v[192:195], v138 offset:2048
	ds_read_b128 v[196:199], v138 offset:3072
	s_mov_b32 m0, s47
	v_lshl_add_u64 v[176:177], v[176:177], 0, s[26:27]
	ds_read_b128 v[200:203], v187 offset:32768
	ds_read_b128 v[204:207], v187 offset:33792
	ds_read_b128 v[208:211], v187 offset:34816
	ds_read_b128 v[212:215], v187 offset:35840
	ds_read_b128 v[216:219], v187 offset:36864
	ds_read_b128 v[220:223], v187 offset:37888
	ds_read_b128 v[224:227], v187 offset:38912
	ds_read_b128 v[228:231], v187 offset:39936
	global_load_lds_dwordx4 v[176:177], off
	v_lshl_add_u64 v[176:177], v[182:183], 0, s[26:27]
	s_mov_b32 m0, s48
	s_nop 0
	global_load_lds_dwordx4 v[176:177], off
	s_waitcnt vmcnt(8)
	s_waitcnt lgkmcnt(0)
	s_barrier
	s_setprio 1
	v_mfma_f32_16x16x32_bf16 v[70:73], v[156:159], v[200:203], v[70:73]
	v_mfma_f32_16x16x32_bf16 v[66:69], v[164:167], v[200:203], v[66:69]
	v_mfma_f32_16x16x32_bf16 v[86:89], v[156:159], v[208:211], v[86:89]
	v_mfma_f32_16x16x32_bf16 v[94:97], v[164:167], v[208:211], v[94:97]
	v_mfma_f32_16x16x32_bf16 v[110:113], v[156:159], v[216:219], v[110:113]
	v_mfma_f32_16x16x32_bf16 v[114:117], v[164:167], v[216:219], v[114:117]
	v_mfma_f32_16x16x32_bf16 v[126:129], v[156:159], v[224:227], v[126:129]
	v_mfma_f32_16x16x32_bf16 v[102:105], v[164:167], v[224:227], v[102:105]
	v_mfma_f32_16x16x32_bf16 v[70:73], v[160:163], v[204:207], v[70:73]
	v_mfma_f32_16x16x32_bf16 v[66:69], v[168:171], v[204:207], v[66:69]
	v_mfma_f32_16x16x32_bf16 v[86:89], v[160:163], v[212:215], v[86:89]
	v_mfma_f32_16x16x32_bf16 v[94:97], v[168:171], v[212:215], v[94:97]
	v_mfma_f32_16x16x32_bf16 v[110:113], v[160:163], v[220:223], v[110:113]
	v_mfma_f32_16x16x32_bf16 v[114:117], v[168:171], v[220:223], v[114:117]
	v_mfma_f32_16x16x32_bf16 v[126:129], v[160:163], v[228:231], v[126:129]
	v_mfma_f32_16x16x32_bf16 v[102:105], v[168:171], v[228:231], v[102:105]
	v_mfma_f32_16x16x32_bf16 v[74:77], v[172:175], v[200:203], v[74:77]
	v_mfma_f32_16x16x32_bf16 v[82:85], v[192:195], v[200:203], v[82:85]
	v_mfma_f32_16x16x32_bf16 v[98:101], v[172:175], v[208:211], v[98:101]
	v_mfma_f32_16x16x32_bf16 v[106:109], v[192:195], v[208:211], v[106:109]
	v_mfma_f32_16x16x32_bf16 v[118:121], v[172:175], v[216:219], v[118:121]
	v_mfma_f32_16x16x32_bf16 v[122:125], v[192:195], v[216:219], v[122:125]
	v_mfma_f32_16x16x32_bf16 v[90:93], v[172:175], v[224:227], v[90:93]
	v_mfma_f32_16x16x32_bf16 v[78:81], v[192:195], v[224:227], v[78:81]
	v_mfma_f32_16x16x32_bf16 v[74:77], v[188:191], v[204:207], v[74:77]
	v_mfma_f32_16x16x32_bf16 v[82:85], v[196:199], v[204:207], v[82:85]
	v_mfma_f32_16x16x32_bf16 v[98:101], v[188:191], v[212:215], v[98:101]
	v_mfma_f32_16x16x32_bf16 v[106:109], v[196:199], v[212:215], v[106:109]
	v_mfma_f32_16x16x32_bf16 v[118:121], v[188:191], v[220:223], v[118:121]
	v_mfma_f32_16x16x32_bf16 v[122:125], v[196:199], v[220:223], v[122:125]
	v_mfma_f32_16x16x32_bf16 v[90:93], v[188:191], v[228:231], v[90:93]
	v_mfma_f32_16x16x32_bf16 v[78:81], v[196:199], v[228:231], v[78:81]
	s_setprio 0
	s_barrier
	s_add_i32 s60, s60, s4
	v_lshl_add_u64 v[176:177], v[232:233], 0, s[28:29]
	s_mov_b32 m0, s60
	ds_read_b128 v[200:203], v187 offset:49152
	ds_read_b128 v[204:207], v187 offset:50176
	ds_read_b128 v[208:211], v187 offset:51200
	ds_read_b128 v[212:215], v187 offset:52224
	ds_read_b128 v[216:219], v187 offset:53248
	ds_read_b128 v[220:223], v187 offset:54272
	ds_read_b128 v[224:227], v187 offset:55296
	ds_read_b128 v[228:231], v187 offset:56320
	global_load_lds_dwordx4 v[176:177], off
	v_lshl_add_u64 v[176:177], v[234:235], 0, s[28:29]
	s_add_i32 m0, s60, 0x2000
	s_add_i32 s60, s61, s4
	global_load_lds_dwordx4 v[176:177], off
	v_lshl_add_u64 v[176:177], v[236:237], 0, s[28:29]
	s_mov_b32 m0, s60
	s_nop 0
	global_load_lds_dwordx4 v[176:177], off
	v_lshl_add_u64 v[176:177], v[238:239], 0, s[28:29]
	s_add_i32 m0, s60, 0x2000
	s_nop 0
	global_load_lds_dwordx4 v[176:177], off
	v_lshl_add_u64 v[176:177], v[240:241], 0, s[28:29]
	s_mov_b32 m0, s49
	s_nop 0
	global_load_lds_dwordx4 v[176:177], off
	v_lshl_add_u64 v[176:177], v[242:243], 0, s[28:29]
	s_mov_b32 m0, s50
	s_nop 0
	global_load_lds_dwordx4 v[176:177], off
	s_waitcnt vmcnt(8)
	s_waitcnt lgkmcnt(0)
	s_barrier
	s_setprio 1
	v_mfma_f32_16x16x32_bf16 v[62:65], v[156:159], v[200:203], v[62:65]
	v_mfma_f32_16x16x32_bf16 v[58:61], v[164:167], v[200:203], v[58:61]
	v_mfma_f32_16x16x32_bf16 v[46:49], v[156:159], v[208:211], v[46:49]
	v_mfma_f32_16x16x32_bf16 v[42:45], v[164:167], v[208:211], v[42:45]
	v_mfma_f32_16x16x32_bf16 v[30:33], v[156:159], v[216:219], v[30:33]
	v_mfma_f32_16x16x32_bf16 v[26:29], v[164:167], v[216:219], v[26:29]
	v_mfma_f32_16x16x32_bf16 v[14:17], v[156:159], v[224:227], v[14:17]
	v_mfma_f32_16x16x32_bf16 v[10:13], v[164:167], v[224:227], v[10:13]
	v_mfma_f32_16x16x32_bf16 v[62:65], v[160:163], v[204:207], v[62:65]
	v_mfma_f32_16x16x32_bf16 v[58:61], v[168:171], v[204:207], v[58:61]
	v_mfma_f32_16x16x32_bf16 v[46:49], v[160:163], v[212:215], v[46:49]
	v_mfma_f32_16x16x32_bf16 v[42:45], v[168:171], v[212:215], v[42:45]
	v_mfma_f32_16x16x32_bf16 v[30:33], v[160:163], v[220:223], v[30:33]
	v_mfma_f32_16x16x32_bf16 v[26:29], v[168:171], v[220:223], v[26:29]
	v_mfma_f32_16x16x32_bf16 v[14:17], v[160:163], v[228:231], v[14:17]
	v_mfma_f32_16x16x32_bf16 v[10:13], v[168:171], v[228:231], v[10:13]
	v_mfma_f32_16x16x32_bf16 v[54:57], v[172:175], v[200:203], v[54:57]
	v_mfma_f32_16x16x32_bf16 v[50:53], v[192:195], v[200:203], v[50:53]
	v_mfma_f32_16x16x32_bf16 v[38:41], v[172:175], v[208:211], v[38:41]
	v_mfma_f32_16x16x32_bf16 v[34:37], v[192:195], v[208:211], v[34:37]
	v_mfma_f32_16x16x32_bf16 v[22:25], v[172:175], v[216:219], v[22:25]
	v_mfma_f32_16x16x32_bf16 v[18:21], v[192:195], v[216:219], v[18:21]
	v_mfma_f32_16x16x32_bf16 v[6:9], v[172:175], v[224:227], v[6:9]
	v_mfma_f32_16x16x32_bf16 v[2:5], v[192:195], v[224:227], v[2:5]
	v_mfma_f32_16x16x32_bf16 v[54:57], v[188:191], v[204:207], v[54:57]
	v_mfma_f32_16x16x32_bf16 v[50:53], v[196:199], v[204:207], v[50:53]
	v_mfma_f32_16x16x32_bf16 v[38:41], v[188:191], v[212:215], v[38:41]
	v_mfma_f32_16x16x32_bf16 v[34:37], v[196:199], v[212:215], v[34:37]
	v_mfma_f32_16x16x32_bf16 v[22:25], v[188:191], v[220:223], v[22:25]
	v_mfma_f32_16x16x32_bf16 v[18:21], v[196:199], v[220:223], v[18:21]
	v_mfma_f32_16x16x32_bf16 v[6:9], v[188:191], v[228:231], v[6:9]
	v_mfma_f32_16x16x32_bf16 v[2:5], v[196:199], v[228:231], v[2:5]
	s_setprio 0
	s_barrier
	s_add_u32 s44, s44, 0x100
	s_addc_u32 s45, s45, 0
	s_cmp_ge_i32 s41, s40
	s_cbranch_scc0 .LBB0_824
	s_branch .LBB0_826

.LBB0_828:
	ds_read_b128 v[158:161], v185
	ds_read_b128 v[162:165], v185 offset:1024
	ds_read_b128 v[166:169], v185 offset:2048
	ds_read_b128 v[170:173], v185 offset:3072
	ds_read_b128 v[174:177], v186
	ds_read_b128 v[190:193], v186 offset:1024
	ds_read_b128 v[194:197], v186 offset:2048
	ds_read_b128 v[198:201], v186 offset:3072
	s_add_i32 s42, s40, 1
	s_ashr_i32 s43, s42, 31
	s_lshl_b64 s[44:45], s[42:43], 7
	s_add_i32 s42, s40, 2
	s_add_u32 s43, s38, s0
	s_addc_u32 s41, s39, s1
	s_add_u32 s60, s36, s0
	s_addc_u32 s61, s37, s1
	s_cmp_eq_u32 s52, s40
	s_cselect_b32 s41, s13, s41
	s_cselect_b32 s40, s12, s43
	s_cselect_b32 s61, s35, s61
	s_cselect_b32 s60, s34, s60
	s_add_u32 s43, s38, s44
	s_addc_u32 s45, s39, s45
	s_add_u32 s44, s43, s8
	s_addc_u32 s45, s45, s9
	v_lshl_add_u64 v[182:183], s[44:45], 0, v[136:137]
	s_add_i32 m0, s5, 0xc000
	ds_read_b128 v[202:205], v187
	ds_read_b128 v[206:209], v187 offset:1024
	ds_read_b128 v[210:213], v187 offset:2048
	ds_read_b128 v[214:217], v187 offset:3072
	ds_read_b128 v[218:221], v187 offset:4096
	ds_read_b128 v[222:225], v187 offset:5120
	ds_read_b128 v[226:229], v187 offset:6144
	ds_read_b128 v[230:233], v187 offset:7168
	global_load_lds_dwordx4 v[182:183], off
	v_lshl_add_u64 v[182:183], s[44:45], 0, v[132:133]
	s_add_i32 m0, s5, 0xe000
	s_nop 0
	global_load_lds_dwordx4 v[182:183], off
	s_waitcnt vmcnt(8)
	s_waitcnt lgkmcnt(0)
	s_barrier
	s_setprio 1
	v_mfma_f32_16x16x32_bf16 v[70:73], v[158:161], v[202:205], v[70:73]
	v_mfma_f32_16x16x32_bf16 v[66:69], v[166:169], v[202:205], v[66:69]
	v_mfma_f32_16x16x32_bf16 v[86:89], v[158:161], v[210:213], v[86:89]
	v_mfma_f32_16x16x32_bf16 v[94:97], v[166:169], v[210:213], v[94:97]
	v_mfma_f32_16x16x32_bf16 v[110:113], v[158:161], v[218:221], v[110:113]
	v_mfma_f32_16x16x32_bf16 v[114:117], v[166:169], v[218:221], v[114:117]
	v_mfma_f32_16x16x32_bf16 v[126:129], v[158:161], v[226:229], v[126:129]
	v_mfma_f32_16x16x32_bf16 v[102:105], v[166:169], v[226:229], v[102:105]
	v_mfma_f32_16x16x32_bf16 v[70:73], v[162:165], v[206:209], v[70:73]
	v_mfma_f32_16x16x32_bf16 v[66:69], v[170:173], v[206:209], v[66:69]
	v_mfma_f32_16x16x32_bf16 v[86:89], v[162:165], v[214:217], v[86:89]
	v_mfma_f32_16x16x32_bf16 v[94:97], v[170:173], v[214:217], v[94:97]
	v_mfma_f32_16x16x32_bf16 v[110:113], v[162:165], v[222:225], v[110:113]
	v_mfma_f32_16x16x32_bf16 v[114:117], v[170:173], v[222:225], v[114:117]
	v_mfma_f32_16x16x32_bf16 v[126:129], v[162:165], v[230:233], v[126:129]
	v_mfma_f32_16x16x32_bf16 v[102:105], v[170:173], v[230:233], v[102:105]
	v_mfma_f32_16x16x32_bf16 v[74:77], v[174:177], v[202:205], v[74:77]
	v_mfma_f32_16x16x32_bf16 v[82:85], v[194:197], v[202:205], v[82:85]
	v_mfma_f32_16x16x32_bf16 v[98:101], v[174:177], v[210:213], v[98:101]
	v_mfma_f32_16x16x32_bf16 v[106:109], v[194:197], v[210:213], v[106:109]
	v_mfma_f32_16x16x32_bf16 v[118:121], v[174:177], v[218:221], v[118:121]
	v_mfma_f32_16x16x32_bf16 v[122:125], v[194:197], v[218:221], v[122:125]
	v_mfma_f32_16x16x32_bf16 v[90:93], v[174:177], v[226:229], v[90:93]
	v_mfma_f32_16x16x32_bf16 v[78:81], v[194:197], v[226:229], v[78:81]
	v_mfma_f32_16x16x32_bf16 v[74:77], v[190:193], v[206:209], v[74:77]
	v_mfma_f32_16x16x32_bf16 v[82:85], v[198:201], v[206:209], v[82:85]
	v_mfma_f32_16x16x32_bf16 v[98:101], v[190:193], v[214:217], v[98:101]
	v_mfma_f32_16x16x32_bf16 v[106:109], v[198:201], v[214:217], v[106:109]
	v_mfma_f32_16x16x32_bf16 v[118:121], v[190:193], v[222:225], v[118:121]
	v_mfma_f32_16x16x32_bf16 v[122:125], v[198:201], v[222:225], v[122:125]
	v_mfma_f32_16x16x32_bf16 v[90:93], v[190:193], v[230:233], v[90:93]
	v_mfma_f32_16x16x32_bf16 v[78:81], v[198:201], v[230:233], v[78:81]
	s_setprio 0
	s_barrier
	s_add_i32 s43, s57, s4
	v_lshl_add_u64 v[182:183], s[60:61], 0, v[134:135]
	s_mov_b32 m0, s43
	ds_read_b128 v[202:205], v187 offset:16384
	ds_read_b128 v[206:209], v187 offset:17408
	ds_read_b128 v[210:213], v187 offset:18432
	ds_read_b128 v[214:217], v187 offset:19456
	ds_read_b128 v[218:221], v187 offset:20480
	ds_read_b128 v[222:225], v187 offset:21504
	ds_read_b128 v[226:229], v187 offset:22528
	ds_read_b128 v[230:233], v187 offset:23552
	global_load_lds_dwordx4 v[182:183], off
	s_add_i32 m0, s43, 0x2000
	s_add_u32 s44, s60, s8
	v_lshl_add_u64 v[234:235], s[60:61], 0, v[130:131]
	s_addc_u32 s45, s61, s9
	s_add_i32 s43, s58, s4
	global_load_lds_dwordx4 v[234:235], off
	v_lshl_add_u64 v[236:237], s[44:45], 0, v[134:135]
	s_mov_b32 m0, s43
	v_lshl_add_u64 v[238:239], s[44:45], 0, v[130:131]
	global_load_lds_dwordx4 v[236:237], off
	s_add_i32 m0, s43, 0x2000
	v_lshl_add_u64 v[240:241], s[40:41], 0, v[136:137]
	global_load_lds_dwordx4 v[238:239], off
	s_mov_b32 m0, s5
	v_lshl_add_u64 v[242:243], s[40:41], 0, v[132:133]
	global_load_lds_dwordx4 v[240:241], off
	s_mov_b32 m0, s46
	s_nop 0
	global_load_lds_dwordx4 v[242:243], off
	s_waitcnt vmcnt(8)
	s_waitcnt lgkmcnt(0)
	s_barrier
	s_setprio 1
	v_mfma_f32_16x16x32_bf16 v[62:65], v[158:161], v[202:205], v[62:65]
	v_mfma_f32_16x16x32_bf16 v[58:61], v[166:169], v[202:205], v[58:61]
	v_mfma_f32_16x16x32_bf16 v[46:49], v[158:161], v[210:213], v[46:49]
	v_mfma_f32_16x16x32_bf16 v[42:45], v[166:169], v[210:213], v[42:45]
	v_mfma_f32_16x16x32_bf16 v[30:33], v[158:161], v[218:221], v[30:33]
	v_mfma_f32_16x16x32_bf16 v[26:29], v[166:169], v[218:221], v[26:29]
	v_mfma_f32_16x16x32_bf16 v[14:17], v[158:161], v[226:229], v[14:17]
	v_mfma_f32_16x16x32_bf16 v[10:13], v[166:169], v[226:229], v[10:13]
	v_mfma_f32_16x16x32_bf16 v[62:65], v[162:165], v[206:209], v[62:65]
	v_mfma_f32_16x16x32_bf16 v[58:61], v[170:173], v[206:209], v[58:61]
	v_mfma_f32_16x16x32_bf16 v[46:49], v[162:165], v[214:217], v[46:49]
	v_mfma_f32_16x16x32_bf16 v[42:45], v[170:173], v[214:217], v[42:45]
	v_mfma_f32_16x16x32_bf16 v[30:33], v[162:165], v[222:225], v[30:33]
	v_mfma_f32_16x16x32_bf16 v[26:29], v[170:173], v[222:225], v[26:29]
	v_mfma_f32_16x16x32_bf16 v[14:17], v[162:165], v[230:233], v[14:17]
	v_mfma_f32_16x16x32_bf16 v[10:13], v[170:173], v[230:233], v[10:13]
	v_mfma_f32_16x16x32_bf16 v[54:57], v[174:177], v[202:205], v[54:57]
	v_mfma_f32_16x16x32_bf16 v[50:53], v[194:197], v[202:205], v[50:53]
	v_mfma_f32_16x16x32_bf16 v[38:41], v[174:177], v[210:213], v[38:41]
	v_mfma_f32_16x16x32_bf16 v[34:37], v[194:197], v[210:213], v[34:37]
	v_mfma_f32_16x16x32_bf16 v[22:25], v[174:177], v[218:221], v[22:25]
	v_mfma_f32_16x16x32_bf16 v[18:21], v[194:197], v[218:221], v[18:21]
	v_mfma_f32_16x16x32_bf16 v[6:9], v[174:177], v[226:229], v[6:9]
	v_mfma_f32_16x16x32_bf16 v[2:5], v[194:197], v[226:229], v[2:5]
	v_mfma_f32_16x16x32_bf16 v[54:57], v[190:193], v[206:209], v[54:57]
	v_mfma_f32_16x16x32_bf16 v[50:53], v[198:201], v[206:209], v[50:53]
	v_mfma_f32_16x16x32_bf16 v[38:41], v[190:193], v[214:217], v[38:41]
	v_mfma_f32_16x16x32_bf16 v[34:37], v[198:201], v[214:217], v[34:37]
	v_mfma_f32_16x16x32_bf16 v[22:25], v[190:193], v[222:225], v[22:25]
	v_mfma_f32_16x16x32_bf16 v[18:21], v[198:201], v[222:225], v[18:21]
	v_mfma_f32_16x16x32_bf16 v[6:9], v[190:193], v[230:233], v[6:9]
	v_mfma_f32_16x16x32_bf16 v[2:5], v[198:201], v[230:233], v[2:5]
	s_setprio 0
	s_barrier
	s_add_i32 s43, 0, 0x18000
	v_add_u32_e32 v138, s43, v181
	s_add_i32 s44, 0, 0x1c000
	ds_read_b128 v[158:161], v138
	ds_read_b128 v[162:165], v138 offset:1024
	ds_read_b128 v[166:169], v138 offset:2048
	ds_read_b128 v[170:173], v138 offset:3072
	v_add_u32_e32 v138, s44, v181
	ds_read_b128 v[174:177], v138
	ds_read_b128 v[190:193], v138 offset:1024
	ds_read_b128 v[194:197], v138 offset:2048
	ds_read_b128 v[198:201], v138 offset:3072
	s_add_u32 s40, s40, s8
	s_addc_u32 s41, s41, s9
	s_mov_b32 m0, s47
	v_lshl_add_u64 v[244:245], s[40:41], 0, v[136:137]
	ds_read_b128 v[202:205], v187 offset:32768
	ds_read_b128 v[206:209], v187 offset:33792
	ds_read_b128 v[210:213], v187 offset:34816
	ds_read_b128 v[214:217], v187 offset:35840
	ds_read_b128 v[218:221], v187 offset:36864
	ds_read_b128 v[222:225], v187 offset:37888
	ds_read_b128 v[226:229], v187 offset:38912
	ds_read_b128 v[230:233], v187 offset:39936
	global_load_lds_dwordx4 v[244:245], off
	v_lshl_add_u64 v[244:245], s[40:41], 0, v[132:133]
	s_mov_b32 m0, s48
	s_nop 0
	global_load_lds_dwordx4 v[244:245], off
	s_waitcnt vmcnt(8)
	s_waitcnt lgkmcnt(0)
	s_barrier
	s_setprio 1
	v_mfma_f32_16x16x32_bf16 v[70:73], v[158:161], v[202:205], v[70:73]
	v_mfma_f32_16x16x32_bf16 v[66:69], v[166:169], v[202:205], v[66:69]
	v_mfma_f32_16x16x32_bf16 v[86:89], v[158:161], v[210:213], v[86:89]
	v_mfma_f32_16x16x32_bf16 v[94:97], v[166:169], v[210:213], v[94:97]
	v_mfma_f32_16x16x32_bf16 v[110:113], v[158:161], v[218:221], v[110:113]
	v_mfma_f32_16x16x32_bf16 v[114:117], v[166:169], v[218:221], v[114:117]
	v_mfma_f32_16x16x32_bf16 v[126:129], v[158:161], v[226:229], v[126:129]
	v_mfma_f32_16x16x32_bf16 v[102:105], v[166:169], v[226:229], v[102:105]
	v_mfma_f32_16x16x32_bf16 v[70:73], v[162:165], v[206:209], v[70:73]
	v_mfma_f32_16x16x32_bf16 v[66:69], v[170:173], v[206:209], v[66:69]
	v_mfma_f32_16x16x32_bf16 v[86:89], v[162:165], v[214:217], v[86:89]
	v_mfma_f32_16x16x32_bf16 v[94:97], v[170:173], v[214:217], v[94:97]
	v_mfma_f32_16x16x32_bf16 v[110:113], v[162:165], v[222:225], v[110:113]
	v_mfma_f32_16x16x32_bf16 v[114:117], v[170:173], v[222:225], v[114:117]
	v_mfma_f32_16x16x32_bf16 v[126:129], v[162:165], v[230:233], v[126:129]
	v_mfma_f32_16x16x32_bf16 v[102:105], v[170:173], v[230:233], v[102:105]
	v_mfma_f32_16x16x32_bf16 v[74:77], v[174:177], v[202:205], v[74:77]
	v_mfma_f32_16x16x32_bf16 v[82:85], v[194:197], v[202:205], v[82:85]
	v_mfma_f32_16x16x32_bf16 v[98:101], v[174:177], v[210:213], v[98:101]
	v_mfma_f32_16x16x32_bf16 v[106:109], v[194:197], v[210:213], v[106:109]
	v_mfma_f32_16x16x32_bf16 v[118:121], v[174:177], v[218:221], v[118:121]
	v_mfma_f32_16x16x32_bf16 v[122:125], v[194:197], v[218:221], v[122:125]
	v_mfma_f32_16x16x32_bf16 v[90:93], v[174:177], v[226:229], v[90:93]
	v_mfma_f32_16x16x32_bf16 v[78:81], v[194:197], v[226:229], v[78:81]
	v_mfma_f32_16x16x32_bf16 v[74:77], v[190:193], v[206:209], v[74:77]
	v_mfma_f32_16x16x32_bf16 v[82:85], v[198:201], v[206:209], v[82:85]
	v_mfma_f32_16x16x32_bf16 v[98:101], v[190:193], v[214:217], v[98:101]
	v_mfma_f32_16x16x32_bf16 v[106:109], v[198:201], v[214:217], v[106:109]
	v_mfma_f32_16x16x32_bf16 v[118:121], v[190:193], v[222:225], v[118:121]
	v_mfma_f32_16x16x32_bf16 v[122:125], v[198:201], v[222:225], v[122:125]
	v_mfma_f32_16x16x32_bf16 v[90:93], v[190:193], v[230:233], v[90:93]
	v_mfma_f32_16x16x32_bf16 v[78:81], v[198:201], v[230:233], v[78:81]
	s_setprio 0
	s_barrier
	s_add_i32 s40, s43, s4
	v_lshl_add_u64 v[182:183], v[182:183], 0, s[22:23]
	s_mov_b32 m0, s40
	ds_read_b128 v[202:205], v187 offset:49152
	ds_read_b128 v[206:209], v187 offset:50176
	ds_read_b128 v[210:213], v187 offset:51200
	ds_read_b128 v[214:217], v187 offset:52224
	ds_read_b128 v[218:221], v187 offset:53248
	ds_read_b128 v[222:225], v187 offset:54272
	ds_read_b128 v[226:229], v187 offset:55296
	ds_read_b128 v[230:233], v187 offset:56320
	global_load_lds_dwordx4 v[182:183], off
	v_lshl_add_u64 v[182:183], v[234:235], 0, s[22:23]
	s_add_i32 m0, s40, 0x2000
	s_add_i32 s40, s44, s4
	global_load_lds_dwordx4 v[182:183], off
	v_lshl_add_u64 v[182:183], v[236:237], 0, s[22:23]
	s_mov_b32 m0, s40
	s_nop 0
	global_load_lds_dwordx4 v[182:183], off
	v_lshl_add_u64 v[182:183], v[238:239], 0, s[22:23]
	s_add_i32 m0, s40, 0x2000
	s_nop 0
	global_load_lds_dwordx4 v[182:183], off
	v_lshl_add_u64 v[182:183], v[240:241], 0, s[22:23]
	s_mov_b32 m0, s49
	s_nop 0
	global_load_lds_dwordx4 v[182:183], off
	v_lshl_add_u64 v[182:183], v[242:243], 0, s[22:23]
	s_mov_b32 m0, s50
	s_nop 0
	global_load_lds_dwordx4 v[182:183], off
	s_waitcnt vmcnt(8)
	s_waitcnt lgkmcnt(0)
	s_barrier
	s_setprio 1
	v_mfma_f32_16x16x32_bf16 v[62:65], v[158:161], v[202:205], v[62:65]
	v_mfma_f32_16x16x32_bf16 v[58:61], v[166:169], v[202:205], v[58:61]
	v_mfma_f32_16x16x32_bf16 v[46:49], v[158:161], v[210:213], v[46:49]
	v_mfma_f32_16x16x32_bf16 v[42:45], v[166:169], v[210:213], v[42:45]
	v_mfma_f32_16x16x32_bf16 v[30:33], v[158:161], v[218:221], v[30:33]
	v_mfma_f32_16x16x32_bf16 v[26:29], v[166:169], v[218:221], v[26:29]
	v_mfma_f32_16x16x32_bf16 v[14:17], v[158:161], v[226:229], v[14:17]
	v_mfma_f32_16x16x32_bf16 v[10:13], v[166:169], v[226:229], v[10:13]
	v_mfma_f32_16x16x32_bf16 v[62:65], v[162:165], v[206:209], v[62:65]
	v_mfma_f32_16x16x32_bf16 v[58:61], v[170:173], v[206:209], v[58:61]
	v_mfma_f32_16x16x32_bf16 v[46:49], v[162:165], v[214:217], v[46:49]
	v_mfma_f32_16x16x32_bf16 v[42:45], v[170:173], v[214:217], v[42:45]
	v_mfma_f32_16x16x32_bf16 v[30:33], v[162:165], v[222:225], v[30:33]
	v_mfma_f32_16x16x32_bf16 v[26:29], v[170:173], v[222:225], v[26:29]
	v_mfma_f32_16x16x32_bf16 v[14:17], v[162:165], v[230:233], v[14:17]
	v_mfma_f32_16x16x32_bf16 v[10:13], v[170:173], v[230:233], v[10:13]
	v_mfma_f32_16x16x32_bf16 v[54:57], v[174:177], v[202:205], v[54:57]
	v_mfma_f32_16x16x32_bf16 v[50:53], v[194:197], v[202:205], v[50:53]
	v_mfma_f32_16x16x32_bf16 v[38:41], v[174:177], v[210:213], v[38:41]
	v_mfma_f32_16x16x32_bf16 v[34:37], v[194:197], v[210:213], v[34:37]
	v_mfma_f32_16x16x32_bf16 v[22:25], v[174:177], v[218:221], v[22:25]
	v_mfma_f32_16x16x32_bf16 v[18:21], v[194:197], v[218:221], v[18:21]
	v_mfma_f32_16x16x32_bf16 v[6:9], v[174:177], v[226:229], v[6:9]
	v_mfma_f32_16x16x32_bf16 v[2:5], v[194:197], v[226:229], v[2:5]
	v_mfma_f32_16x16x32_bf16 v[54:57], v[190:193], v[206:209], v[54:57]
	v_mfma_f32_16x16x32_bf16 v[50:53], v[198:201], v[206:209], v[50:53]
	v_mfma_f32_16x16x32_bf16 v[38:41], v[190:193], v[214:217], v[38:41]
	v_mfma_f32_16x16x32_bf16 v[34:37], v[198:201], v[214:217], v[34:37]
	v_mfma_f32_16x16x32_bf16 v[22:25], v[190:193], v[222:225], v[22:25]
	v_mfma_f32_16x16x32_bf16 v[18:21], v[198:201], v[222:225], v[18:21]
	v_mfma_f32_16x16x32_bf16 v[6:9], v[190:193], v[230:233], v[6:9]
	v_mfma_f32_16x16x32_bf16 v[2:5], v[198:201], v[230:233], v[2:5]
	s_setprio 0
	s_barrier
	s_add_u32 s0, s0, 0x100
	s_addc_u32 s1, s1, 0
	s_cmp_ge_i32 s42, s51
	s_mov_b32 s40, s42
	s_cbranch_scc0 .LBB0_828

.LBB0_902:
	s_mov_b64 s[28:29], s[10:11]
	s_mov_b32 s10, s37
	s_mov_b32 s0, s37
	s_add_i32 s37, s47, s1
	s_mov_b64 s[30:31], s[8:9]
	s_and_b64 s[8:9], s[26:27], exec
	s_cselect_b32 s8, s37, s10
	s_cselect_b32 s10, s46, s46
	s_ashr_i32 s11, s10, 31
	s_lshl_b64 s[10:11], s[10:11], 19
	s_add_u32 s10, s2, s10
	s_addc_u32 s11, s3, s11
	s_and_b64 s[34:35], s[26:27], exec
	s_cselect_b32 s1, s11, s29
	s_cselect_b32 s50, s10, s28
	s_ashr_i32 s9, s8, 31
	s_lshl_b64 s[8:9], s[8:9], 19
	s_add_u32 s8, s4, s8
	s_addc_u32 s9, s5, s9
	s_and_b64 s[34:35], s[26:27], exec
	s_cselect_b32 s51, s9, s31
	s_cselect_b32 s52, s8, s30
	s_add_u32 s28, s28, 0x40080
	s_addc_u32 s29, s29, 0
	s_add_u32 s53, s30, 0x100
	s_addc_u32 s54, s31, 0
	s_mov_b32 s55, -2
	s_waitcnt lgkmcnt(0)
	v_add_u32_e32 v254, 0x18000, v207
	v_add_u32_e32 v255, 0x1c000, v207
	ds_read_b128 v[130:133], v209
	ds_read_b128 v[134:137], v209 offset:1024
	ds_read_b128 v[138:141], v209 offset:2048
	ds_read_b128 v[142:145], v209 offset:3072
	ds_read_b128 v[146:149], v210
	ds_read_b128 v[150:153], v210 offset:1024
	ds_read_b128 v[154:157], v210 offset:2048
	ds_read_b128 v[158:161], v210 offset:3072
	s_add_u32 s30, s28, 0xfffc0080
	s_addc_u32 s31, s29, -1
	s_cmp_eq_u32 s55, 12
	s_cselect_b32 s35, s1, s31
	s_cselect_b32 s34, s50, s30
	s_cselect_b32 s31, s51, s54
	s_cselect_b32 s30, s52, s53
	v_lshl_add_u64 v[216:217], s[28:29], 0, v[190:191]
	s_add_i32 m0, s39, 0xc000
	ds_read_b128 v[162:165], v211
	ds_read_b128 v[166:169], v211 offset:1024
	ds_read_b128 v[170:173], v211 offset:2048
	ds_read_b128 v[174:177], v211 offset:3072
	ds_read_b128 v[194:197], v211 offset:4096
	ds_read_b128 v[198:201], v211 offset:5120
	ds_read_b128 v[202:205], v211 offset:6144
	ds_read_b128 v[212:215], v211 offset:7168
	global_load_lds_dwordx4 v[216:217], off
	v_lshl_add_u64 v[216:217], s[28:29], 0, v[192:193]
	s_add_i32 m0, s39, 0xe000
	s_nop 0
	global_load_lds_dwordx4 v[216:217], off
	s_waitcnt vmcnt(8)
	s_waitcnt lgkmcnt(0)
	s_barrier
	s_setprio 1
	v_mfma_f32_16x16x32_bf16 v[126:129], v[130:133], v[162:165], 0
	v_mfma_f32_16x16x32_bf16 v[122:125], v[138:141], v[162:165], 0
	v_mfma_f32_16x16x32_bf16 v[110:113], v[130:133], v[170:173], 0
	v_mfma_f32_16x16x32_bf16 v[106:109], v[138:141], v[170:173], 0
	v_mfma_f32_16x16x32_bf16 v[94:97], v[130:133], v[194:197], 0
	v_mfma_f32_16x16x32_bf16 v[90:93], v[138:141], v[194:197], 0
	v_mfma_f32_16x16x32_bf16 v[78:81], v[130:133], v[202:205], 0
	v_mfma_f32_16x16x32_bf16 v[74:77], v[138:141], v[202:205], 0
	v_mfma_f32_16x16x32_bf16 v[126:129], v[134:137], v[166:169], v[126:129]
	v_mfma_f32_16x16x32_bf16 v[122:125], v[142:145], v[166:169], v[122:125]
	v_mfma_f32_16x16x32_bf16 v[110:113], v[134:137], v[174:177], v[110:113]
	v_mfma_f32_16x16x32_bf16 v[106:109], v[142:145], v[174:177], v[106:109]
	v_mfma_f32_16x16x32_bf16 v[94:97], v[134:137], v[198:201], v[94:97]
	v_mfma_f32_16x16x32_bf16 v[90:93], v[142:145], v[198:201], v[90:93]
	v_mfma_f32_16x16x32_bf16 v[78:81], v[134:137], v[212:215], v[78:81]
	v_mfma_f32_16x16x32_bf16 v[74:77], v[142:145], v[212:215], v[74:77]
	v_mfma_f32_16x16x32_bf16 v[118:121], v[146:149], v[162:165], 0
	v_mfma_f32_16x16x32_bf16 v[114:117], v[154:157], v[162:165], 0
	v_mfma_f32_16x16x32_bf16 v[102:105], v[146:149], v[170:173], 0
	v_mfma_f32_16x16x32_bf16 v[98:101], v[154:157], v[170:173], 0
	v_mfma_f32_16x16x32_bf16 v[86:89], v[146:149], v[194:197], 0
	v_mfma_f32_16x16x32_bf16 v[82:85], v[154:157], v[194:197], 0
	v_mfma_f32_16x16x32_bf16 v[70:73], v[146:149], v[202:205], 0
	v_mfma_f32_16x16x32_bf16 v[66:69], v[154:157], v[202:205], 0
	v_mfma_f32_16x16x32_bf16 v[118:121], v[150:153], v[166:169], v[118:121]
	v_mfma_f32_16x16x32_bf16 v[114:117], v[158:161], v[166:169], v[114:117]
	v_mfma_f32_16x16x32_bf16 v[102:105], v[150:153], v[174:177], v[102:105]
	v_mfma_f32_16x16x32_bf16 v[98:101], v[158:161], v[174:177], v[98:101]
	v_mfma_f32_16x16x32_bf16 v[86:89], v[150:153], v[198:201], v[86:89]
	v_mfma_f32_16x16x32_bf16 v[82:85], v[158:161], v[198:201], v[82:85]
	v_mfma_f32_16x16x32_bf16 v[70:73], v[150:153], v[212:215], v[70:73]
	v_mfma_f32_16x16x32_bf16 v[66:69], v[158:161], v[212:215], v[66:69]
	s_setprio 0
	s_barrier
	s_add_i32 s56, s48, s38
	v_lshl_add_u64 v[216:217], s[30:31], 0, v[184:185]
	s_mov_b32 m0, s56
	ds_read_b128 v[162:165], v211 offset:16384
	ds_read_b128 v[166:169], v211 offset:17408
	ds_read_b128 v[170:173], v211 offset:18432
	ds_read_b128 v[174:177], v211 offset:19456
	ds_read_b128 v[194:197], v211 offset:20480
	ds_read_b128 v[198:201], v211 offset:21504
	ds_read_b128 v[202:205], v211 offset:22528
	ds_read_b128 v[212:215], v211 offset:23552
	global_load_lds_dwordx4 v[216:217], off
	s_add_i32 m0, s56, 0x2000
	s_add_u32 s56, s30, 0x40000
	v_lshl_add_u64 v[218:219], s[30:31], 0, v[188:189]
	s_addc_u32 s57, s31, 0
	s_add_i32 s58, s49, s38
	global_load_lds_dwordx4 v[218:219], off
	v_lshl_add_u64 v[220:221], s[56:57], 0, v[184:185]
	s_mov_b32 m0, s58
	v_lshl_add_u64 v[222:223], s[34:35], 0, v[186:187]
	global_load_lds_dwordx4 v[220:221], off
	v_lshl_add_u64 v[220:221], s[56:57], 0, v[188:189]
	s_add_i32 m0, s58, 0x2000
	s_nop 0
	global_load_lds_dwordx4 v[220:221], off
	v_lshl_add_u64 v[220:221], s[34:35], 0, v[182:183]
	s_mov_b32 m0, s39
	s_nop 0
	global_load_lds_dwordx4 v[220:221], off
	s_mov_b32 m0, s40
	s_nop 0
	global_load_lds_dwordx4 v[222:223], off
	s_waitcnt vmcnt(8)
	s_waitcnt lgkmcnt(0)
	s_barrier
	s_setprio 1
	v_mfma_f32_16x16x32_bf16 v[62:65], v[130:133], v[162:165], 0
	v_mfma_f32_16x16x32_bf16 v[58:61], v[138:141], v[162:165], 0
	v_mfma_f32_16x16x32_bf16 v[46:49], v[130:133], v[170:173], 0
	v_mfma_f32_16x16x32_bf16 v[42:45], v[138:141], v[170:173], 0
	v_mfma_f32_16x16x32_bf16 v[30:33], v[130:133], v[194:197], 0
	v_mfma_f32_16x16x32_bf16 v[26:29], v[138:141], v[194:197], 0
	v_mfma_f32_16x16x32_bf16 v[14:17], v[130:133], v[202:205], 0
	v_mfma_f32_16x16x32_bf16 v[10:13], v[138:141], v[202:205], 0
	v_mfma_f32_16x16x32_bf16 v[62:65], v[134:137], v[166:169], v[62:65]
	v_mfma_f32_16x16x32_bf16 v[58:61], v[142:145], v[166:169], v[58:61]
	v_mfma_f32_16x16x32_bf16 v[46:49], v[134:137], v[174:177], v[46:49]
	v_mfma_f32_16x16x32_bf16 v[42:45], v[142:145], v[174:177], v[42:45]
	v_mfma_f32_16x16x32_bf16 v[30:33], v[134:137], v[198:201], v[30:33]
	v_mfma_f32_16x16x32_bf16 v[26:29], v[142:145], v[198:201], v[26:29]
	v_mfma_f32_16x16x32_bf16 v[14:17], v[134:137], v[212:215], v[14:17]
	v_mfma_f32_16x16x32_bf16 v[10:13], v[142:145], v[212:215], v[10:13]
	v_mfma_f32_16x16x32_bf16 v[54:57], v[146:149], v[162:165], 0
	v_mfma_f32_16x16x32_bf16 v[50:53], v[154:157], v[162:165], 0
	v_mfma_f32_16x16x32_bf16 v[38:41], v[146:149], v[170:173], 0
	v_mfma_f32_16x16x32_bf16 v[34:37], v[154:157], v[170:173], 0
	v_mfma_f32_16x16x32_bf16 v[22:25], v[146:149], v[194:197], 0
	v_mfma_f32_16x16x32_bf16 v[18:21], v[154:157], v[194:197], 0
	v_mfma_f32_16x16x32_bf16 v[6:9], v[146:149], v[202:205], 0
	v_mfma_f32_16x16x32_bf16 v[2:5], v[154:157], v[202:205], 0
	v_mfma_f32_16x16x32_bf16 v[54:57], v[150:153], v[166:169], v[54:57]
	v_mfma_f32_16x16x32_bf16 v[50:53], v[158:161], v[166:169], v[50:53]
	v_mfma_f32_16x16x32_bf16 v[38:41], v[150:153], v[174:177], v[38:41]
	v_mfma_f32_16x16x32_bf16 v[34:37], v[158:161], v[174:177], v[34:37]
	v_mfma_f32_16x16x32_bf16 v[22:25], v[150:153], v[198:201], v[22:25]
	v_mfma_f32_16x16x32_bf16 v[18:21], v[158:161], v[198:201], v[18:21]
	v_mfma_f32_16x16x32_bf16 v[6:9], v[150:153], v[212:215], v[6:9]
	v_mfma_f32_16x16x32_bf16 v[2:5], v[158:161], v[212:215], v[2:5]
	s_setprio 0
	s_barrier
	s_add_i32 s56, 0, 0x18000
	s_add_i32 s57, 0, 0x1c000
	ds_read_b128 v[130:133], v254
	ds_read_b128 v[134:137], v254 offset:1024
	ds_read_b128 v[138:141], v254 offset:2048
	ds_read_b128 v[142:145], v254 offset:3072
	ds_read_b128 v[146:149], v255
	ds_read_b128 v[150:153], v255 offset:1024
	ds_read_b128 v[154:157], v255 offset:2048
	ds_read_b128 v[158:161], v255 offset:3072
	s_add_u32 s34, s34, 0x40000
	s_addc_u32 s35, s35, 0
	s_mov_b32 m0, s41
	v_lshl_add_u64 v[224:225], s[34:35], 0, v[182:183]
	ds_read_b128 v[162:165], v211 offset:32768
	ds_read_b128 v[166:169], v211 offset:33792
	ds_read_b128 v[170:173], v211 offset:34816
	ds_read_b128 v[174:177], v211 offset:35840
	ds_read_b128 v[194:197], v211 offset:36864
	ds_read_b128 v[198:201], v211 offset:37888
	ds_read_b128 v[202:205], v211 offset:38912
	ds_read_b128 v[212:215], v211 offset:39936
	global_load_lds_dwordx4 v[224:225], off
	v_lshl_add_u64 v[224:225], s[34:35], 0, v[186:187]
	s_mov_b32 m0, s42
	s_nop 0
	global_load_lds_dwordx4 v[224:225], off
	s_waitcnt vmcnt(8)
	s_waitcnt lgkmcnt(0)
	s_barrier
	s_setprio 1
	v_mfma_f32_16x16x32_bf16 v[126:129], v[130:133], v[162:165], v[126:129]
	v_mfma_f32_16x16x32_bf16 v[122:125], v[138:141], v[162:165], v[122:125]
	v_mfma_f32_16x16x32_bf16 v[110:113], v[130:133], v[170:173], v[110:113]
	v_mfma_f32_16x16x32_bf16 v[106:109], v[138:141], v[170:173], v[106:109]
	v_mfma_f32_16x16x32_bf16 v[94:97], v[130:133], v[194:197], v[94:97]
	v_mfma_f32_16x16x32_bf16 v[90:93], v[138:141], v[194:197], v[90:93]
	v_mfma_f32_16x16x32_bf16 v[78:81], v[130:133], v[202:205], v[78:81]
	v_mfma_f32_16x16x32_bf16 v[74:77], v[138:141], v[202:205], v[74:77]
	v_mfma_f32_16x16x32_bf16 v[126:129], v[134:137], v[166:169], v[126:129]
	v_mfma_f32_16x16x32_bf16 v[122:125], v[142:145], v[166:169], v[122:125]
	v_mfma_f32_16x16x32_bf16 v[110:113], v[134:137], v[174:177], v[110:113]
	v_mfma_f32_16x16x32_bf16 v[106:109], v[142:145], v[174:177], v[106:109]
	v_mfma_f32_16x16x32_bf16 v[94:97], v[134:137], v[198:201], v[94:97]
	v_mfma_f32_16x16x32_bf16 v[90:93], v[142:145], v[198:201], v[90:93]
	v_mfma_f32_16x16x32_bf16 v[78:81], v[134:137], v[212:215], v[78:81]
	v_mfma_f32_16x16x32_bf16 v[74:77], v[142:145], v[212:215], v[74:77]
	v_mfma_f32_16x16x32_bf16 v[118:121], v[146:149], v[162:165], v[118:121]
	v_mfma_f32_16x16x32_bf16 v[114:117], v[154:157], v[162:165], v[114:117]
	v_mfma_f32_16x16x32_bf16 v[102:105], v[146:149], v[170:173], v[102:105]
	v_mfma_f32_16x16x32_bf16 v[98:101], v[154:157], v[170:173], v[98:101]
	v_mfma_f32_16x16x32_bf16 v[86:89], v[146:149], v[194:197], v[86:89]
	v_mfma_f32_16x16x32_bf16 v[82:85], v[154:157], v[194:197], v[82:85]
	v_mfma_f32_16x16x32_bf16 v[70:73], v[146:149], v[202:205], v[70:73]
	v_mfma_f32_16x16x32_bf16 v[66:69], v[154:157], v[202:205], v[66:69]
	v_mfma_f32_16x16x32_bf16 v[118:121], v[150:153], v[166:169], v[118:121]
	v_mfma_f32_16x16x32_bf16 v[114:117], v[158:161], v[166:169], v[114:117]
	v_mfma_f32_16x16x32_bf16 v[102:105], v[150:153], v[174:177], v[102:105]
	v_mfma_f32_16x16x32_bf16 v[98:101], v[158:161], v[174:177], v[98:101]
	v_mfma_f32_16x16x32_bf16 v[86:89], v[150:153], v[198:201], v[86:89]
	v_mfma_f32_16x16x32_bf16 v[82:85], v[158:161], v[198:201], v[82:85]
	v_mfma_f32_16x16x32_bf16 v[70:73], v[150:153], v[212:215], v[70:73]
	v_mfma_f32_16x16x32_bf16 v[66:69], v[158:161], v[212:215], v[66:69]
	s_setprio 0
	s_barrier
	s_add_i32 s34, s56, s38
	v_lshl_add_u64 v[216:217], v[216:217], 0, s[22:23]
	s_mov_b32 m0, s34
	ds_read_b128 v[162:165], v211 offset:49152
	ds_read_b128 v[166:169], v211 offset:50176
	ds_read_b128 v[170:173], v211 offset:51200
	ds_read_b128 v[174:177], v211 offset:52224
	ds_read_b128 v[194:197], v211 offset:53248
	ds_read_b128 v[198:201], v211 offset:54272
	ds_read_b128 v[202:205], v211 offset:55296
	ds_read_b128 v[212:215], v211 offset:56320
	global_load_lds_dwordx4 v[216:217], off
	s_add_i32 m0, s34, 0x2000
	s_add_u32 s30, s30, 0x40080
	v_lshl_add_u64 v[216:217], v[218:219], 0, s[22:23]
	s_addc_u32 s31, s31, 0
	s_add_i32 s34, s57, s38
	global_load_lds_dwordx4 v[216:217], off
	v_lshl_add_u64 v[216:217], s[30:31], 0, v[184:185]
	s_mov_b32 m0, s34
	s_nop 0
	global_load_lds_dwordx4 v[216:217], off
	v_lshl_add_u64 v[216:217], s[30:31], 0, v[188:189]
	s_add_i32 m0, s34, 0x2000
	s_nop 0
	global_load_lds_dwordx4 v[216:217], off
	v_lshl_add_u64 v[216:217], v[220:221], 0, s[22:23]
	s_mov_b32 m0, s44
	s_nop 0
	global_load_lds_dwordx4 v[216:217], off
	v_lshl_add_u64 v[216:217], v[222:223], 0, s[22:23]
	s_mov_b32 m0, s45
	s_nop 0
	global_load_lds_dwordx4 v[216:217], off
	s_waitcnt vmcnt(8)
	s_waitcnt lgkmcnt(0)
	s_barrier
	s_setprio 1
	v_mfma_f32_16x16x32_bf16 v[62:65], v[130:133], v[162:165], v[62:65]
	v_mfma_f32_16x16x32_bf16 v[58:61], v[138:141], v[162:165], v[58:61]
	v_mfma_f32_16x16x32_bf16 v[46:49], v[130:133], v[170:173], v[46:49]
	v_mfma_f32_16x16x32_bf16 v[42:45], v[138:141], v[170:173], v[42:45]
	v_mfma_f32_16x16x32_bf16 v[30:33], v[130:133], v[194:197], v[30:33]
	v_mfma_f32_16x16x32_bf16 v[26:29], v[138:141], v[194:197], v[26:29]
	v_mfma_f32_16x16x32_bf16 v[14:17], v[130:133], v[202:205], v[14:17]
	v_mfma_f32_16x16x32_bf16 v[10:13], v[138:141], v[202:205], v[10:13]
	v_mfma_f32_16x16x32_bf16 v[62:65], v[134:137], v[166:169], v[62:65]
	v_mfma_f32_16x16x32_bf16 v[58:61], v[142:145], v[166:169], v[58:61]
	v_mfma_f32_16x16x32_bf16 v[46:49], v[134:137], v[174:177], v[46:49]
	v_mfma_f32_16x16x32_bf16 v[42:45], v[142:145], v[174:177], v[42:45]
	v_mfma_f32_16x16x32_bf16 v[30:33], v[134:137], v[198:201], v[30:33]
	v_mfma_f32_16x16x32_bf16 v[26:29], v[142:145], v[198:201], v[26:29]
	v_mfma_f32_16x16x32_bf16 v[14:17], v[134:137], v[212:215], v[14:17]
	v_mfma_f32_16x16x32_bf16 v[10:13], v[142:145], v[212:215], v[10:13]
	v_mfma_f32_16x16x32_bf16 v[54:57], v[146:149], v[162:165], v[54:57]
	v_mfma_f32_16x16x32_bf16 v[50:53], v[154:157], v[162:165], v[50:53]
	v_mfma_f32_16x16x32_bf16 v[38:41], v[146:149], v[170:173], v[38:41]
	v_mfma_f32_16x16x32_bf16 v[34:37], v[154:157], v[170:173], v[34:37]
	v_mfma_f32_16x16x32_bf16 v[22:25], v[146:149], v[194:197], v[22:25]
	v_mfma_f32_16x16x32_bf16 v[18:21], v[154:157], v[194:197], v[18:21]
	v_mfma_f32_16x16x32_bf16 v[6:9], v[146:149], v[202:205], v[6:9]
	v_mfma_f32_16x16x32_bf16 v[2:5], v[154:157], v[202:205], v[2:5]
	v_mfma_f32_16x16x32_bf16 v[54:57], v[150:153], v[166:169], v[54:57]
	v_mfma_f32_16x16x32_bf16 v[50:53], v[158:161], v[166:169], v[50:53]
	v_mfma_f32_16x16x32_bf16 v[38:41], v[150:153], v[174:177], v[38:41]
	v_mfma_f32_16x16x32_bf16 v[34:37], v[158:161], v[174:177], v[34:37]
	v_mfma_f32_16x16x32_bf16 v[22:25], v[150:153], v[198:201], v[22:25]
	v_mfma_f32_16x16x32_bf16 v[18:21], v[158:161], v[198:201], v[18:21]
	v_mfma_f32_16x16x32_bf16 v[6:9], v[150:153], v[212:215], v[6:9]
	v_mfma_f32_16x16x32_bf16 v[2:5], v[158:161], v[212:215], v[2:5]
	s_setprio 0
	s_barrier
	s_add_i32 s55, s55, 2
	s_add_u32 s28, s28, 0x100
	s_addc_u32 s29, s29, 0
	s_add_u32 s53, s53, 0x100
	s_addc_u32 s54, s54, 0
	s_cmp_gt_u32 s55, 13
	s_cbranch_scc1 .Lpeel_x3
.LBB0_903:
	ds_read_b128 v[130:133], v209
	ds_read_b128 v[134:137], v209 offset:1024
	ds_read_b128 v[138:141], v209 offset:2048
	ds_read_b128 v[142:145], v209 offset:3072
	ds_read_b128 v[146:149], v210
	ds_read_b128 v[150:153], v210 offset:1024
	ds_read_b128 v[154:157], v210 offset:2048
	ds_read_b128 v[158:161], v210 offset:3072
	s_add_u32 s30, s28, 0xfffc0080
	s_addc_u32 s31, s29, -1
	s_cmp_eq_u32 s55, 12
	s_cselect_b32 s35, s1, s31
	s_cselect_b32 s34, s50, s30
	s_cselect_b32 s31, s51, s54
	s_cselect_b32 s30, s52, s53
	v_lshl_add_u64 v[216:217], s[28:29], 0, v[190:191]
	s_add_i32 m0, s39, 0xc000
	ds_read_b128 v[162:165], v211
	ds_read_b128 v[166:169], v211 offset:1024
	ds_read_b128 v[170:173], v211 offset:2048
	ds_read_b128 v[174:177], v211 offset:3072
	ds_read_b128 v[194:197], v211 offset:4096
	ds_read_b128 v[198:201], v211 offset:5120
	ds_read_b128 v[202:205], v211 offset:6144
	ds_read_b128 v[212:215], v211 offset:7168
	global_load_lds_dwordx4 v[216:217], off
	v_lshl_add_u64 v[216:217], s[28:29], 0, v[192:193]
	s_add_i32 m0, s39, 0xe000
	s_nop 0
	global_load_lds_dwordx4 v[216:217], off
	s_waitcnt vmcnt(8)
	s_waitcnt lgkmcnt(0)
	s_barrier
	s_setprio 1
	v_mfma_f32_16x16x32_bf16 v[126:129], v[130:133], v[162:165], v[126:129]
	v_mfma_f32_16x16x32_bf16 v[122:125], v[138:141], v[162:165], v[122:125]
	v_mfma_f32_16x16x32_bf16 v[110:113], v[130:133], v[170:173], v[110:113]
	v_mfma_f32_16x16x32_bf16 v[106:109], v[138:141], v[170:173], v[106:109]
	v_mfma_f32_16x16x32_bf16 v[94:97], v[130:133], v[194:197], v[94:97]
	v_mfma_f32_16x16x32_bf16 v[90:93], v[138:141], v[194:197], v[90:93]
	v_mfma_f32_16x16x32_bf16 v[78:81], v[130:133], v[202:205], v[78:81]
	v_mfma_f32_16x16x32_bf16 v[74:77], v[138:141], v[202:205], v[74:77]
	v_mfma_f32_16x16x32_bf16 v[126:129], v[134:137], v[166:169], v[126:129]
	v_mfma_f32_16x16x32_bf16 v[122:125], v[142:145], v[166:169], v[122:125]
	v_mfma_f32_16x16x32_bf16 v[110:113], v[134:137], v[174:177], v[110:113]
	v_mfma_f32_16x16x32_bf16 v[106:109], v[142:145], v[174:177], v[106:109]
	v_mfma_f32_16x16x32_bf16 v[94:97], v[134:137], v[198:201], v[94:97]
	v_mfma_f32_16x16x32_bf16 v[90:93], v[142:145], v[198:201], v[90:93]
	v_mfma_f32_16x16x32_bf16 v[78:81], v[134:137], v[212:215], v[78:81]
	v_mfma_f32_16x16x32_bf16 v[74:77], v[142:145], v[212:215], v[74:77]
	v_mfma_f32_16x16x32_bf16 v[118:121], v[146:149], v[162:165], v[118:121]
	v_mfma_f32_16x16x32_bf16 v[114:117], v[154:157], v[162:165], v[114:117]
	v_mfma_f32_16x16x32_bf16 v[102:105], v[146:149], v[170:173], v[102:105]
	v_mfma_f32_16x16x32_bf16 v[98:101], v[154:157], v[170:173], v[98:101]
	v_mfma_f32_16x16x32_bf16 v[86:89], v[146:149], v[194:197], v[86:89]
	v_mfma_f32_16x16x32_bf16 v[82:85], v[154:157], v[194:197], v[82:85]
	v_mfma_f32_16x16x32_bf16 v[70:73], v[146:149], v[202:205], v[70:73]
	v_mfma_f32_16x16x32_bf16 v[66:69], v[154:157], v[202:205], v[66:69]
	v_mfma_f32_16x16x32_bf16 v[118:121], v[150:153], v[166:169], v[118:121]
	v_mfma_f32_16x16x32_bf16 v[114:117], v[158:161], v[166:169], v[114:117]
	v_mfma_f32_16x16x32_bf16 v[102:105], v[150:153], v[174:177], v[102:105]
	v_mfma_f32_16x16x32_bf16 v[98:101], v[158:161], v[174:177], v[98:101]
	v_mfma_f32_16x16x32_bf16 v[86:89], v[150:153], v[198:201], v[86:89]
	v_mfma_f32_16x16x32_bf16 v[82:85], v[158:161], v[198:201], v[82:85]
	v_mfma_f32_16x16x32_bf16 v[70:73], v[150:153], v[212:215], v[70:73]
	v_mfma_f32_16x16x32_bf16 v[66:69], v[158:161], v[212:215], v[66:69]
	s_setprio 0
	s_barrier
	s_add_i32 s56, s48, s38
	v_lshl_add_u64 v[216:217], s[30:31], 0, v[184:185]
	s_mov_b32 m0, s56
	ds_read_b128 v[162:165], v211 offset:16384
	ds_read_b128 v[166:169], v211 offset:17408
	ds_read_b128 v[170:173], v211 offset:18432
	ds_read_b128 v[174:177], v211 offset:19456
	ds_read_b128 v[194:197], v211 offset:20480
	ds_read_b128 v[198:201], v211 offset:21504
	ds_read_b128 v[202:205], v211 offset:22528
	ds_read_b128 v[212:215], v211 offset:23552
	global_load_lds_dwordx4 v[216:217], off
	s_add_i32 m0, s56, 0x2000
	s_add_u32 s56, s30, 0x40000
	v_lshl_add_u64 v[218:219], s[30:31], 0, v[188:189]
	s_addc_u32 s57, s31, 0
	s_add_i32 s58, s49, s38
	global_load_lds_dwordx4 v[218:219], off
	v_lshl_add_u64 v[220:221], s[56:57], 0, v[184:185]
	s_mov_b32 m0, s58
	v_lshl_add_u64 v[222:223], s[34:35], 0, v[186:187]
	global_load_lds_dwordx4 v[220:221], off
	v_lshl_add_u64 v[220:221], s[56:57], 0, v[188:189]
	s_add_i32 m0, s58, 0x2000
	s_nop 0
	global_load_lds_dwordx4 v[220:221], off
	v_lshl_add_u64 v[220:221], s[34:35], 0, v[182:183]
	s_mov_b32 m0, s39
	s_nop 0
	global_load_lds_dwordx4 v[220:221], off
	s_mov_b32 m0, s40
	s_nop 0
	global_load_lds_dwordx4 v[222:223], off
	s_waitcnt vmcnt(8)
	s_waitcnt lgkmcnt(0)
	s_barrier
	s_setprio 1
	v_mfma_f32_16x16x32_bf16 v[62:65], v[130:133], v[162:165], v[62:65]
	v_mfma_f32_16x16x32_bf16 v[58:61], v[138:141], v[162:165], v[58:61]
	v_mfma_f32_16x16x32_bf16 v[46:49], v[130:133], v[170:173], v[46:49]
	v_mfma_f32_16x16x32_bf16 v[42:45], v[138:141], v[170:173], v[42:45]
	v_mfma_f32_16x16x32_bf16 v[30:33], v[130:133], v[194:197], v[30:33]
	v_mfma_f32_16x16x32_bf16 v[26:29], v[138:141], v[194:197], v[26:29]
	v_mfma_f32_16x16x32_bf16 v[14:17], v[130:133], v[202:205], v[14:17]
	v_mfma_f32_16x16x32_bf16 v[10:13], v[138:141], v[202:205], v[10:13]
	v_mfma_f32_16x16x32_bf16 v[62:65], v[134:137], v[166:169], v[62:65]
	v_mfma_f32_16x16x32_bf16 v[58:61], v[142:145], v[166:169], v[58:61]
	v_mfma_f32_16x16x32_bf16 v[46:49], v[134:137], v[174:177], v[46:49]
	v_mfma_f32_16x16x32_bf16 v[42:45], v[142:145], v[174:177], v[42:45]
	v_mfma_f32_16x16x32_bf16 v[30:33], v[134:137], v[198:201], v[30:33]
	v_mfma_f32_16x16x32_bf16 v[26:29], v[142:145], v[198:201], v[26:29]
	v_mfma_f32_16x16x32_bf16 v[14:17], v[134:137], v[212:215], v[14:17]
	v_mfma_f32_16x16x32_bf16 v[10:13], v[142:145], v[212:215], v[10:13]
	v_mfma_f32_16x16x32_bf16 v[54:57], v[146:149], v[162:165], v[54:57]
	v_mfma_f32_16x16x32_bf16 v[50:53], v[154:157], v[162:165], v[50:53]
	v_mfma_f32_16x16x32_bf16 v[38:41], v[146:149], v[170:173], v[38:41]
	v_mfma_f32_16x16x32_bf16 v[34:37], v[154:157], v[170:173], v[34:37]
	v_mfma_f32_16x16x32_bf16 v[22:25], v[146:149], v[194:197], v[22:25]
	v_mfma_f32_16x16x32_bf16 v[18:21], v[154:157], v[194:197], v[18:21]
	v_mfma_f32_16x16x32_bf16 v[6:9], v[146:149], v[202:205], v[6:9]
	v_mfma_f32_16x16x32_bf16 v[2:5], v[154:157], v[202:205], v[2:5]
	v_mfma_f32_16x16x32_bf16 v[54:57], v[150:153], v[166:169], v[54:57]
	v_mfma_f32_16x16x32_bf16 v[50:53], v[158:161], v[166:169], v[50:53]
	v_mfma_f32_16x16x32_bf16 v[38:41], v[150:153], v[174:177], v[38:41]
	v_mfma_f32_16x16x32_bf16 v[34:37], v[158:161], v[174:177], v[34:37]
	v_mfma_f32_16x16x32_bf16 v[22:25], v[150:153], v[198:201], v[22:25]
	v_mfma_f32_16x16x32_bf16 v[18:21], v[158:161], v[198:201], v[18:21]
	v_mfma_f32_16x16x32_bf16 v[6:9], v[150:153], v[212:215], v[6:9]
	v_mfma_f32_16x16x32_bf16 v[2:5], v[158:161], v[212:215], v[2:5]
	s_setprio 0
	s_barrier
	s_add_i32 s56, 0, 0x18000
	s_add_i32 s57, 0, 0x1c000
	ds_read_b128 v[130:133], v254
	ds_read_b128 v[134:137], v254 offset:1024
	ds_read_b128 v[138:141], v254 offset:2048
	ds_read_b128 v[142:145], v254 offset:3072
	ds_read_b128 v[146:149], v255
	ds_read_b128 v[150:153], v255 offset:1024
	ds_read_b128 v[154:157], v255 offset:2048
	ds_read_b128 v[158:161], v255 offset:3072
	s_add_u32 s34, s34, 0x40000
	s_addc_u32 s35, s35, 0
	s_mov_b32 m0, s41
	v_lshl_add_u64 v[224:225], s[34:35], 0, v[182:183]
	ds_read_b128 v[162:165], v211 offset:32768
	ds_read_b128 v[166:169], v211 offset:33792
	ds_read_b128 v[170:173], v211 offset:34816
	ds_read_b128 v[174:177], v211 offset:35840
	ds_read_b128 v[194:197], v211 offset:36864
	ds_read_b128 v[198:201], v211 offset:37888
	ds_read_b128 v[202:205], v211 offset:38912
	ds_read_b128 v[212:215], v211 offset:39936
	global_load_lds_dwordx4 v[224:225], off
	v_lshl_add_u64 v[224:225], s[34:35], 0, v[186:187]
	s_mov_b32 m0, s42
	s_nop 0
	global_load_lds_dwordx4 v[224:225], off
	s_waitcnt vmcnt(8)
	s_waitcnt lgkmcnt(0)
	s_barrier
	s_setprio 1
	v_mfma_f32_16x16x32_bf16 v[126:129], v[130:133], v[162:165], v[126:129]
	v_mfma_f32_16x16x32_bf16 v[122:125], v[138:141], v[162:165], v[122:125]
	v_mfma_f32_16x16x32_bf16 v[110:113], v[130:133], v[170:173], v[110:113]
	v_mfma_f32_16x16x32_bf16 v[106:109], v[138:141], v[170:173], v[106:109]
	v_mfma_f32_16x16x32_bf16 v[94:97], v[130:133], v[194:197], v[94:97]
	v_mfma_f32_16x16x32_bf16 v[90:93], v[138:141], v[194:197], v[90:93]
	v_mfma_f32_16x16x32_bf16 v[78:81], v[130:133], v[202:205], v[78:81]
	v_mfma_f32_16x16x32_bf16 v[74:77], v[138:141], v[202:205], v[74:77]
	v_mfma_f32_16x16x32_bf16 v[126:129], v[134:137], v[166:169], v[126:129]
	v_mfma_f32_16x16x32_bf16 v[122:125], v[142:145], v[166:169], v[122:125]
	v_mfma_f32_16x16x32_bf16 v[110:113], v[134:137], v[174:177], v[110:113]
	v_mfma_f32_16x16x32_bf16 v[106:109], v[142:145], v[174:177], v[106:109]
	v_mfma_f32_16x16x32_bf16 v[94:97], v[134:137], v[198:201], v[94:97]
	v_mfma_f32_16x16x32_bf16 v[90:93], v[142:145], v[198:201], v[90:93]
	v_mfma_f32_16x16x32_bf16 v[78:81], v[134:137], v[212:215], v[78:81]
	v_mfma_f32_16x16x32_bf16 v[74:77], v[142:145], v[212:215], v[74:77]
	v_mfma_f32_16x16x32_bf16 v[118:121], v[146:149], v[162:165], v[118:121]
	v_mfma_f32_16x16x32_bf16 v[114:117], v[154:157], v[162:165], v[114:117]
	v_mfma_f32_16x16x32_bf16 v[102:105], v[146:149], v[170:173], v[102:105]
	v_mfma_f32_16x16x32_bf16 v[98:101], v[154:157], v[170:173], v[98:101]
	v_mfma_f32_16x16x32_bf16 v[86:89], v[146:149], v[194:197], v[86:89]
	v_mfma_f32_16x16x32_bf16 v[82:85], v[154:157], v[194:197], v[82:85]
	v_mfma_f32_16x16x32_bf16 v[70:73], v[146:149], v[202:205], v[70:73]
	v_mfma_f32_16x16x32_bf16 v[66:69], v[154:157], v[202:205], v[66:69]
	v_mfma_f32_16x16x32_bf16 v[118:121], v[150:153], v[166:169], v[118:121]
	v_mfma_f32_16x16x32_bf16 v[114:117], v[158:161], v[166:169], v[114:117]
	v_mfma_f32_16x16x32_bf16 v[102:105], v[150:153], v[174:177], v[102:105]
	v_mfma_f32_16x16x32_bf16 v[98:101], v[158:161], v[174:177], v[98:101]
	v_mfma_f32_16x16x32_bf16 v[86:89], v[150:153], v[198:201], v[86:89]
	v_mfma_f32_16x16x32_bf16 v[82:85], v[158:161], v[198:201], v[82:85]
	v_mfma_f32_16x16x32_bf16 v[70:73], v[150:153], v[212:215], v[70:73]
	v_mfma_f32_16x16x32_bf16 v[66:69], v[158:161], v[212:215], v[66:69]
	s_setprio 0
	s_barrier
	s_add_i32 s34, s56, s38
	v_lshl_add_u64 v[216:217], v[216:217], 0, s[22:23]
	s_mov_b32 m0, s34
	ds_read_b128 v[162:165], v211 offset:49152
	ds_read_b128 v[166:169], v211 offset:50176
	ds_read_b128 v[170:173], v211 offset:51200
	ds_read_b128 v[174:177], v211 offset:52224
	ds_read_b128 v[194:197], v211 offset:53248
	ds_read_b128 v[198:201], v211 offset:54272
	ds_read_b128 v[202:205], v211 offset:55296
	ds_read_b128 v[212:215], v211 offset:56320
	global_load_lds_dwordx4 v[216:217], off
	s_add_i32 m0, s34, 0x2000
	s_add_u32 s30, s30, 0x40080
	v_lshl_add_u64 v[216:217], v[218:219], 0, s[22:23]
	s_addc_u32 s31, s31, 0
	s_add_i32 s34, s57, s38
	global_load_lds_dwordx4 v[216:217], off
	v_lshl_add_u64 v[216:217], s[30:31], 0, v[184:185]
	s_mov_b32 m0, s34
	s_nop 0
	global_load_lds_dwordx4 v[216:217], off
	v_lshl_add_u64 v[216:217], s[30:31], 0, v[188:189]
	s_add_i32 m0, s34, 0x2000
	s_nop 0
	global_load_lds_dwordx4 v[216:217], off
	v_lshl_add_u64 v[216:217], v[220:221], 0, s[22:23]
	s_mov_b32 m0, s44
	s_nop 0
	global_load_lds_dwordx4 v[216:217], off
	v_lshl_add_u64 v[216:217], v[222:223], 0, s[22:23]
	s_mov_b32 m0, s45
	s_nop 0
	global_load_lds_dwordx4 v[216:217], off
	s_waitcnt vmcnt(8)
	s_waitcnt lgkmcnt(0)
	s_barrier
	s_setprio 1
	v_mfma_f32_16x16x32_bf16 v[62:65], v[130:133], v[162:165], v[62:65]
	v_mfma_f32_16x16x32_bf16 v[58:61], v[138:141], v[162:165], v[58:61]
	v_mfma_f32_16x16x32_bf16 v[46:49], v[130:133], v[170:173], v[46:49]
	v_mfma_f32_16x16x32_bf16 v[42:45], v[138:141], v[170:173], v[42:45]
	v_mfma_f32_16x16x32_bf16 v[30:33], v[130:133], v[194:197], v[30:33]
	v_mfma_f32_16x16x32_bf16 v[26:29], v[138:141], v[194:197], v[26:29]
	v_mfma_f32_16x16x32_bf16 v[14:17], v[130:133], v[202:205], v[14:17]
	v_mfma_f32_16x16x32_bf16 v[10:13], v[138:141], v[202:205], v[10:13]
	v_mfma_f32_16x16x32_bf16 v[62:65], v[134:137], v[166:169], v[62:65]
	v_mfma_f32_16x16x32_bf16 v[58:61], v[142:145], v[166:169], v[58:61]
	v_mfma_f32_16x16x32_bf16 v[46:49], v[134:137], v[174:177], v[46:49]
	v_mfma_f32_16x16x32_bf16 v[42:45], v[142:145], v[174:177], v[42:45]
	v_mfma_f32_16x16x32_bf16 v[30:33], v[134:137], v[198:201], v[30:33]
	v_mfma_f32_16x16x32_bf16 v[26:29], v[142:145], v[198:201], v[26:29]
	v_mfma_f32_16x16x32_bf16 v[14:17], v[134:137], v[212:215], v[14:17]
	v_mfma_f32_16x16x32_bf16 v[10:13], v[142:145], v[212:215], v[10:13]
	v_mfma_f32_16x16x32_bf16 v[54:57], v[146:149], v[162:165], v[54:57]
	v_mfma_f32_16x16x32_bf16 v[50:53], v[154:157], v[162:165], v[50:53]
	v_mfma_f32_16x16x32_bf16 v[38:41], v[146:149], v[170:173], v[38:41]
	v_mfma_f32_16x16x32_bf16 v[34:37], v[154:157], v[170:173], v[34:37]
	v_mfma_f32_16x16x32_bf16 v[22:25], v[146:149], v[194:197], v[22:25]
	v_mfma_f32_16x16x32_bf16 v[18:21], v[154:157], v[194:197], v[18:21]
	v_mfma_f32_16x16x32_bf16 v[6:9], v[146:149], v[202:205], v[6:9]
	v_mfma_f32_16x16x32_bf16 v[2:5], v[154:157], v[202:205], v[2:5]
	v_mfma_f32_16x16x32_bf16 v[54:57], v[150:153], v[166:169], v[54:57]
	v_mfma_f32_16x16x32_bf16 v[50:53], v[158:161], v[166:169], v[50:53]
	v_mfma_f32_16x16x32_bf16 v[38:41], v[150:153], v[174:177], v[38:41]
	v_mfma_f32_16x16x32_bf16 v[34:37], v[158:161], v[174:177], v[34:37]
	v_mfma_f32_16x16x32_bf16 v[22:25], v[150:153], v[198:201], v[22:25]
	v_mfma_f32_16x16x32_bf16 v[18:21], v[158:161], v[198:201], v[18:21]
	v_mfma_f32_16x16x32_bf16 v[6:9], v[150:153], v[212:215], v[6:9]
	v_mfma_f32_16x16x32_bf16 v[2:5], v[158:161], v[212:215], v[2:5]
	s_setprio 0
	s_barrier
	s_add_i32 s55, s55, 2
	s_add_u32 s28, s28, 0x100
	s_addc_u32 s29, s29, 0
	s_add_u32 s53, s53, 0x100
	s_addc_u32 s54, s54, 0
	s_cmp_gt_u32 s55, 13
	s_cbranch_scc0 .LBB0_903

.LBB0_990:
	s_ashr_i32 s37, s36, 31
	s_lshl_b64 s[2:3], s[36:37], 19
	s_add_u32 s40, s48, s2
	s_addc_u32 s41, s49, s3
	s_and_b64 s[2:3], s[44:45], exec
	s_cselect_b32 s1, s41, s9
	s_cselect_b32 s2, s40, s8
	s_ashr_i32 s39, s38, 31
	s_lshl_b64 s[4:5], s[38:39], 19
	s_add_u32 s42, s50, s4
	s_addc_u32 s43, s51, s5
	s_and_b64 s[4:5], s[44:45], exec
	s_cselect_b32 s3, s43, s11
	s_cselect_b32 s4, s42, s10
	s_add_u32 s8, s8, 0x40080
	s_addc_u32 s9, s9, 0
	s_add_u32 s5, s10, 0x100
	s_addc_u32 s7, s11, 0
	s_mov_b32 s22, -2
	v_add_u32_e32 v254, 0x18000, v213
	v_add_u32_e32 v255, 0x1c000, v213
	ds_read_b128 v[66:69], v219
	ds_read_b128 v[70:73], v219 offset:1024
	ds_read_b128 v[86:89], v219 offset:2048
	ds_read_b128 v[106:109], v219 offset:3072
	ds_read_b128 v[146:149], v220
	ds_read_b128 v[150:153], v220 offset:1024
	ds_read_b128 v[154:157], v220 offset:2048
	ds_read_b128 v[158:161], v220 offset:3072
	s_add_u32 s10, s8, 0xfffc0080
	s_addc_u32 s11, s9, -1
	s_cmp_eq_u32 s22, 12
	s_cselect_b32 s45, s1, s11
	s_cselect_b32 s44, s2, s10
	s_cselect_b32 s11, s3, s7
	s_cselect_b32 s10, s4, s5
	s_add_i32 m0, s54, 0xc000
	ds_read_b128 v[162:165], v221
	ds_read_b128 v[166:169], v221 offset:1024
	ds_read_b128 v[170:173], v221 offset:2048
	ds_read_b128 v[174:177], v221 offset:3072
	ds_read_b128 v[196:199], v221 offset:4096
	ds_read_b128 v[200:203], v221 offset:5120
	ds_read_b128 v[204:207], v221 offset:6144
	ds_read_b128 v[208:211], v221 offset:7168
	global_load_lds_dwordx4 v192, s[8:9]
	s_add_i32 m0, s54, 0xe000
	s_nop 0
	global_load_lds_dwordx4 v194, s[8:9]
	s_waitcnt vmcnt(8)
	s_waitcnt lgkmcnt(0)
	s_barrier
	s_setprio 1
	v_mfma_f32_16x16x32_bf16 v[142:145], v[66:69], v[162:165], 0
	v_mfma_f32_16x16x32_bf16 v[134:137], v[86:89], v[162:165], 0
	v_mfma_f32_16x16x32_bf16 v[126:129], v[66:69], v[170:173], 0
	v_mfma_f32_16x16x32_bf16 v[122:125], v[86:89], v[170:173], 0
	v_mfma_f32_16x16x32_bf16 v[110:113], v[66:69], v[196:199], 0
	v_mfma_f32_16x16x32_bf16 v[102:105], v[86:89], v[196:199], 0
	v_mfma_f32_16x16x32_bf16 v[90:93], v[66:69], v[204:207], 0
	v_mfma_f32_16x16x32_bf16 v[82:85], v[86:89], v[204:207], 0
	v_mfma_f32_16x16x32_bf16 v[142:145], v[70:73], v[166:169], v[142:145]
	v_mfma_f32_16x16x32_bf16 v[134:137], v[106:109], v[166:169], v[134:137]
	v_mfma_f32_16x16x32_bf16 v[126:129], v[70:73], v[174:177], v[126:129]
	v_mfma_f32_16x16x32_bf16 v[122:125], v[106:109], v[174:177], v[122:125]
	v_mfma_f32_16x16x32_bf16 v[110:113], v[70:73], v[200:203], v[110:113]
	v_mfma_f32_16x16x32_bf16 v[102:105], v[106:109], v[200:203], v[102:105]
	v_mfma_f32_16x16x32_bf16 v[90:93], v[70:73], v[208:211], v[90:93]
	v_mfma_f32_16x16x32_bf16 v[82:85], v[106:109], v[208:211], v[82:85]
	v_mfma_f32_16x16x32_bf16 v[138:141], v[146:149], v[162:165], 0
	v_mfma_f32_16x16x32_bf16 v[130:133], v[154:157], v[162:165], 0
	v_mfma_f32_16x16x32_bf16 v[118:121], v[146:149], v[170:173], 0
	v_mfma_f32_16x16x32_bf16 v[114:117], v[154:157], v[170:173], 0
	v_mfma_f32_16x16x32_bf16 v[98:101], v[146:149], v[196:199], 0
	v_mfma_f32_16x16x32_bf16 v[94:97], v[154:157], v[196:199], 0
	v_mfma_f32_16x16x32_bf16 v[78:81], v[146:149], v[204:207], 0
	v_mfma_f32_16x16x32_bf16 v[74:77], v[154:157], v[204:207], 0
	v_mfma_f32_16x16x32_bf16 v[138:141], v[150:153], v[166:169], v[138:141]
	v_mfma_f32_16x16x32_bf16 v[130:133], v[158:161], v[166:169], v[130:133]
	v_mfma_f32_16x16x32_bf16 v[118:121], v[150:153], v[174:177], v[118:121]
	v_mfma_f32_16x16x32_bf16 v[114:117], v[158:161], v[174:177], v[114:117]
	v_mfma_f32_16x16x32_bf16 v[98:101], v[150:153], v[200:203], v[98:101]
	v_mfma_f32_16x16x32_bf16 v[94:97], v[158:161], v[200:203], v[94:97]
	v_mfma_f32_16x16x32_bf16 v[78:81], v[150:153], v[208:211], v[78:81]
	v_mfma_f32_16x16x32_bf16 v[74:77], v[158:161], v[208:211], v[74:77]
	s_setprio 0
	s_barrier
	s_add_i32 s37, s62, s53
	s_mov_b32 m0, s37
	ds_read_b128 v[162:165], v221 offset:16384
	ds_read_b128 v[166:169], v221 offset:17408
	ds_read_b128 v[170:173], v221 offset:18432
	ds_read_b128 v[174:177], v221 offset:19456
	ds_read_b128 v[196:199], v221 offset:20480
	ds_read_b128 v[200:203], v221 offset:21504
	ds_read_b128 v[204:207], v221 offset:22528
	ds_read_b128 v[208:211], v221 offset:23552
	global_load_lds_dwordx4 v184, s[10:11]
	s_add_i32 m0, s37, 0x2000
	s_add_u32 s46, s10, 0x40000
	s_addc_u32 s47, s11, 0
	s_add_i32 s37, s63, s53
	global_load_lds_dwordx4 v188, s[10:11]
	s_mov_b32 m0, s37
	s_nop 0
	global_load_lds_dwordx4 v184, s[46:47]
	s_add_i32 m0, s37, 0x2000
	s_nop 0
	global_load_lds_dwordx4 v188, s[46:47]
	s_mov_b32 m0, s54
	s_nop 0
	global_load_lds_dwordx4 v182, s[44:45]
	s_mov_b32 m0, s55
	s_nop 0
	global_load_lds_dwordx4 v186, s[44:45]
	s_waitcnt vmcnt(8)
	s_waitcnt lgkmcnt(0)
	s_barrier
	s_setprio 1
	v_mfma_f32_16x16x32_bf16 v[62:65], v[66:69], v[162:165], 0
	v_mfma_f32_16x16x32_bf16 v[54:57], v[86:89], v[162:165], 0
	v_mfma_f32_16x16x32_bf16 v[46:49], v[66:69], v[170:173], 0
	v_mfma_f32_16x16x32_bf16 v[42:45], v[86:89], v[170:173], 0
	v_mfma_f32_16x16x32_bf16 v[30:33], v[66:69], v[196:199], 0
	v_mfma_f32_16x16x32_bf16 v[26:29], v[86:89], v[196:199], 0
	v_mfma_f32_16x16x32_bf16 v[14:17], v[66:69], v[204:207], 0
	v_mfma_f32_16x16x32_bf16 v[10:13], v[86:89], v[204:207], 0
	v_mfma_f32_16x16x32_bf16 v[62:65], v[70:73], v[166:169], v[62:65]
	v_mfma_f32_16x16x32_bf16 v[54:57], v[106:109], v[166:169], v[54:57]
	v_mfma_f32_16x16x32_bf16 v[46:49], v[70:73], v[174:177], v[46:49]
	v_mfma_f32_16x16x32_bf16 v[42:45], v[106:109], v[174:177], v[42:45]
	v_mfma_f32_16x16x32_bf16 v[30:33], v[70:73], v[200:203], v[30:33]
	v_mfma_f32_16x16x32_bf16 v[26:29], v[106:109], v[200:203], v[26:29]
	v_mfma_f32_16x16x32_bf16 v[14:17], v[70:73], v[208:211], v[14:17]
	v_mfma_f32_16x16x32_bf16 v[10:13], v[106:109], v[208:211], v[10:13]
	v_mfma_f32_16x16x32_bf16 v[58:61], v[146:149], v[162:165], 0
	v_mfma_f32_16x16x32_bf16 v[50:53], v[154:157], v[162:165], 0
	v_mfma_f32_16x16x32_bf16 v[38:41], v[146:149], v[170:173], 0
	v_mfma_f32_16x16x32_bf16 v[34:37], v[154:157], v[170:173], 0
	v_mfma_f32_16x16x32_bf16 v[22:25], v[146:149], v[196:199], 0
	v_mfma_f32_16x16x32_bf16 v[18:21], v[154:157], v[196:199], 0
	v_mfma_f32_16x16x32_bf16 v[6:9], v[146:149], v[204:207], 0
	v_mfma_f32_16x16x32_bf16 v[2:5], v[154:157], v[204:207], 0
	v_mfma_f32_16x16x32_bf16 v[58:61], v[150:153], v[166:169], v[58:61]
	v_mfma_f32_16x16x32_bf16 v[50:53], v[158:161], v[166:169], v[50:53]
	v_mfma_f32_16x16x32_bf16 v[38:41], v[150:153], v[174:177], v[38:41]
	v_mfma_f32_16x16x32_bf16 v[34:37], v[158:161], v[174:177], v[34:37]
	v_mfma_f32_16x16x32_bf16 v[22:25], v[150:153], v[200:203], v[22:25]
	v_mfma_f32_16x16x32_bf16 v[18:21], v[158:161], v[200:203], v[18:21]
	v_mfma_f32_16x16x32_bf16 v[6:9], v[150:153], v[208:211], v[6:9]
	v_mfma_f32_16x16x32_bf16 v[2:5], v[158:161], v[208:211], v[2:5]
	s_setprio 0
	s_barrier
	s_add_i32 s37, 0, 0x18000
	s_add_i32 s39, 0, 0x1c000
	ds_read_b128 v[66:69], v254
	ds_read_b128 v[70:73], v254 offset:1024
	ds_read_b128 v[86:89], v254 offset:2048
	ds_read_b128 v[106:109], v254 offset:3072
	ds_read_b128 v[146:149], v255
	ds_read_b128 v[150:153], v255 offset:1024
	ds_read_b128 v[154:157], v255 offset:2048
	ds_read_b128 v[158:161], v255 offset:3072
	s_add_u32 s44, s44, 0x40000
	s_addc_u32 s45, s45, 0
	s_mov_b32 m0, s56
	ds_read_b128 v[162:165], v221 offset:32768
	ds_read_b128 v[166:169], v221 offset:33792
	ds_read_b128 v[170:173], v221 offset:34816
	ds_read_b128 v[174:177], v221 offset:35840
	ds_read_b128 v[196:199], v221 offset:36864
	ds_read_b128 v[200:203], v221 offset:37888
	ds_read_b128 v[204:207], v221 offset:38912
	ds_read_b128 v[208:211], v221 offset:39936
	global_load_lds_dwordx4 v182, s[44:45]
	s_mov_b32 m0, s57
	s_nop 0
	global_load_lds_dwordx4 v186, s[44:45]
	s_waitcnt vmcnt(8)
	s_waitcnt lgkmcnt(0)
	s_barrier
	s_setprio 1
	v_mfma_f32_16x16x32_bf16 v[142:145], v[66:69], v[162:165], v[142:145]
	v_mfma_f32_16x16x32_bf16 v[134:137], v[86:89], v[162:165], v[134:137]
	v_mfma_f32_16x16x32_bf16 v[126:129], v[66:69], v[170:173], v[126:129]
	v_mfma_f32_16x16x32_bf16 v[122:125], v[86:89], v[170:173], v[122:125]
	v_mfma_f32_16x16x32_bf16 v[110:113], v[66:69], v[196:199], v[110:113]
	v_mfma_f32_16x16x32_bf16 v[102:105], v[86:89], v[196:199], v[102:105]
	v_mfma_f32_16x16x32_bf16 v[90:93], v[66:69], v[204:207], v[90:93]
	v_mfma_f32_16x16x32_bf16 v[82:85], v[86:89], v[204:207], v[82:85]
	v_mfma_f32_16x16x32_bf16 v[142:145], v[70:73], v[166:169], v[142:145]
	v_mfma_f32_16x16x32_bf16 v[134:137], v[106:109], v[166:169], v[134:137]
	v_mfma_f32_16x16x32_bf16 v[126:129], v[70:73], v[174:177], v[126:129]
	v_mfma_f32_16x16x32_bf16 v[122:125], v[106:109], v[174:177], v[122:125]
	v_mfma_f32_16x16x32_bf16 v[110:113], v[70:73], v[200:203], v[110:113]
	v_mfma_f32_16x16x32_bf16 v[102:105], v[106:109], v[200:203], v[102:105]
	v_mfma_f32_16x16x32_bf16 v[90:93], v[70:73], v[208:211], v[90:93]
	v_mfma_f32_16x16x32_bf16 v[82:85], v[106:109], v[208:211], v[82:85]
	v_mfma_f32_16x16x32_bf16 v[138:141], v[146:149], v[162:165], v[138:141]
	v_mfma_f32_16x16x32_bf16 v[130:133], v[154:157], v[162:165], v[130:133]
	v_mfma_f32_16x16x32_bf16 v[118:121], v[146:149], v[170:173], v[118:121]
	v_mfma_f32_16x16x32_bf16 v[114:117], v[154:157], v[170:173], v[114:117]
	v_mfma_f32_16x16x32_bf16 v[98:101], v[146:149], v[196:199], v[98:101]
	v_mfma_f32_16x16x32_bf16 v[94:97], v[154:157], v[196:199], v[94:97]
	v_mfma_f32_16x16x32_bf16 v[78:81], v[146:149], v[204:207], v[78:81]
	v_mfma_f32_16x16x32_bf16 v[74:77], v[154:157], v[204:207], v[74:77]
	v_mfma_f32_16x16x32_bf16 v[138:141], v[150:153], v[166:169], v[138:141]
	v_mfma_f32_16x16x32_bf16 v[130:133], v[158:161], v[166:169], v[130:133]
	v_mfma_f32_16x16x32_bf16 v[118:121], v[150:153], v[174:177], v[118:121]
	v_mfma_f32_16x16x32_bf16 v[114:117], v[158:161], v[174:177], v[114:117]
	v_mfma_f32_16x16x32_bf16 v[98:101], v[150:153], v[200:203], v[98:101]
	v_mfma_f32_16x16x32_bf16 v[94:97], v[158:161], v[200:203], v[94:97]
	v_mfma_f32_16x16x32_bf16 v[78:81], v[150:153], v[208:211], v[78:81]
	v_mfma_f32_16x16x32_bf16 v[74:77], v[158:161], v[208:211], v[74:77]
	s_setprio 0
	s_barrier
	s_add_i32 s37, s37, s53
	s_mov_b32 m0, s37
	ds_read_b128 v[162:165], v221 offset:49152
	ds_read_b128 v[166:169], v221 offset:50176
	ds_read_b128 v[170:173], v221 offset:51200
	ds_read_b128 v[174:177], v221 offset:52224
	ds_read_b128 v[196:199], v221 offset:53248
	ds_read_b128 v[200:203], v221 offset:54272
	ds_read_b128 v[204:207], v221 offset:55296
	ds_read_b128 v[208:211], v221 offset:56320
	s_add_u32 s98, s10, 0x80
	s_addc_u32 s99, s11, 0
	global_load_lds_dwordx4 v184, s[98:99]
	s_add_i32 m0, s37, 0x2000
	s_add_u32 s10, s10, 0x40080
	s_addc_u32 s11, s11, 0
	s_add_i32 s37, s39, s53
	global_load_lds_dwordx4 v188, s[98:99]
	s_mov_b32 m0, s37
	s_nop 0
	global_load_lds_dwordx4 v184, s[10:11]
	s_add_i32 m0, s37, 0x2000
	s_nop 0
	global_load_lds_dwordx4 v188, s[10:11]
	s_add_u32 s98, s44, 0xfffc0080
	s_addc_u32 s99, s45, -1
	s_mov_b32 m0, s60
	s_nop 0
	global_load_lds_dwordx4 v182, s[98:99]
	s_mov_b32 m0, s61
	s_nop 0
	global_load_lds_dwordx4 v186, s[98:99]
	s_waitcnt vmcnt(8)
	s_waitcnt lgkmcnt(0)
	s_barrier
	s_setprio 1
	v_mfma_f32_16x16x32_bf16 v[62:65], v[66:69], v[162:165], v[62:65]
	v_mfma_f32_16x16x32_bf16 v[54:57], v[86:89], v[162:165], v[54:57]
	v_mfma_f32_16x16x32_bf16 v[46:49], v[66:69], v[170:173], v[46:49]
	v_mfma_f32_16x16x32_bf16 v[42:45], v[86:89], v[170:173], v[42:45]
	v_mfma_f32_16x16x32_bf16 v[30:33], v[66:69], v[196:199], v[30:33]
	v_mfma_f32_16x16x32_bf16 v[26:29], v[86:89], v[196:199], v[26:29]
	v_mfma_f32_16x16x32_bf16 v[14:17], v[66:69], v[204:207], v[14:17]
	v_mfma_f32_16x16x32_bf16 v[10:13], v[86:89], v[204:207], v[10:13]
	v_mfma_f32_16x16x32_bf16 v[62:65], v[70:73], v[166:169], v[62:65]
	v_mfma_f32_16x16x32_bf16 v[54:57], v[106:109], v[166:169], v[54:57]
	v_mfma_f32_16x16x32_bf16 v[46:49], v[70:73], v[174:177], v[46:49]
	v_mfma_f32_16x16x32_bf16 v[42:45], v[106:109], v[174:177], v[42:45]
	v_mfma_f32_16x16x32_bf16 v[30:33], v[70:73], v[200:203], v[30:33]
	v_mfma_f32_16x16x32_bf16 v[26:29], v[106:109], v[200:203], v[26:29]
	v_mfma_f32_16x16x32_bf16 v[14:17], v[70:73], v[208:211], v[14:17]
	v_mfma_f32_16x16x32_bf16 v[10:13], v[106:109], v[208:211], v[10:13]
	v_mfma_f32_16x16x32_bf16 v[58:61], v[146:149], v[162:165], v[58:61]
	v_mfma_f32_16x16x32_bf16 v[50:53], v[154:157], v[162:165], v[50:53]
	v_mfma_f32_16x16x32_bf16 v[38:41], v[146:149], v[170:173], v[38:41]
	v_mfma_f32_16x16x32_bf16 v[34:37], v[154:157], v[170:173], v[34:37]
	v_mfma_f32_16x16x32_bf16 v[22:25], v[146:149], v[196:199], v[22:25]
	v_mfma_f32_16x16x32_bf16 v[18:21], v[154:157], v[196:199], v[18:21]
	v_mfma_f32_16x16x32_bf16 v[6:9], v[146:149], v[204:207], v[6:9]
	v_mfma_f32_16x16x32_bf16 v[2:5], v[154:157], v[204:207], v[2:5]
	v_mfma_f32_16x16x32_bf16 v[58:61], v[150:153], v[166:169], v[58:61]
	v_mfma_f32_16x16x32_bf16 v[50:53], v[158:161], v[166:169], v[50:53]
	v_mfma_f32_16x16x32_bf16 v[38:41], v[150:153], v[174:177], v[38:41]
	v_mfma_f32_16x16x32_bf16 v[34:37], v[158:161], v[174:177], v[34:37]
	v_mfma_f32_16x16x32_bf16 v[22:25], v[150:153], v[200:203], v[22:25]
	v_mfma_f32_16x16x32_bf16 v[18:21], v[158:161], v[200:203], v[18:21]
	v_mfma_f32_16x16x32_bf16 v[6:9], v[150:153], v[208:211], v[6:9]
	v_mfma_f32_16x16x32_bf16 v[2:5], v[158:161], v[208:211], v[2:5]
	s_setprio 0
	s_barrier
	s_add_i32 s22, s22, 2
	s_add_u32 s8, s8, 0x100
	s_addc_u32 s9, s9, 0
	s_add_u32 s5, s5, 0x100
	s_addc_u32 s7, s7, 0
	s_cmp_gt_u32 s22, 13
	s_cbranch_scc1 .Lpeel_x4
.LBB0_991:
	ds_read_b128 v[66:69], v219
	ds_read_b128 v[70:73], v219 offset:1024
	ds_read_b128 v[86:89], v219 offset:2048
	ds_read_b128 v[106:109], v219 offset:3072
	ds_read_b128 v[146:149], v220
	ds_read_b128 v[150:153], v220 offset:1024
	ds_read_b128 v[154:157], v220 offset:2048
	ds_read_b128 v[158:161], v220 offset:3072
	s_add_u32 s10, s8, 0xfffc0080
	s_addc_u32 s11, s9, -1
	s_cmp_eq_u32 s22, 12
	s_cselect_b32 s45, s1, s11
	s_cselect_b32 s44, s2, s10
	s_cselect_b32 s11, s3, s7
	s_cselect_b32 s10, s4, s5
	s_add_i32 m0, s54, 0xc000
	ds_read_b128 v[162:165], v221
	ds_read_b128 v[166:169], v221 offset:1024
	ds_read_b128 v[170:173], v221 offset:2048
	ds_read_b128 v[174:177], v221 offset:3072
	ds_read_b128 v[196:199], v221 offset:4096
	ds_read_b128 v[200:203], v221 offset:5120
	ds_read_b128 v[204:207], v221 offset:6144
	ds_read_b128 v[208:211], v221 offset:7168
	global_load_lds_dwordx4 v192, s[8:9]
	s_add_i32 m0, s54, 0xe000
	s_nop 0
	global_load_lds_dwordx4 v194, s[8:9]
	s_waitcnt vmcnt(8)
	s_waitcnt lgkmcnt(0)
	s_barrier
	s_setprio 1
	v_mfma_f32_16x16x32_bf16 v[142:145], v[66:69], v[162:165], v[142:145]
	v_mfma_f32_16x16x32_bf16 v[134:137], v[86:89], v[162:165], v[134:137]
	v_mfma_f32_16x16x32_bf16 v[126:129], v[66:69], v[170:173], v[126:129]
	v_mfma_f32_16x16x32_bf16 v[122:125], v[86:89], v[170:173], v[122:125]
	v_mfma_f32_16x16x32_bf16 v[110:113], v[66:69], v[196:199], v[110:113]
	v_mfma_f32_16x16x32_bf16 v[102:105], v[86:89], v[196:199], v[102:105]
	v_mfma_f32_16x16x32_bf16 v[90:93], v[66:69], v[204:207], v[90:93]
	v_mfma_f32_16x16x32_bf16 v[82:85], v[86:89], v[204:207], v[82:85]
	v_mfma_f32_16x16x32_bf16 v[142:145], v[70:73], v[166:169], v[142:145]
	v_mfma_f32_16x16x32_bf16 v[134:137], v[106:109], v[166:169], v[134:137]
	v_mfma_f32_16x16x32_bf16 v[126:129], v[70:73], v[174:177], v[126:129]
	v_mfma_f32_16x16x32_bf16 v[122:125], v[106:109], v[174:177], v[122:125]
	v_mfma_f32_16x16x32_bf16 v[110:113], v[70:73], v[200:203], v[110:113]
	v_mfma_f32_16x16x32_bf16 v[102:105], v[106:109], v[200:203], v[102:105]
	v_mfma_f32_16x16x32_bf16 v[90:93], v[70:73], v[208:211], v[90:93]
	v_mfma_f32_16x16x32_bf16 v[82:85], v[106:109], v[208:211], v[82:85]
	v_mfma_f32_16x16x32_bf16 v[138:141], v[146:149], v[162:165], v[138:141]
	v_mfma_f32_16x16x32_bf16 v[130:133], v[154:157], v[162:165], v[130:133]
	v_mfma_f32_16x16x32_bf16 v[118:121], v[146:149], v[170:173], v[118:121]
	v_mfma_f32_16x16x32_bf16 v[114:117], v[154:157], v[170:173], v[114:117]
	v_mfma_f32_16x16x32_bf16 v[98:101], v[146:149], v[196:199], v[98:101]
	v_mfma_f32_16x16x32_bf16 v[94:97], v[154:157], v[196:199], v[94:97]
	v_mfma_f32_16x16x32_bf16 v[78:81], v[146:149], v[204:207], v[78:81]
	v_mfma_f32_16x16x32_bf16 v[74:77], v[154:157], v[204:207], v[74:77]
	v_mfma_f32_16x16x32_bf16 v[138:141], v[150:153], v[166:169], v[138:141]
	v_mfma_f32_16x16x32_bf16 v[130:133], v[158:161], v[166:169], v[130:133]
	v_mfma_f32_16x16x32_bf16 v[118:121], v[150:153], v[174:177], v[118:121]
	v_mfma_f32_16x16x32_bf16 v[114:117], v[158:161], v[174:177], v[114:117]
	v_mfma_f32_16x16x32_bf16 v[98:101], v[150:153], v[200:203], v[98:101]
	v_mfma_f32_16x16x32_bf16 v[94:97], v[158:161], v[200:203], v[94:97]
	v_mfma_f32_16x16x32_bf16 v[78:81], v[150:153], v[208:211], v[78:81]
	v_mfma_f32_16x16x32_bf16 v[74:77], v[158:161], v[208:211], v[74:77]
	s_setprio 0
	s_barrier
	s_add_i32 s37, s62, s53
	s_mov_b32 m0, s37
	ds_read_b128 v[162:165], v221 offset:16384
	ds_read_b128 v[166:169], v221 offset:17408
	ds_read_b128 v[170:173], v221 offset:18432
	ds_read_b128 v[174:177], v221 offset:19456
	ds_read_b128 v[196:199], v221 offset:20480
	ds_read_b128 v[200:203], v221 offset:21504
	ds_read_b128 v[204:207], v221 offset:22528
	ds_read_b128 v[208:211], v221 offset:23552
	global_load_lds_dwordx4 v184, s[10:11]
	s_add_i32 m0, s37, 0x2000
	s_add_u32 s46, s10, 0x40000
	s_addc_u32 s47, s11, 0
	s_add_i32 s37, s63, s53
	global_load_lds_dwordx4 v188, s[10:11]
	s_mov_b32 m0, s37
	s_nop 0
	global_load_lds_dwordx4 v184, s[46:47]
	s_add_i32 m0, s37, 0x2000
	s_nop 0
	global_load_lds_dwordx4 v188, s[46:47]
	s_mov_b32 m0, s54
	s_nop 0
	global_load_lds_dwordx4 v182, s[44:45]
	s_mov_b32 m0, s55
	s_nop 0
	global_load_lds_dwordx4 v186, s[44:45]
	s_waitcnt vmcnt(8)
	s_waitcnt lgkmcnt(0)
	s_barrier
	s_setprio 1
	v_mfma_f32_16x16x32_bf16 v[62:65], v[66:69], v[162:165], v[62:65]
	v_mfma_f32_16x16x32_bf16 v[54:57], v[86:89], v[162:165], v[54:57]
	v_mfma_f32_16x16x32_bf16 v[46:49], v[66:69], v[170:173], v[46:49]
	v_mfma_f32_16x16x32_bf16 v[42:45], v[86:89], v[170:173], v[42:45]
	v_mfma_f32_16x16x32_bf16 v[30:33], v[66:69], v[196:199], v[30:33]
	v_mfma_f32_16x16x32_bf16 v[26:29], v[86:89], v[196:199], v[26:29]
	v_mfma_f32_16x16x32_bf16 v[14:17], v[66:69], v[204:207], v[14:17]
	v_mfma_f32_16x16x32_bf16 v[10:13], v[86:89], v[204:207], v[10:13]
	v_mfma_f32_16x16x32_bf16 v[62:65], v[70:73], v[166:169], v[62:65]
	v_mfma_f32_16x16x32_bf16 v[54:57], v[106:109], v[166:169], v[54:57]
	v_mfma_f32_16x16x32_bf16 v[46:49], v[70:73], v[174:177], v[46:49]
	v_mfma_f32_16x16x32_bf16 v[42:45], v[106:109], v[174:177], v[42:45]
	v_mfma_f32_16x16x32_bf16 v[30:33], v[70:73], v[200:203], v[30:33]
	v_mfma_f32_16x16x32_bf16 v[26:29], v[106:109], v[200:203], v[26:29]
	v_mfma_f32_16x16x32_bf16 v[14:17], v[70:73], v[208:211], v[14:17]
	v_mfma_f32_16x16x32_bf16 v[10:13], v[106:109], v[208:211], v[10:13]
	v_mfma_f32_16x16x32_bf16 v[58:61], v[146:149], v[162:165], v[58:61]
	v_mfma_f32_16x16x32_bf16 v[50:53], v[154:157], v[162:165], v[50:53]
	v_mfma_f32_16x16x32_bf16 v[38:41], v[146:149], v[170:173], v[38:41]
	v_mfma_f32_16x16x32_bf16 v[34:37], v[154:157], v[170:173], v[34:37]
	v_mfma_f32_16x16x32_bf16 v[22:25], v[146:149], v[196:199], v[22:25]
	v_mfma_f32_16x16x32_bf16 v[18:21], v[154:157], v[196:199], v[18:21]
	v_mfma_f32_16x16x32_bf16 v[6:9], v[146:149], v[204:207], v[6:9]
	v_mfma_f32_16x16x32_bf16 v[2:5], v[154:157], v[204:207], v[2:5]
	v_mfma_f32_16x16x32_bf16 v[58:61], v[150:153], v[166:169], v[58:61]
	v_mfma_f32_16x16x32_bf16 v[50:53], v[158:161], v[166:169], v[50:53]
	v_mfma_f32_16x16x32_bf16 v[38:41], v[150:153], v[174:177], v[38:41]
	v_mfma_f32_16x16x32_bf16 v[34:37], v[158:161], v[174:177], v[34:37]
	v_mfma_f32_16x16x32_bf16 v[22:25], v[150:153], v[200:203], v[22:25]
	v_mfma_f32_16x16x32_bf16 v[18:21], v[158:161], v[200:203], v[18:21]
	v_mfma_f32_16x16x32_bf16 v[6:9], v[150:153], v[208:211], v[6:9]
	v_mfma_f32_16x16x32_bf16 v[2:5], v[158:161], v[208:211], v[2:5]
	s_setprio 0
	s_barrier
	s_add_i32 s37, 0, 0x18000
	s_add_i32 s39, 0, 0x1c000
	ds_read_b128 v[66:69], v254
	ds_read_b128 v[70:73], v254 offset:1024
	ds_read_b128 v[86:89], v254 offset:2048
	ds_read_b128 v[106:109], v254 offset:3072
	ds_read_b128 v[146:149], v255
	ds_read_b128 v[150:153], v255 offset:1024
	ds_read_b128 v[154:157], v255 offset:2048
	ds_read_b128 v[158:161], v255 offset:3072
	s_add_u32 s44, s44, 0x40000
	s_addc_u32 s45, s45, 0
	s_mov_b32 m0, s56
	ds_read_b128 v[162:165], v221 offset:32768
	ds_read_b128 v[166:169], v221 offset:33792
	ds_read_b128 v[170:173], v221 offset:34816
	ds_read_b128 v[174:177], v221 offset:35840
	ds_read_b128 v[196:199], v221 offset:36864
	ds_read_b128 v[200:203], v221 offset:37888
	ds_read_b128 v[204:207], v221 offset:38912
	ds_read_b128 v[208:211], v221 offset:39936
	global_load_lds_dwordx4 v182, s[44:45]
	s_mov_b32 m0, s57
	s_nop 0
	global_load_lds_dwordx4 v186, s[44:45]
	s_waitcnt vmcnt(8)
	s_waitcnt lgkmcnt(0)
	s_barrier
	s_setprio 1
	v_mfma_f32_16x16x32_bf16 v[142:145], v[66:69], v[162:165], v[142:145]
	v_mfma_f32_16x16x32_bf16 v[134:137], v[86:89], v[162:165], v[134:137]
	v_mfma_f32_16x16x32_bf16 v[126:129], v[66:69], v[170:173], v[126:129]
	v_mfma_f32_16x16x32_bf16 v[122:125], v[86:89], v[170:173], v[122:125]
	v_mfma_f32_16x16x32_bf16 v[110:113], v[66:69], v[196:199], v[110:113]
	v_mfma_f32_16x16x32_bf16 v[102:105], v[86:89], v[196:199], v[102:105]
	v_mfma_f32_16x16x32_bf16 v[90:93], v[66:69], v[204:207], v[90:93]
	v_mfma_f32_16x16x32_bf16 v[82:85], v[86:89], v[204:207], v[82:85]
	v_mfma_f32_16x16x32_bf16 v[142:145], v[70:73], v[166:169], v[142:145]
	v_mfma_f32_16x16x32_bf16 v[134:137], v[106:109], v[166:169], v[134:137]
	v_mfma_f32_16x16x32_bf16 v[126:129], v[70:73], v[174:177], v[126:129]
	v_mfma_f32_16x16x32_bf16 v[122:125], v[106:109], v[174:177], v[122:125]
	v_mfma_f32_16x16x32_bf16 v[110:113], v[70:73], v[200:203], v[110:113]
	v_mfma_f32_16x16x32_bf16 v[102:105], v[106:109], v[200:203], v[102:105]
	v_mfma_f32_16x16x32_bf16 v[90:93], v[70:73], v[208:211], v[90:93]
	v_mfma_f32_16x16x32_bf16 v[82:85], v[106:109], v[208:211], v[82:85]
	v_mfma_f32_16x16x32_bf16 v[138:141], v[146:149], v[162:165], v[138:141]
	v_mfma_f32_16x16x32_bf16 v[130:133], v[154:157], v[162:165], v[130:133]
	v_mfma_f32_16x16x32_bf16 v[118:121], v[146:149], v[170:173], v[118:121]
	v_mfma_f32_16x16x32_bf16 v[114:117], v[154:157], v[170:173], v[114:117]
	v_mfma_f32_16x16x32_bf16 v[98:101], v[146:149], v[196:199], v[98:101]
	v_mfma_f32_16x16x32_bf16 v[94:97], v[154:157], v[196:199], v[94:97]
	v_mfma_f32_16x16x32_bf16 v[78:81], v[146:149], v[204:207], v[78:81]
	v_mfma_f32_16x16x32_bf16 v[74:77], v[154:157], v[204:207], v[74:77]
	v_mfma_f32_16x16x32_bf16 v[138:141], v[150:153], v[166:169], v[138:141]
	v_mfma_f32_16x16x32_bf16 v[130:133], v[158:161], v[166:169], v[130:133]
	v_mfma_f32_16x16x32_bf16 v[118:121], v[150:153], v[174:177], v[118:121]
	v_mfma_f32_16x16x32_bf16 v[114:117], v[158:161], v[174:177], v[114:117]
	v_mfma_f32_16x16x32_bf16 v[98:101], v[150:153], v[200:203], v[98:101]
	v_mfma_f32_16x16x32_bf16 v[94:97], v[158:161], v[200:203], v[94:97]
	v_mfma_f32_16x16x32_bf16 v[78:81], v[150:153], v[208:211], v[78:81]
	v_mfma_f32_16x16x32_bf16 v[74:77], v[158:161], v[208:211], v[74:77]
	s_setprio 0
	s_barrier
	s_add_i32 s37, s37, s53
	s_mov_b32 m0, s37
	ds_read_b128 v[162:165], v221 offset:49152
	ds_read_b128 v[166:169], v221 offset:50176
	ds_read_b128 v[170:173], v221 offset:51200
	ds_read_b128 v[174:177], v221 offset:52224
	ds_read_b128 v[196:199], v221 offset:53248
	ds_read_b128 v[200:203], v221 offset:54272
	ds_read_b128 v[204:207], v221 offset:55296
	ds_read_b128 v[208:211], v221 offset:56320
	s_add_u32 s98, s10, 0x80
	s_addc_u32 s99, s11, 0
	global_load_lds_dwordx4 v184, s[98:99]
	s_add_i32 m0, s37, 0x2000
	s_add_u32 s10, s10, 0x40080
	s_addc_u32 s11, s11, 0
	s_add_i32 s37, s39, s53
	global_load_lds_dwordx4 v188, s[98:99]
	s_mov_b32 m0, s37
	s_nop 0
	global_load_lds_dwordx4 v184, s[10:11]
	s_add_i32 m0, s37, 0x2000
	s_nop 0
	global_load_lds_dwordx4 v188, s[10:11]
	s_add_u32 s98, s44, 0xfffc0080
	s_addc_u32 s99, s45, -1
	s_mov_b32 m0, s60
	s_nop 0
	global_load_lds_dwordx4 v182, s[98:99]
	s_mov_b32 m0, s61
	s_nop 0
	global_load_lds_dwordx4 v186, s[98:99]
	s_waitcnt vmcnt(8)
	s_waitcnt lgkmcnt(0)
	s_barrier
	s_setprio 1
	v_mfma_f32_16x16x32_bf16 v[62:65], v[66:69], v[162:165], v[62:65]
	v_mfma_f32_16x16x32_bf16 v[54:57], v[86:89], v[162:165], v[54:57]
	v_mfma_f32_16x16x32_bf16 v[46:49], v[66:69], v[170:173], v[46:49]
	v_mfma_f32_16x16x32_bf16 v[42:45], v[86:89], v[170:173], v[42:45]
	v_mfma_f32_16x16x32_bf16 v[30:33], v[66:69], v[196:199], v[30:33]
	v_mfma_f32_16x16x32_bf16 v[26:29], v[86:89], v[196:199], v[26:29]
	v_mfma_f32_16x16x32_bf16 v[14:17], v[66:69], v[204:207], v[14:17]
	v_mfma_f32_16x16x32_bf16 v[10:13], v[86:89], v[204:207], v[10:13]
	v_mfma_f32_16x16x32_bf16 v[62:65], v[70:73], v[166:169], v[62:65]
	v_mfma_f32_16x16x32_bf16 v[54:57], v[106:109], v[166:169], v[54:57]
	v_mfma_f32_16x16x32_bf16 v[46:49], v[70:73], v[174:177], v[46:49]
	v_mfma_f32_16x16x32_bf16 v[42:45], v[106:109], v[174:177], v[42:45]
	v_mfma_f32_16x16x32_bf16 v[30:33], v[70:73], v[200:203], v[30:33]
	v_mfma_f32_16x16x32_bf16 v[26:29], v[106:109], v[200:203], v[26:29]
	v_mfma_f32_16x16x32_bf16 v[14:17], v[70:73], v[208:211], v[14:17]
	v_mfma_f32_16x16x32_bf16 v[10:13], v[106:109], v[208:211], v[10:13]
	v_mfma_f32_16x16x32_bf16 v[58:61], v[146:149], v[162:165], v[58:61]
	v_mfma_f32_16x16x32_bf16 v[50:53], v[154:157], v[162:165], v[50:53]
	v_mfma_f32_16x16x32_bf16 v[38:41], v[146:149], v[170:173], v[38:41]
	v_mfma_f32_16x16x32_bf16 v[34:37], v[154:157], v[170:173], v[34:37]
	v_mfma_f32_16x16x32_bf16 v[22:25], v[146:149], v[196:199], v[22:25]
	v_mfma_f32_16x16x32_bf16 v[18:21], v[154:157], v[196:199], v[18:21]
	v_mfma_f32_16x16x32_bf16 v[6:9], v[146:149], v[204:207], v[6:9]
	v_mfma_f32_16x16x32_bf16 v[2:5], v[154:157], v[204:207], v[2:5]
	v_mfma_f32_16x16x32_bf16 v[58:61], v[150:153], v[166:169], v[58:61]
	v_mfma_f32_16x16x32_bf16 v[50:53], v[158:161], v[166:169], v[50:53]
	v_mfma_f32_16x16x32_bf16 v[38:41], v[150:153], v[174:177], v[38:41]
	v_mfma_f32_16x16x32_bf16 v[34:37], v[158:161], v[174:177], v[34:37]
	v_mfma_f32_16x16x32_bf16 v[22:25], v[150:153], v[200:203], v[22:25]
	v_mfma_f32_16x16x32_bf16 v[18:21], v[158:161], v[200:203], v[18:21]
	v_mfma_f32_16x16x32_bf16 v[6:9], v[150:153], v[208:211], v[6:9]
	v_mfma_f32_16x16x32_bf16 v[2:5], v[158:161], v[208:211], v[2:5]
	s_setprio 0
	s_barrier
	s_add_i32 s22, s22, 2
	s_add_u32 s8, s8, 0x100
	s_addc_u32 s9, s9, 0
	s_add_u32 s5, s5, 0x100
	s_addc_u32 s7, s7, 0
	s_cmp_gt_u32 s22, 13
	s_cbranch_scc0 .LBB0_991

.LBB0_1107:
	s_and_b64 s[20:21], s[26:27], exec
	s_cselect_b32 s21, s35, s23
	s_cselect_b32 s20, s34, s22
	s_add_u32 s22, s22, 0xb0080
	s_addc_u32 s23, s23, 0
	s_add_u32 s49, s24, 0x100
	s_addc_u32 s50, s25, 0
	s_mov_b32 s51, -2
	ds_read_b128 v[142:145], v150
	ds_read_b128 v[156:159], v150 offset:1024
	ds_read_b128 v[160:163], v150 offset:2048
	ds_read_b128 v[164:167], v150 offset:3072
	ds_read_b128 v[168:171], v151
	ds_read_b128 v[172:175], v151 offset:1024
	ds_read_b128 v[180:183], v151 offset:2048
	ds_read_b128 v[184:187], v151 offset:3072
	s_add_u32 s24, s22, 0xfff50080
	s_addc_u32 s25, s23, -1
	s_cmp_eq_u32 s51, 40
	s_cselect_b32 s27, s21, s25
	s_cselect_b32 s26, s20, s24
	s_cselect_b32 s25, s19, s50
	s_cselect_b32 s24, s18, s49
	s_mov_b32 m0, s36
	ds_read_b128 v[188:191], v152
	ds_read_b128 v[192:195], v152 offset:1024
	ds_read_b128 v[196:199], v152 offset:2048
	ds_read_b128 v[200:203], v152 offset:3072
	ds_read_b128 v[204:207], v152 offset:4096
	ds_read_b128 v[208:211], v152 offset:5120
	ds_read_b128 v[212:215], v152 offset:6144
	ds_read_b128 v[216:219], v152 offset:7168
	global_load_lds_dwordx4 v138, s[22:23]
	s_mov_b32 m0, s37
	s_nop 0
	global_load_lds_dwordx4 v140, s[22:23]
	s_waitcnt vmcnt(8)
	s_waitcnt lgkmcnt(0)
	s_barrier
	s_setprio 1
	v_mfma_f32_16x16x32_bf16 v[126:129], v[142:145], v[188:191], 0
	v_mfma_f32_16x16x32_bf16 v[122:125], v[160:163], v[188:191], 0
	v_mfma_f32_16x16x32_bf16 v[110:113], v[142:145], v[196:199], 0
	v_mfma_f32_16x16x32_bf16 v[106:109], v[160:163], v[196:199], 0
	v_mfma_f32_16x16x32_bf16 v[94:97], v[142:145], v[204:207], 0
	v_mfma_f32_16x16x32_bf16 v[90:93], v[160:163], v[204:207], 0
	v_mfma_f32_16x16x32_bf16 v[78:81], v[142:145], v[212:215], 0
	v_mfma_f32_16x16x32_bf16 v[74:77], v[160:163], v[212:215], 0
	v_mfma_f32_16x16x32_bf16 v[126:129], v[156:159], v[192:195], v[126:129]
	v_mfma_f32_16x16x32_bf16 v[122:125], v[164:167], v[192:195], v[122:125]
	v_mfma_f32_16x16x32_bf16 v[110:113], v[156:159], v[200:203], v[110:113]
	v_mfma_f32_16x16x32_bf16 v[106:109], v[164:167], v[200:203], v[106:109]
	v_mfma_f32_16x16x32_bf16 v[94:97], v[156:159], v[208:211], v[94:97]
	v_mfma_f32_16x16x32_bf16 v[90:93], v[164:167], v[208:211], v[90:93]
	v_mfma_f32_16x16x32_bf16 v[78:81], v[156:159], v[216:219], v[78:81]
	v_mfma_f32_16x16x32_bf16 v[74:77], v[164:167], v[216:219], v[74:77]
	v_mfma_f32_16x16x32_bf16 v[118:121], v[168:171], v[188:191], 0
	v_mfma_f32_16x16x32_bf16 v[114:117], v[180:183], v[188:191], 0
	v_mfma_f32_16x16x32_bf16 v[102:105], v[168:171], v[196:199], 0
	v_mfma_f32_16x16x32_bf16 v[98:101], v[180:183], v[196:199], 0
	v_mfma_f32_16x16x32_bf16 v[86:89], v[168:171], v[204:207], 0
	v_mfma_f32_16x16x32_bf16 v[82:85], v[180:183], v[204:207], 0
	v_mfma_f32_16x16x32_bf16 v[70:73], v[168:171], v[212:215], 0
	v_mfma_f32_16x16x32_bf16 v[66:69], v[180:183], v[212:215], 0
	v_mfma_f32_16x16x32_bf16 v[118:121], v[172:175], v[192:195], v[118:121]
	v_mfma_f32_16x16x32_bf16 v[114:117], v[184:187], v[192:195], v[114:117]
	v_mfma_f32_16x16x32_bf16 v[102:105], v[172:175], v[200:203], v[102:105]
	v_mfma_f32_16x16x32_bf16 v[98:101], v[184:187], v[200:203], v[98:101]
	v_mfma_f32_16x16x32_bf16 v[86:89], v[172:175], v[208:211], v[86:89]
	v_mfma_f32_16x16x32_bf16 v[82:85], v[184:187], v[208:211], v[82:85]
	v_mfma_f32_16x16x32_bf16 v[70:73], v[172:175], v[216:219], v[70:73]
	v_mfma_f32_16x16x32_bf16 v[66:69], v[184:187], v[216:219], v[66:69]
	s_setprio 0
	s_barrier
	s_mov_b32 m0, s38
	s_add_u32 s52, s24, 0xb0000
	ds_read_b128 v[188:191], v152 offset:16384
	ds_read_b128 v[192:195], v152 offset:17408
	ds_read_b128 v[196:199], v152 offset:18432
	ds_read_b128 v[200:203], v152 offset:19456
	ds_read_b128 v[204:207], v152 offset:20480
	ds_read_b128 v[208:211], v152 offset:21504
	ds_read_b128 v[212:215], v152 offset:22528
	ds_read_b128 v[216:219], v152 offset:23552
	global_load_lds_dwordx4 v134, s[24:25]
	s_mov_b32 m0, s39
	s_addc_u32 s53, s25, 0
	global_load_lds_dwordx4 v130, s[24:25]
	s_mov_b32 m0, s40
	s_nop 0
	global_load_lds_dwordx4 v134, s[52:53]
	s_mov_b32 m0, s41
	s_nop 0
	global_load_lds_dwordx4 v130, s[52:53]
	s_mov_b32 m0, s4
	s_nop 0
	global_load_lds_dwordx4 v136, s[26:27]
	s_mov_b32 m0, s5
	s_nop 0
	global_load_lds_dwordx4 v132, s[26:27]
	s_waitcnt vmcnt(8)
	s_waitcnt lgkmcnt(0)
	s_barrier
	s_setprio 1
	v_mfma_f32_16x16x32_bf16 v[62:65], v[142:145], v[188:191], 0
	v_mfma_f32_16x16x32_bf16 v[58:61], v[160:163], v[188:191], 0
	v_mfma_f32_16x16x32_bf16 v[46:49], v[142:145], v[196:199], 0
	v_mfma_f32_16x16x32_bf16 v[42:45], v[160:163], v[196:199], 0
	v_mfma_f32_16x16x32_bf16 v[34:37], v[142:145], v[204:207], 0
	v_mfma_f32_16x16x32_bf16 v[26:29], v[160:163], v[204:207], 0
	v_mfma_f32_16x16x32_bf16 v[18:21], v[142:145], v[212:215], 0
	v_mfma_f32_16x16x32_bf16 v[10:13], v[160:163], v[212:215], 0
	v_mfma_f32_16x16x32_bf16 v[62:65], v[156:159], v[192:195], v[62:65]
	v_mfma_f32_16x16x32_bf16 v[58:61], v[164:167], v[192:195], v[58:61]
	v_mfma_f32_16x16x32_bf16 v[46:49], v[156:159], v[200:203], v[46:49]
	v_mfma_f32_16x16x32_bf16 v[42:45], v[164:167], v[200:203], v[42:45]
	v_mfma_f32_16x16x32_bf16 v[34:37], v[156:159], v[208:211], v[34:37]
	v_mfma_f32_16x16x32_bf16 v[26:29], v[164:167], v[208:211], v[26:29]
	v_mfma_f32_16x16x32_bf16 v[18:21], v[156:159], v[216:219], v[18:21]
	v_mfma_f32_16x16x32_bf16 v[10:13], v[164:167], v[216:219], v[10:13]
	v_mfma_f32_16x16x32_bf16 v[54:57], v[168:171], v[188:191], 0
	v_mfma_f32_16x16x32_bf16 v[50:53], v[180:183], v[188:191], 0
	v_mfma_f32_16x16x32_bf16 v[38:41], v[168:171], v[196:199], 0
	v_mfma_f32_16x16x32_bf16 v[30:33], v[180:183], v[196:199], 0
	v_mfma_f32_16x16x32_bf16 v[22:25], v[168:171], v[204:207], 0
	v_mfma_f32_16x16x32_bf16 v[14:17], v[180:183], v[204:207], 0
	v_mfma_f32_16x16x32_bf16 v[6:9], v[168:171], v[212:215], 0
	v_mfma_f32_16x16x32_bf16 v[2:5], v[180:183], v[212:215], 0
	v_mfma_f32_16x16x32_bf16 v[54:57], v[172:175], v[192:195], v[54:57]
	v_mfma_f32_16x16x32_bf16 v[50:53], v[184:187], v[192:195], v[50:53]
	v_mfma_f32_16x16x32_bf16 v[38:41], v[172:175], v[200:203], v[38:41]
	v_mfma_f32_16x16x32_bf16 v[30:33], v[184:187], v[200:203], v[30:33]
	v_mfma_f32_16x16x32_bf16 v[22:25], v[172:175], v[208:211], v[22:25]
	v_mfma_f32_16x16x32_bf16 v[14:17], v[184:187], v[208:211], v[14:17]
	v_mfma_f32_16x16x32_bf16 v[6:9], v[172:175], v[216:219], v[6:9]
	v_mfma_f32_16x16x32_bf16 v[2:5], v[184:187], v[216:219], v[2:5]
	s_setprio 0
	s_barrier
	ds_read_b128 v[142:145], v153
	ds_read_b128 v[156:159], v153 offset:1024
	ds_read_b128 v[160:163], v153 offset:2048
	ds_read_b128 v[164:167], v153 offset:3072
	ds_read_b128 v[168:171], v154
	ds_read_b128 v[172:175], v154 offset:1024
	ds_read_b128 v[180:183], v154 offset:2048
	ds_read_b128 v[184:187], v154 offset:3072
	s_add_u32 s26, s26, 0xb0000
	s_addc_u32 s27, s27, 0
	s_mov_b32 m0, s29
	ds_read_b128 v[188:191], v152 offset:32768
	ds_read_b128 v[192:195], v152 offset:33792
	ds_read_b128 v[196:199], v152 offset:34816
	ds_read_b128 v[200:203], v152 offset:35840
	ds_read_b128 v[204:207], v152 offset:36864
	ds_read_b128 v[208:211], v152 offset:37888
	ds_read_b128 v[212:215], v152 offset:38912
	ds_read_b128 v[216:219], v152 offset:39936
	global_load_lds_dwordx4 v136, s[26:27]
	s_mov_b32 m0, s30
	s_nop 0
	global_load_lds_dwordx4 v132, s[26:27]
	s_waitcnt vmcnt(8)
	s_waitcnt lgkmcnt(0)
	s_barrier
	s_setprio 1
	v_mfma_f32_16x16x32_bf16 v[126:129], v[142:145], v[188:191], v[126:129]
	v_mfma_f32_16x16x32_bf16 v[122:125], v[160:163], v[188:191], v[122:125]
	v_mfma_f32_16x16x32_bf16 v[110:113], v[142:145], v[196:199], v[110:113]
	v_mfma_f32_16x16x32_bf16 v[106:109], v[160:163], v[196:199], v[106:109]
	v_mfma_f32_16x16x32_bf16 v[94:97], v[142:145], v[204:207], v[94:97]
	v_mfma_f32_16x16x32_bf16 v[90:93], v[160:163], v[204:207], v[90:93]
	v_mfma_f32_16x16x32_bf16 v[78:81], v[142:145], v[212:215], v[78:81]
	v_mfma_f32_16x16x32_bf16 v[74:77], v[160:163], v[212:215], v[74:77]
	v_mfma_f32_16x16x32_bf16 v[126:129], v[156:159], v[192:195], v[126:129]
	v_mfma_f32_16x16x32_bf16 v[122:125], v[164:167], v[192:195], v[122:125]
	v_mfma_f32_16x16x32_bf16 v[110:113], v[156:159], v[200:203], v[110:113]
	v_mfma_f32_16x16x32_bf16 v[106:109], v[164:167], v[200:203], v[106:109]
	v_mfma_f32_16x16x32_bf16 v[94:97], v[156:159], v[208:211], v[94:97]
	v_mfma_f32_16x16x32_bf16 v[90:93], v[164:167], v[208:211], v[90:93]
	v_mfma_f32_16x16x32_bf16 v[78:81], v[156:159], v[216:219], v[78:81]
	v_mfma_f32_16x16x32_bf16 v[74:77], v[164:167], v[216:219], v[74:77]
	v_mfma_f32_16x16x32_bf16 v[118:121], v[168:171], v[188:191], v[118:121]
	v_mfma_f32_16x16x32_bf16 v[114:117], v[180:183], v[188:191], v[114:117]
	v_mfma_f32_16x16x32_bf16 v[102:105], v[168:171], v[196:199], v[102:105]
	v_mfma_f32_16x16x32_bf16 v[98:101], v[180:183], v[196:199], v[98:101]
	v_mfma_f32_16x16x32_bf16 v[86:89], v[168:171], v[204:207], v[86:89]
	v_mfma_f32_16x16x32_bf16 v[82:85], v[180:183], v[204:207], v[82:85]
	v_mfma_f32_16x16x32_bf16 v[70:73], v[168:171], v[212:215], v[70:73]
	v_mfma_f32_16x16x32_bf16 v[66:69], v[180:183], v[212:215], v[66:69]
	v_mfma_f32_16x16x32_bf16 v[118:121], v[172:175], v[192:195], v[118:121]
	v_mfma_f32_16x16x32_bf16 v[114:117], v[184:187], v[192:195], v[114:117]
	v_mfma_f32_16x16x32_bf16 v[102:105], v[172:175], v[200:203], v[102:105]
	v_mfma_f32_16x16x32_bf16 v[98:101], v[184:187], v[200:203], v[98:101]
	v_mfma_f32_16x16x32_bf16 v[86:89], v[172:175], v[208:211], v[86:89]
	v_mfma_f32_16x16x32_bf16 v[82:85], v[184:187], v[208:211], v[82:85]
	v_mfma_f32_16x16x32_bf16 v[70:73], v[172:175], v[216:219], v[70:73]
	v_mfma_f32_16x16x32_bf16 v[66:69], v[184:187], v[216:219], v[66:69]
	s_setprio 0
	s_barrier
	s_mov_b32 m0, s42
	ds_read_b128 v[188:191], v152 offset:49152
	ds_read_b128 v[192:195], v152 offset:50176
	ds_read_b128 v[196:199], v152 offset:51200
	ds_read_b128 v[200:203], v152 offset:52224
	ds_read_b128 v[204:207], v152 offset:53248
	ds_read_b128 v[208:211], v152 offset:54272
	ds_read_b128 v[212:215], v152 offset:55296
	ds_read_b128 v[216:219], v152 offset:56320
	s_add_u32 s98, s24, 0x80
	s_addc_u32 s99, s25, 0
	global_load_lds_dwordx4 v134, s[98:99]
	s_mov_b32 m0, s43
	s_add_u32 s24, s24, 0xb0080
	s_addc_u32 s25, s25, 0
	global_load_lds_dwordx4 v130, s[98:99]
	s_mov_b32 m0, s44
	s_nop 0
	global_load_lds_dwordx4 v134, s[24:25]
	s_mov_b32 m0, s45
	s_nop 0
	global_load_lds_dwordx4 v130, s[24:25]
	s_add_u32 s98, s26, 0xfff50080
	s_addc_u32 s99, s27, -1
	s_mov_b32 m0, s0
	s_nop 0
	global_load_lds_dwordx4 v136, s[98:99]
	s_mov_b32 m0, s1
	s_nop 0
	global_load_lds_dwordx4 v132, s[98:99]
	s_waitcnt vmcnt(8)
	s_waitcnt lgkmcnt(0)
	s_barrier
	s_setprio 1
	v_mfma_f32_16x16x32_bf16 v[62:65], v[142:145], v[188:191], v[62:65]
	v_mfma_f32_16x16x32_bf16 v[58:61], v[160:163], v[188:191], v[58:61]
	v_mfma_f32_16x16x32_bf16 v[46:49], v[142:145], v[196:199], v[46:49]
	v_mfma_f32_16x16x32_bf16 v[42:45], v[160:163], v[196:199], v[42:45]
	v_mfma_f32_16x16x32_bf16 v[34:37], v[142:145], v[204:207], v[34:37]
	v_mfma_f32_16x16x32_bf16 v[26:29], v[160:163], v[204:207], v[26:29]
	v_mfma_f32_16x16x32_bf16 v[18:21], v[142:145], v[212:215], v[18:21]
	v_mfma_f32_16x16x32_bf16 v[10:13], v[160:163], v[212:215], v[10:13]
	v_mfma_f32_16x16x32_bf16 v[62:65], v[156:159], v[192:195], v[62:65]
	v_mfma_f32_16x16x32_bf16 v[58:61], v[164:167], v[192:195], v[58:61]
	v_mfma_f32_16x16x32_bf16 v[46:49], v[156:159], v[200:203], v[46:49]
	v_mfma_f32_16x16x32_bf16 v[42:45], v[164:167], v[200:203], v[42:45]
	v_mfma_f32_16x16x32_bf16 v[34:37], v[156:159], v[208:211], v[34:37]
	v_mfma_f32_16x16x32_bf16 v[26:29], v[164:167], v[208:211], v[26:29]
	v_mfma_f32_16x16x32_bf16 v[18:21], v[156:159], v[216:219], v[18:21]
	v_mfma_f32_16x16x32_bf16 v[10:13], v[164:167], v[216:219], v[10:13]
	v_mfma_f32_16x16x32_bf16 v[54:57], v[168:171], v[188:191], v[54:57]
	v_mfma_f32_16x16x32_bf16 v[50:53], v[180:183], v[188:191], v[50:53]
	v_mfma_f32_16x16x32_bf16 v[38:41], v[168:171], v[196:199], v[38:41]
	v_mfma_f32_16x16x32_bf16 v[30:33], v[180:183], v[196:199], v[30:33]
	v_mfma_f32_16x16x32_bf16 v[22:25], v[168:171], v[204:207], v[22:25]
	v_mfma_f32_16x16x32_bf16 v[14:17], v[180:183], v[204:207], v[14:17]
	v_mfma_f32_16x16x32_bf16 v[6:9], v[168:171], v[212:215], v[6:9]
	v_mfma_f32_16x16x32_bf16 v[2:5], v[180:183], v[212:215], v[2:5]
	v_mfma_f32_16x16x32_bf16 v[54:57], v[172:175], v[192:195], v[54:57]
	v_mfma_f32_16x16x32_bf16 v[50:53], v[184:187], v[192:195], v[50:53]
	v_mfma_f32_16x16x32_bf16 v[38:41], v[172:175], v[200:203], v[38:41]
	v_mfma_f32_16x16x32_bf16 v[30:33], v[184:187], v[200:203], v[30:33]
	v_mfma_f32_16x16x32_bf16 v[22:25], v[172:175], v[208:211], v[22:25]
	v_mfma_f32_16x16x32_bf16 v[14:17], v[184:187], v[208:211], v[14:17]
	v_mfma_f32_16x16x32_bf16 v[6:9], v[172:175], v[216:219], v[6:9]
	v_mfma_f32_16x16x32_bf16 v[2:5], v[184:187], v[216:219], v[2:5]
	s_setprio 0
	s_barrier
	s_add_i32 s51, s51, 2
	s_add_u32 s22, s22, 0x100
	s_addc_u32 s23, s23, 0
	s_add_u32 s49, s49, 0x100
	s_addc_u32 s50, s50, 0
	s_cmp_gt_u32 s51, 41
	s_cbranch_scc1 .Lpeel_x5
.LBB0_1108:
	ds_read_b128 v[142:145], v150
	ds_read_b128 v[156:159], v150 offset:1024
	ds_read_b128 v[160:163], v150 offset:2048
	ds_read_b128 v[164:167], v150 offset:3072
	ds_read_b128 v[168:171], v151
	ds_read_b128 v[172:175], v151 offset:1024
	ds_read_b128 v[180:183], v151 offset:2048
	ds_read_b128 v[184:187], v151 offset:3072
	s_add_u32 s24, s22, 0xfff50080
	s_addc_u32 s25, s23, -1
	s_cmp_eq_u32 s51, 40
	s_cselect_b32 s27, s21, s25
	s_cselect_b32 s26, s20, s24
	s_cselect_b32 s25, s19, s50
	s_cselect_b32 s24, s18, s49
	s_mov_b32 m0, s36
	ds_read_b128 v[188:191], v152
	ds_read_b128 v[192:195], v152 offset:1024
	ds_read_b128 v[196:199], v152 offset:2048
	ds_read_b128 v[200:203], v152 offset:3072
	ds_read_b128 v[204:207], v152 offset:4096
	ds_read_b128 v[208:211], v152 offset:5120
	ds_read_b128 v[212:215], v152 offset:6144
	ds_read_b128 v[216:219], v152 offset:7168
	global_load_lds_dwordx4 v138, s[22:23]
	s_mov_b32 m0, s37
	s_nop 0
	global_load_lds_dwordx4 v140, s[22:23]
	s_waitcnt vmcnt(8)
	s_waitcnt lgkmcnt(0)
	s_barrier
	s_setprio 1
	v_mfma_f32_16x16x32_bf16 v[126:129], v[142:145], v[188:191], v[126:129]
	v_mfma_f32_16x16x32_bf16 v[122:125], v[160:163], v[188:191], v[122:125]
	v_mfma_f32_16x16x32_bf16 v[110:113], v[142:145], v[196:199], v[110:113]
	v_mfma_f32_16x16x32_bf16 v[106:109], v[160:163], v[196:199], v[106:109]
	v_mfma_f32_16x16x32_bf16 v[94:97], v[142:145], v[204:207], v[94:97]
	v_mfma_f32_16x16x32_bf16 v[90:93], v[160:163], v[204:207], v[90:93]
	v_mfma_f32_16x16x32_bf16 v[78:81], v[142:145], v[212:215], v[78:81]
	v_mfma_f32_16x16x32_bf16 v[74:77], v[160:163], v[212:215], v[74:77]
	v_mfma_f32_16x16x32_bf16 v[126:129], v[156:159], v[192:195], v[126:129]
	v_mfma_f32_16x16x32_bf16 v[122:125], v[164:167], v[192:195], v[122:125]
	v_mfma_f32_16x16x32_bf16 v[110:113], v[156:159], v[200:203], v[110:113]
	v_mfma_f32_16x16x32_bf16 v[106:109], v[164:167], v[200:203], v[106:109]
	v_mfma_f32_16x16x32_bf16 v[94:97], v[156:159], v[208:211], v[94:97]
	v_mfma_f32_16x16x32_bf16 v[90:93], v[164:167], v[208:211], v[90:93]
	v_mfma_f32_16x16x32_bf16 v[78:81], v[156:159], v[216:219], v[78:81]
	v_mfma_f32_16x16x32_bf16 v[74:77], v[164:167], v[216:219], v[74:77]
	v_mfma_f32_16x16x32_bf16 v[118:121], v[168:171], v[188:191], v[118:121]
	v_mfma_f32_16x16x32_bf16 v[114:117], v[180:183], v[188:191], v[114:117]
	v_mfma_f32_16x16x32_bf16 v[102:105], v[168:171], v[196:199], v[102:105]
	v_mfma_f32_16x16x32_bf16 v[98:101], v[180:183], v[196:199], v[98:101]
	v_mfma_f32_16x16x32_bf16 v[86:89], v[168:171], v[204:207], v[86:89]
	v_mfma_f32_16x16x32_bf16 v[82:85], v[180:183], v[204:207], v[82:85]
	v_mfma_f32_16x16x32_bf16 v[70:73], v[168:171], v[212:215], v[70:73]
	v_mfma_f32_16x16x32_bf16 v[66:69], v[180:183], v[212:215], v[66:69]
	v_mfma_f32_16x16x32_bf16 v[118:121], v[172:175], v[192:195], v[118:121]
	v_mfma_f32_16x16x32_bf16 v[114:117], v[184:187], v[192:195], v[114:117]
	v_mfma_f32_16x16x32_bf16 v[102:105], v[172:175], v[200:203], v[102:105]
	v_mfma_f32_16x16x32_bf16 v[98:101], v[184:187], v[200:203], v[98:101]
	v_mfma_f32_16x16x32_bf16 v[86:89], v[172:175], v[208:211], v[86:89]
	v_mfma_f32_16x16x32_bf16 v[82:85], v[184:187], v[208:211], v[82:85]
	v_mfma_f32_16x16x32_bf16 v[70:73], v[172:175], v[216:219], v[70:73]
	v_mfma_f32_16x16x32_bf16 v[66:69], v[184:187], v[216:219], v[66:69]
	s_setprio 0
	s_barrier
	s_mov_b32 m0, s38
	s_add_u32 s52, s24, 0xb0000
	ds_read_b128 v[188:191], v152 offset:16384
	ds_read_b128 v[192:195], v152 offset:17408
	ds_read_b128 v[196:199], v152 offset:18432
	ds_read_b128 v[200:203], v152 offset:19456
	ds_read_b128 v[204:207], v152 offset:20480
	ds_read_b128 v[208:211], v152 offset:21504
	ds_read_b128 v[212:215], v152 offset:22528
	ds_read_b128 v[216:219], v152 offset:23552
	global_load_lds_dwordx4 v134, s[24:25]
	s_mov_b32 m0, s39
	s_addc_u32 s53, s25, 0
	global_load_lds_dwordx4 v130, s[24:25]
	s_mov_b32 m0, s40
	s_nop 0
	global_load_lds_dwordx4 v134, s[52:53]
	s_mov_b32 m0, s41
	s_nop 0
	global_load_lds_dwordx4 v130, s[52:53]
	s_mov_b32 m0, s4
	s_nop 0
	global_load_lds_dwordx4 v136, s[26:27]
	s_mov_b32 m0, s5
	s_nop 0
	global_load_lds_dwordx4 v132, s[26:27]
	s_waitcnt vmcnt(8)
	s_waitcnt lgkmcnt(0)
	s_barrier
	s_setprio 1
	v_mfma_f32_16x16x32_bf16 v[62:65], v[142:145], v[188:191], v[62:65]
	v_mfma_f32_16x16x32_bf16 v[58:61], v[160:163], v[188:191], v[58:61]
	v_mfma_f32_16x16x32_bf16 v[46:49], v[142:145], v[196:199], v[46:49]
	v_mfma_f32_16x16x32_bf16 v[42:45], v[160:163], v[196:199], v[42:45]
	v_mfma_f32_16x16x32_bf16 v[34:37], v[142:145], v[204:207], v[34:37]
	v_mfma_f32_16x16x32_bf16 v[26:29], v[160:163], v[204:207], v[26:29]
	v_mfma_f32_16x16x32_bf16 v[18:21], v[142:145], v[212:215], v[18:21]
	v_mfma_f32_16x16x32_bf16 v[10:13], v[160:163], v[212:215], v[10:13]
	v_mfma_f32_16x16x32_bf16 v[62:65], v[156:159], v[192:195], v[62:65]
	v_mfma_f32_16x16x32_bf16 v[58:61], v[164:167], v[192:195], v[58:61]
	v_mfma_f32_16x16x32_bf16 v[46:49], v[156:159], v[200:203], v[46:49]
	v_mfma_f32_16x16x32_bf16 v[42:45], v[164:167], v[200:203], v[42:45]
	v_mfma_f32_16x16x32_bf16 v[34:37], v[156:159], v[208:211], v[34:37]
	v_mfma_f32_16x16x32_bf16 v[26:29], v[164:167], v[208:211], v[26:29]
	v_mfma_f32_16x16x32_bf16 v[18:21], v[156:159], v[216:219], v[18:21]
	v_mfma_f32_16x16x32_bf16 v[10:13], v[164:167], v[216:219], v[10:13]
	v_mfma_f32_16x16x32_bf16 v[54:57], v[168:171], v[188:191], v[54:57]
	v_mfma_f32_16x16x32_bf16 v[50:53], v[180:183], v[188:191], v[50:53]
	v_mfma_f32_16x16x32_bf16 v[38:41], v[168:171], v[196:199], v[38:41]
	v_mfma_f32_16x16x32_bf16 v[30:33], v[180:183], v[196:199], v[30:33]
	v_mfma_f32_16x16x32_bf16 v[22:25], v[168:171], v[204:207], v[22:25]
	v_mfma_f32_16x16x32_bf16 v[14:17], v[180:183], v[204:207], v[14:17]
	v_mfma_f32_16x16x32_bf16 v[6:9], v[168:171], v[212:215], v[6:9]
	v_mfma_f32_16x16x32_bf16 v[2:5], v[180:183], v[212:215], v[2:5]
	v_mfma_f32_16x16x32_bf16 v[54:57], v[172:175], v[192:195], v[54:57]
	v_mfma_f32_16x16x32_bf16 v[50:53], v[184:187], v[192:195], v[50:53]
	v_mfma_f32_16x16x32_bf16 v[38:41], v[172:175], v[200:203], v[38:41]
	v_mfma_f32_16x16x32_bf16 v[30:33], v[184:187], v[200:203], v[30:33]
	v_mfma_f32_16x16x32_bf16 v[22:25], v[172:175], v[208:211], v[22:25]
	v_mfma_f32_16x16x32_bf16 v[14:17], v[184:187], v[208:211], v[14:17]
	v_mfma_f32_16x16x32_bf16 v[6:9], v[172:175], v[216:219], v[6:9]
	v_mfma_f32_16x16x32_bf16 v[2:5], v[184:187], v[216:219], v[2:5]
	s_setprio 0
	s_barrier
	ds_read_b128 v[142:145], v153
	ds_read_b128 v[156:159], v153 offset:1024
	ds_read_b128 v[160:163], v153 offset:2048
	ds_read_b128 v[164:167], v153 offset:3072
	ds_read_b128 v[168:171], v154
	ds_read_b128 v[172:175], v154 offset:1024
	ds_read_b128 v[180:183], v154 offset:2048
	ds_read_b128 v[184:187], v154 offset:3072
	s_add_u32 s26, s26, 0xb0000
	s_addc_u32 s27, s27, 0
	s_mov_b32 m0, s29
	ds_read_b128 v[188:191], v152 offset:32768
	ds_read_b128 v[192:195], v152 offset:33792
	ds_read_b128 v[196:199], v152 offset:34816
	ds_read_b128 v[200:203], v152 offset:35840
	ds_read_b128 v[204:207], v152 offset:36864
	ds_read_b128 v[208:211], v152 offset:37888
	ds_read_b128 v[212:215], v152 offset:38912
	ds_read_b128 v[216:219], v152 offset:39936
	global_load_lds_dwordx4 v136, s[26:27]
	s_mov_b32 m0, s30
	s_nop 0
	global_load_lds_dwordx4 v132, s[26:27]
	s_waitcnt vmcnt(8)
	s_waitcnt lgkmcnt(0)
	s_barrier
	s_setprio 1
	v_mfma_f32_16x16x32_bf16 v[126:129], v[142:145], v[188:191], v[126:129]
	v_mfma_f32_16x16x32_bf16 v[122:125], v[160:163], v[188:191], v[122:125]
	v_mfma_f32_16x16x32_bf16 v[110:113], v[142:145], v[196:199], v[110:113]
	v_mfma_f32_16x16x32_bf16 v[106:109], v[160:163], v[196:199], v[106:109]
	v_mfma_f32_16x16x32_bf16 v[94:97], v[142:145], v[204:207], v[94:97]
	v_mfma_f32_16x16x32_bf16 v[90:93], v[160:163], v[204:207], v[90:93]
	v_mfma_f32_16x16x32_bf16 v[78:81], v[142:145], v[212:215], v[78:81]
	v_mfma_f32_16x16x32_bf16 v[74:77], v[160:163], v[212:215], v[74:77]
	v_mfma_f32_16x16x32_bf16 v[126:129], v[156:159], v[192:195], v[126:129]
	v_mfma_f32_16x16x32_bf16 v[122:125], v[164:167], v[192:195], v[122:125]
	v_mfma_f32_16x16x32_bf16 v[110:113], v[156:159], v[200:203], v[110:113]
	v_mfma_f32_16x16x32_bf16 v[106:109], v[164:167], v[200:203], v[106:109]
	v_mfma_f32_16x16x32_bf16 v[94:97], v[156:159], v[208:211], v[94:97]
	v_mfma_f32_16x16x32_bf16 v[90:93], v[164:167], v[208:211], v[90:93]
	v_mfma_f32_16x16x32_bf16 v[78:81], v[156:159], v[216:219], v[78:81]
	v_mfma_f32_16x16x32_bf16 v[74:77], v[164:167], v[216:219], v[74:77]
	v_mfma_f32_16x16x32_bf16 v[118:121], v[168:171], v[188:191], v[118:121]
	v_mfma_f32_16x16x32_bf16 v[114:117], v[180:183], v[188:191], v[114:117]
	v_mfma_f32_16x16x32_bf16 v[102:105], v[168:171], v[196:199], v[102:105]
	v_mfma_f32_16x16x32_bf16 v[98:101], v[180:183], v[196:199], v[98:101]
	v_mfma_f32_16x16x32_bf16 v[86:89], v[168:171], v[204:207], v[86:89]
	v_mfma_f32_16x16x32_bf16 v[82:85], v[180:183], v[204:207], v[82:85]
	v_mfma_f32_16x16x32_bf16 v[70:73], v[168:171], v[212:215], v[70:73]
	v_mfma_f32_16x16x32_bf16 v[66:69], v[180:183], v[212:215], v[66:69]
	v_mfma_f32_16x16x32_bf16 v[118:121], v[172:175], v[192:195], v[118:121]
	v_mfma_f32_16x16x32_bf16 v[114:117], v[184:187], v[192:195], v[114:117]
	v_mfma_f32_16x16x32_bf16 v[102:105], v[172:175], v[200:203], v[102:105]
	v_mfma_f32_16x16x32_bf16 v[98:101], v[184:187], v[200:203], v[98:101]
	v_mfma_f32_16x16x32_bf16 v[86:89], v[172:175], v[208:211], v[86:89]
	v_mfma_f32_16x16x32_bf16 v[82:85], v[184:187], v[208:211], v[82:85]
	v_mfma_f32_16x16x32_bf16 v[70:73], v[172:175], v[216:219], v[70:73]
	v_mfma_f32_16x16x32_bf16 v[66:69], v[184:187], v[216:219], v[66:69]
	s_setprio 0
	s_barrier
	s_mov_b32 m0, s42
	ds_read_b128 v[188:191], v152 offset:49152
	ds_read_b128 v[192:195], v152 offset:50176
	ds_read_b128 v[196:199], v152 offset:51200
	ds_read_b128 v[200:203], v152 offset:52224
	ds_read_b128 v[204:207], v152 offset:53248
	ds_read_b128 v[208:211], v152 offset:54272
	ds_read_b128 v[212:215], v152 offset:55296
	ds_read_b128 v[216:219], v152 offset:56320
	s_add_u32 s98, s24, 0x80
	s_addc_u32 s99, s25, 0
	global_load_lds_dwordx4 v134, s[98:99]
	s_mov_b32 m0, s43
	s_add_u32 s24, s24, 0xb0080
	s_addc_u32 s25, s25, 0
	global_load_lds_dwordx4 v130, s[98:99]
	s_mov_b32 m0, s44
	s_nop 0
	global_load_lds_dwordx4 v134, s[24:25]
	s_mov_b32 m0, s45
	s_nop 0
	global_load_lds_dwordx4 v130, s[24:25]
	s_add_u32 s98, s26, 0xfff50080
	s_addc_u32 s99, s27, -1
	s_mov_b32 m0, s0
	s_nop 0
	global_load_lds_dwordx4 v136, s[98:99]
	s_mov_b32 m0, s1
	s_nop 0
	global_load_lds_dwordx4 v132, s[98:99]
	s_waitcnt vmcnt(8)
	s_waitcnt lgkmcnt(0)
	s_barrier
	s_setprio 1
	v_mfma_f32_16x16x32_bf16 v[62:65], v[142:145], v[188:191], v[62:65]
	v_mfma_f32_16x16x32_bf16 v[58:61], v[160:163], v[188:191], v[58:61]
	v_mfma_f32_16x16x32_bf16 v[46:49], v[142:145], v[196:199], v[46:49]
	v_mfma_f32_16x16x32_bf16 v[42:45], v[160:163], v[196:199], v[42:45]
	v_mfma_f32_16x16x32_bf16 v[34:37], v[142:145], v[204:207], v[34:37]
	v_mfma_f32_16x16x32_bf16 v[26:29], v[160:163], v[204:207], v[26:29]
	v_mfma_f32_16x16x32_bf16 v[18:21], v[142:145], v[212:215], v[18:21]
	v_mfma_f32_16x16x32_bf16 v[10:13], v[160:163], v[212:215], v[10:13]
	v_mfma_f32_16x16x32_bf16 v[62:65], v[156:159], v[192:195], v[62:65]
	v_mfma_f32_16x16x32_bf16 v[58:61], v[164:167], v[192:195], v[58:61]
	v_mfma_f32_16x16x32_bf16 v[46:49], v[156:159], v[200:203], v[46:49]
	v_mfma_f32_16x16x32_bf16 v[42:45], v[164:167], v[200:203], v[42:45]
	v_mfma_f32_16x16x32_bf16 v[34:37], v[156:159], v[208:211], v[34:37]
	v_mfma_f32_16x16x32_bf16 v[26:29], v[164:167], v[208:211], v[26:29]
	v_mfma_f32_16x16x32_bf16 v[18:21], v[156:159], v[216:219], v[18:21]
	v_mfma_f32_16x16x32_bf16 v[10:13], v[164:167], v[216:219], v[10:13]
	v_mfma_f32_16x16x32_bf16 v[54:57], v[168:171], v[188:191], v[54:57]
	v_mfma_f32_16x16x32_bf16 v[50:53], v[180:183], v[188:191], v[50:53]
	v_mfma_f32_16x16x32_bf16 v[38:41], v[168:171], v[196:199], v[38:41]
	v_mfma_f32_16x16x32_bf16 v[30:33], v[180:183], v[196:199], v[30:33]
	v_mfma_f32_16x16x32_bf16 v[22:25], v[168:171], v[204:207], v[22:25]
	v_mfma_f32_16x16x32_bf16 v[14:17], v[180:183], v[204:207], v[14:17]
	v_mfma_f32_16x16x32_bf16 v[6:9], v[168:171], v[212:215], v[6:9]
	v_mfma_f32_16x16x32_bf16 v[2:5], v[180:183], v[212:215], v[2:5]
	v_mfma_f32_16x16x32_bf16 v[54:57], v[172:175], v[192:195], v[54:57]
	v_mfma_f32_16x16x32_bf16 v[50:53], v[184:187], v[192:195], v[50:53]
	v_mfma_f32_16x16x32_bf16 v[38:41], v[172:175], v[200:203], v[38:41]
	v_mfma_f32_16x16x32_bf16 v[30:33], v[184:187], v[200:203], v[30:33]
	v_mfma_f32_16x16x32_bf16 v[22:25], v[172:175], v[208:211], v[22:25]
	v_mfma_f32_16x16x32_bf16 v[14:17], v[184:187], v[208:211], v[14:17]
	v_mfma_f32_16x16x32_bf16 v[6:9], v[172:175], v[216:219], v[6:9]
	v_mfma_f32_16x16x32_bf16 v[2:5], v[184:187], v[216:219], v[2:5]
	s_setprio 0
	s_barrier
	s_add_i32 s51, s51, 2
	s_add_u32 s22, s22, 0x100
	s_addc_u32 s23, s23, 0
	s_add_u32 s49, s49, 0x100
	s_addc_u32 s50, s50, 0
	s_cmp_gt_u32 s51, 41
	s_cbranch_scc0 .LBB0_1108
